# row-wise phases hand-written: adaLN RMSNorm+modulate (PREP1/PREP3), group RMSNorm, final RMSNorm as 8 consecutive rows per wave with register-ring prefetch and DPP+readlane reductions
# speedup vs baseline: 1.3696x; 1.0432x over previous
.Lstab_end:
	v_lshlrev_b32_e32 v0, 4, v205
	v_lshlrev_b32_e32 v1, 3, v205
	v_readlane_b32 s0, v245, 21
	v_readlane_b32 s6, v247, 6
	v_readlane_b32 s7, v247, 7
	v_readlane_b32 s8, v247, 10
	v_readlane_b32 s9, v247, 11
	v_readlane_b32 s10, v247, 29
	v_readlane_b32 s11, v247, 30
	s_add_u32 s12, s4, 0x3800000
	s_addc_u32 s13, s5, 0
	s_cmp_eq_u32 s24, 0
	s_cselect_b32 s6, s6, s10
	s_cselect_b32 s7, s7, s11
	s_cselect_b32 s8, s8, s12
	s_cselect_b32 s9, s9, s13
	s_lshl_b32 s1, s0, 15
	s_add_u32 s6, s6, s1
	s_addc_u32 s7, s7, 0
	s_lshl_b32 s1, s0, 12
	s_add_u32 s8, s8, s1
	s_addc_u32 s9, s9, 0
	s_lshl_b32 s1, s0, 14
	s_add_u32 s1, s1, 0x3e00000
	s_add_u32 s10, s4, s1
	s_addc_u32 s11, s5, 0
	s_lshl_b32 s1, s0, 11
	s_add_u32 s1, s1, 0x3c00000
	s_add_u32 s12, s4, s1
	s_addc_u32 s13, s5, 0
	s_lshl_b32 s1, s24, 12
	s_add_u32 s1, s1, 0x100000
	s_add_u32 s14, s4, s1
	s_addc_u32 s15, s5, 0
	s_mul_i32 s1, s24, 0x1e000
	s_add_u32 s16, s4, s1
	s_addc_u32 s17, s5, 0
	s_lshr_b32 s1, s0, 9
	s_mul_i32 s1, s1, 0x6000
	s_add_u32 s1, s1, 0x0
	s_add_u32 s18, s16, s1
	s_addc_u32 s19, s17, 0
	s_add_u32 s16, s16, 0x18000
	s_addc_u32 s17, s17, 0
	s_cmp_lt_u32 s0, 0x400
	s_cselect_b32 s1, 1, 0
	s_cmp_eq_u32 s1, 1
	s_cbranch_scc0 .Lrn_p1_noctx
	global_load_dwordx4 v[2:5], v0, s[14:15] offset:0
	global_load_dwordx4 v[6:9], v0, s[14:15] offset:1024
	global_load_dwordx4 v[10:13], v0, s[14:15] offset:2048
	global_load_dwordx4 v[14:17], v0, s[14:15] offset:3072
	s_add_u32 s20, s16, 0x1000
	s_addc_u32 s21, s17, 0
	global_load_dwordx4 v[18:21], v0, s[20:21] offset:0
	global_load_dwordx4 v[22:25], v0, s[20:21] offset:1024
	global_load_dwordx4 v[26:29], v0, s[20:21] offset:2048
	global_load_dwordx4 v[30:33], v0, s[20:21] offset:3072
	global_load_dwordx4 v[34:37], v0, s[16:17] offset:0
	global_load_dwordx4 v[38:41], v0, s[16:17] offset:1024
	global_load_dwordx4 v[42:45], v0, s[16:17] offset:2048
	global_load_dwordx4 v[46:49], v0, s[16:17] offset:3072
	global_load_dwordx4 v[82:85], v0, s[8:9] offset:0
	global_load_dwordx4 v[86:89], v0, s[8:9] offset:1024
	global_load_dwordx4 v[90:93], v0, s[8:9] offset:2048
	global_load_dwordx4 v[94:97], v0, s[8:9] offset:3072
	s_add_u32 s20, s18, 0x1000
	s_addc_u32 s21, s19, 0
	global_load_dwordx4 v[50:53], v0, s[20:21] offset:0
	global_load_dwordx4 v[54:57], v0, s[20:21] offset:1024
	global_load_dwordx4 v[58:61], v0, s[20:21] offset:2048
	global_load_dwordx4 v[62:65], v0, s[20:21] offset:3072
	global_load_dwordx4 v[66:69], v0, s[18:19] offset:0
	global_load_dwordx4 v[70:73], v0, s[18:19] offset:1024
	global_load_dwordx4 v[74:77], v0, s[18:19] offset:2048
	global_load_dwordx4 v[78:81], v0, s[18:19] offset:3072
	global_load_dwordx4 v[98:101], v0, s[6:7] offset:0
	global_load_dwordx4 v[102:105], v0, s[6:7] offset:1024
	global_load_dwordx4 v[106:109], v0, s[6:7] offset:2048
	global_load_dwordx4 v[110:113], v0, s[6:7] offset:3072
	s_add_u32 s6, s6, 0x1000
	s_addc_u32 s7, s7, 0
	global_load_dwordx4 v[114:117], v0, s[6:7] offset:0
	global_load_dwordx4 v[118:121], v0, s[6:7] offset:1024
	global_load_dwordx4 v[122:125], v0, s[6:7] offset:2048
	global_load_dwordx4 v[126:129], v0, s[6:7] offset:3072
	s_add_u32 s6, s6, 0x1000
	s_addc_u32 s7, s7, 0
	global_load_dwordx4 v[138:141], v0, s[6:7] offset:0
	global_load_dwordx4 v[142:145], v0, s[6:7] offset:1024
	global_load_dwordx4 v[146:149], v0, s[6:7] offset:2048
	global_load_dwordx4 v[150:153], v0, s[6:7] offset:3072
	s_add_u32 s6, s6, 0x1000
	s_addc_u32 s7, s7, 0
	global_load_dwordx4 v[154:157], v0, s[6:7] offset:0
	global_load_dwordx4 v[158:161], v0, s[6:7] offset:1024
	global_load_dwordx4 v[162:165], v0, s[6:7] offset:2048
	global_load_dwordx4 v[166:169], v0, s[6:7] offset:3072
	s_add_u32 s6, s6, 0x1000
	s_addc_u32 s7, s7, 0
	global_load_dwordx4 v[170:173], v0, s[6:7] offset:0
	global_load_dwordx4 v[174:177], v0, s[6:7] offset:1024
	global_load_dwordx4 v[178:181], v0, s[6:7] offset:2048
	global_load_dwordx4 v[182:185], v0, s[6:7] offset:3072
	s_add_u32 s6, s6, 0x1000
	s_addc_u32 s7, s7, 0
	s_waitcnt vmcnt(28)
	v_pk_mul_f32 v[130:131], v[82:83], v[82:83]
	v_pk_fma_f32 v[130:131], v[84:85], v[84:85], v[130:131]
	v_pk_fma_f32 v[130:131], v[86:87], v[86:87], v[130:131]
	v_pk_fma_f32 v[130:131], v[88:89], v[88:89], v[130:131]
	v_pk_fma_f32 v[130:131], v[90:91], v[90:91], v[130:131]
	v_pk_fma_f32 v[130:131], v[92:93], v[92:93], v[130:131]
	v_pk_fma_f32 v[130:131], v[94:95], v[94:95], v[130:131]
	v_pk_fma_f32 v[130:131], v[96:97], v[96:97], v[130:131]
	v_add_f32_e32 v130, v130, v131
	s_nop 1
	v_add_f32_dpp v130, v130, v130 row_ror:8 row_mask:0xf bank_mask:0xf
	s_nop 1
	v_add_f32_dpp v130, v130, v130 row_ror:4 row_mask:0xf bank_mask:0xf
	s_nop 1
	v_add_f32_dpp v130, v130, v130 row_ror:2 row_mask:0xf bank_mask:0xf
	s_nop 1
	v_add_f32_dpp v130, v130, v130 row_ror:1 row_mask:0xf bank_mask:0xf
	s_nop 1
	s_nop 0
	v_readlane_b32 s0, v130, 0
	v_readlane_b32 s1, v130, 16
	v_readlane_b32 s22, v130, 32
	v_readlane_b32 s23, v130, 48
	s_nop 1
	v_mov_b32_e32 v132, s0
	v_add_f32_e32 v132, s1, v132
	v_add_f32_e32 v132, s22, v132
	v_add_f32_e32 v132, s23, v132
	v_fmamk_f32 v132, v132, 0x3a800000, v197
	v_rsq_f32_e32 v132, v132
	s_nop 0
	v_pk_add_f32 v[18:19], v[18:19], 1.0 op_sel_hi:[1,0]
	v_pk_add_f32 v[20:21], v[20:21], 1.0 op_sel_hi:[1,0]
	v_pk_add_f32 v[22:23], v[22:23], 1.0 op_sel_hi:[1,0]
	v_pk_add_f32 v[24:25], v[24:25], 1.0 op_sel_hi:[1,0]
	v_pk_add_f32 v[26:27], v[26:27], 1.0 op_sel_hi:[1,0]
	v_pk_add_f32 v[28:29], v[28:29], 1.0 op_sel_hi:[1,0]
	v_pk_add_f32 v[30:31], v[30:31], 1.0 op_sel_hi:[1,0]
	v_pk_add_f32 v[32:33], v[32:33], 1.0 op_sel_hi:[1,0]
	v_pk_mul_f32 v[82:83], v[82:83], v[132:133] op_sel_hi:[1,0]
	v_pk_mul_f32 v[84:85], v[84:85], v[132:133] op_sel_hi:[1,0]
	v_pk_mul_f32 v[86:87], v[86:87], v[132:133] op_sel_hi:[1,0]
	v_pk_mul_f32 v[88:89], v[88:89], v[132:133] op_sel_hi:[1,0]
	v_pk_mul_f32 v[90:91], v[90:91], v[132:133] op_sel_hi:[1,0]
	v_pk_mul_f32 v[92:93], v[92:93], v[132:133] op_sel_hi:[1,0]
	v_pk_mul_f32 v[94:95], v[94:95], v[132:133] op_sel_hi:[1,0]
	v_pk_mul_f32 v[96:97], v[96:97], v[132:133] op_sel_hi:[1,0]
	v_pk_mul_f32 v[82:83], v[2:3], v[82:83]
	v_pk_mul_f32 v[84:85], v[4:5], v[84:85]
	v_pk_mul_f32 v[86:87], v[6:7], v[86:87]
	v_pk_mul_f32 v[88:89], v[8:9], v[88:89]
	v_pk_mul_f32 v[90:91], v[10:11], v[90:91]
	v_pk_mul_f32 v[92:93], v[12:13], v[92:93]
	v_pk_mul_f32 v[94:95], v[14:15], v[94:95]
	v_pk_mul_f32 v[96:97], v[16:17], v[96:97]
	v_pk_fma_f32 v[82:83], v[18:19], v[82:83], v[34:35]
	v_pk_fma_f32 v[84:85], v[20:21], v[84:85], v[36:37]
	v_pk_fma_f32 v[86:87], v[22:23], v[86:87], v[38:39]
	v_pk_fma_f32 v[88:89], v[24:25], v[88:89], v[40:41]
	v_pk_fma_f32 v[90:91], v[26:27], v[90:91], v[42:43]
	v_pk_fma_f32 v[92:93], v[28:29], v[92:93], v[44:45]
	v_pk_fma_f32 v[94:95], v[30:31], v[94:95], v[46:47]
	v_pk_fma_f32 v[96:97], v[32:33], v[96:97], v[48:49]
	v_cvt_pk_bf16_f32 v82, v82, v83
	v_cvt_pk_bf16_f32 v83, v84, v85
	v_cvt_pk_bf16_f32 v84, v86, v87
	v_cvt_pk_bf16_f32 v85, v88, v89
	v_cvt_pk_bf16_f32 v86, v90, v91
	v_cvt_pk_bf16_f32 v87, v92, v93
	v_cvt_pk_bf16_f32 v88, v94, v95
	v_cvt_pk_bf16_f32 v89, v96, v97
	global_store_dwordx2 v1, v[82:83], s[12:13] offset:0
	global_store_dwordx2 v1, v[84:85], s[12:13] offset:512
	global_store_dwordx2 v1, v[86:87], s[12:13] offset:1024
	global_store_dwordx2 v1, v[88:89], s[12:13] offset:1536
	global_load_dwordx4 v[82:85], v0, s[6:7] offset:0
	global_load_dwordx4 v[86:89], v0, s[6:7] offset:1024
	global_load_dwordx4 v[90:93], v0, s[6:7] offset:2048
	global_load_dwordx4 v[94:97], v0, s[6:7] offset:3072
	s_add_u32 s6, s6, 0x1000
	s_addc_u32 s7, s7, 0
	s_waitcnt vmcnt(24)
	v_pk_mul_f32 v[130:131], v[98:99], v[98:99]
	v_pk_fma_f32 v[130:131], v[100:101], v[100:101], v[130:131]
	v_pk_fma_f32 v[130:131], v[102:103], v[102:103], v[130:131]
	v_pk_fma_f32 v[130:131], v[104:105], v[104:105], v[130:131]
	v_pk_fma_f32 v[130:131], v[106:107], v[106:107], v[130:131]
	v_pk_fma_f32 v[130:131], v[108:109], v[108:109], v[130:131]
	v_pk_fma_f32 v[130:131], v[110:111], v[110:111], v[130:131]
	v_pk_fma_f32 v[130:131], v[112:113], v[112:113], v[130:131]
	v_add_f32_e32 v130, v130, v131
	s_nop 1
	v_add_f32_dpp v130, v130, v130 row_ror:8 row_mask:0xf bank_mask:0xf
	s_nop 1
	v_add_f32_dpp v130, v130, v130 row_ror:4 row_mask:0xf bank_mask:0xf
	s_nop 1
	v_add_f32_dpp v130, v130, v130 row_ror:2 row_mask:0xf bank_mask:0xf
	s_nop 1
	v_add_f32_dpp v130, v130, v130 row_ror:1 row_mask:0xf bank_mask:0xf
	s_nop 1
	s_nop 0
	v_readlane_b32 s0, v130, 0
	v_readlane_b32 s1, v130, 16
	v_readlane_b32 s22, v130, 32
	v_readlane_b32 s23, v130, 48
	s_nop 1
	v_mov_b32_e32 v132, s0
	v_add_f32_e32 v132, s1, v132
	v_add_f32_e32 v132, s22, v132
	v_add_f32_e32 v132, s23, v132
	v_fmamk_f32 v132, v132, 0x3a800000, v197
	v_rsq_f32_e32 v132, v132
	s_nop 0
	v_pk_add_f32 v[50:51], v[50:51], 1.0 op_sel_hi:[1,0]
	v_pk_add_f32 v[52:53], v[52:53], 1.0 op_sel_hi:[1,0]
	v_pk_add_f32 v[54:55], v[54:55], 1.0 op_sel_hi:[1,0]
	v_pk_add_f32 v[56:57], v[56:57], 1.0 op_sel_hi:[1,0]
	v_pk_add_f32 v[58:59], v[58:59], 1.0 op_sel_hi:[1,0]
	v_pk_add_f32 v[60:61], v[60:61], 1.0 op_sel_hi:[1,0]
	v_pk_add_f32 v[62:63], v[62:63], 1.0 op_sel_hi:[1,0]
	v_pk_add_f32 v[64:65], v[64:65], 1.0 op_sel_hi:[1,0]
	v_pk_mul_f32 v[98:99], v[98:99], v[132:133] op_sel_hi:[1,0]
	v_pk_mul_f32 v[100:101], v[100:101], v[132:133] op_sel_hi:[1,0]
	v_pk_mul_f32 v[102:103], v[102:103], v[132:133] op_sel_hi:[1,0]
	v_pk_mul_f32 v[104:105], v[104:105], v[132:133] op_sel_hi:[1,0]
	v_pk_mul_f32 v[106:107], v[106:107], v[132:133] op_sel_hi:[1,0]
	v_pk_mul_f32 v[108:109], v[108:109], v[132:133] op_sel_hi:[1,0]
	v_pk_mul_f32 v[110:111], v[110:111], v[132:133] op_sel_hi:[1,0]
	v_pk_mul_f32 v[112:113], v[112:113], v[132:133] op_sel_hi:[1,0]
	v_pk_mul_f32 v[98:99], v[2:3], v[98:99]
	v_pk_mul_f32 v[100:101], v[4:5], v[100:101]
	v_pk_mul_f32 v[102:103], v[6:7], v[102:103]
	v_pk_mul_f32 v[104:105], v[8:9], v[104:105]
	v_pk_mul_f32 v[106:107], v[10:11], v[106:107]
	v_pk_mul_f32 v[108:109], v[12:13], v[108:109]
	v_pk_mul_f32 v[110:111], v[14:15], v[110:111]
	v_pk_mul_f32 v[112:113], v[16:17], v[112:113]
	v_pk_fma_f32 v[98:99], v[50:51], v[98:99], v[66:67]
	v_pk_fma_f32 v[100:101], v[52:53], v[100:101], v[68:69]
	v_pk_fma_f32 v[102:103], v[54:55], v[102:103], v[70:71]
	v_pk_fma_f32 v[104:105], v[56:57], v[104:105], v[72:73]
	v_pk_fma_f32 v[106:107], v[58:59], v[106:107], v[74:75]
	v_pk_fma_f32 v[108:109], v[60:61], v[108:109], v[76:77]
	v_pk_fma_f32 v[110:111], v[62:63], v[110:111], v[78:79]
	v_pk_fma_f32 v[112:113], v[64:65], v[112:113], v[80:81]
	v_cvt_pk_bf16_f32 v98, v98, v99
	v_cvt_pk_bf16_f32 v99, v100, v101
	v_cvt_pk_bf16_f32 v100, v102, v103
	v_cvt_pk_bf16_f32 v101, v104, v105
	v_cvt_pk_bf16_f32 v102, v106, v107
	v_cvt_pk_bf16_f32 v103, v108, v109
	v_cvt_pk_bf16_f32 v104, v110, v111
	v_cvt_pk_bf16_f32 v105, v112, v113
	global_store_dwordx2 v1, v[98:99], s[10:11] offset:0
	global_store_dwordx2 v1, v[100:101], s[10:11] offset:512
	global_store_dwordx2 v1, v[102:103], s[10:11] offset:1024
	global_store_dwordx2 v1, v[104:105], s[10:11] offset:1536
	s_add_u32 s10, s10, 0x800
	s_addc_u32 s11, s11, 0
	global_load_dwordx4 v[98:101], v0, s[6:7] offset:0
	global_load_dwordx4 v[102:105], v0, s[6:7] offset:1024
	global_load_dwordx4 v[106:109], v0, s[6:7] offset:2048
	global_load_dwordx4 v[110:113], v0, s[6:7] offset:3072
	s_add_u32 s6, s6, 0x1000
	s_addc_u32 s7, s7, 0
	s_waitcnt vmcnt(28)
	v_pk_mul_f32 v[130:131], v[114:115], v[114:115]
	v_pk_fma_f32 v[130:131], v[116:117], v[116:117], v[130:131]
	v_pk_fma_f32 v[130:131], v[118:119], v[118:119], v[130:131]
	v_pk_fma_f32 v[130:131], v[120:121], v[120:121], v[130:131]
	v_pk_fma_f32 v[130:131], v[122:123], v[122:123], v[130:131]
	v_pk_fma_f32 v[130:131], v[124:125], v[124:125], v[130:131]
	v_pk_fma_f32 v[130:131], v[126:127], v[126:127], v[130:131]
	v_pk_fma_f32 v[130:131], v[128:129], v[128:129], v[130:131]
	v_add_f32_e32 v130, v130, v131
	s_nop 1
	v_add_f32_dpp v130, v130, v130 row_ror:8 row_mask:0xf bank_mask:0xf
	s_nop 1
	v_add_f32_dpp v130, v130, v130 row_ror:4 row_mask:0xf bank_mask:0xf
	s_nop 1
	v_add_f32_dpp v130, v130, v130 row_ror:2 row_mask:0xf bank_mask:0xf
	s_nop 1
	v_add_f32_dpp v130, v130, v130 row_ror:1 row_mask:0xf bank_mask:0xf
	s_nop 1
	s_nop 0
	v_readlane_b32 s0, v130, 0
	v_readlane_b32 s1, v130, 16
	v_readlane_b32 s22, v130, 32
	v_readlane_b32 s23, v130, 48
	s_nop 1
	v_mov_b32_e32 v132, s0
	v_add_f32_e32 v132, s1, v132
	v_add_f32_e32 v132, s22, v132
	v_add_f32_e32 v132, s23, v132
	v_fmamk_f32 v132, v132, 0x3a800000, v197
	v_rsq_f32_e32 v132, v132
	s_nop 0
	v_pk_mul_f32 v[114:115], v[114:115], v[132:133] op_sel_hi:[1,0]
	v_pk_mul_f32 v[116:117], v[116:117], v[132:133] op_sel_hi:[1,0]
	v_pk_mul_f32 v[118:119], v[118:119], v[132:133] op_sel_hi:[1,0]
	v_pk_mul_f32 v[120:121], v[120:121], v[132:133] op_sel_hi:[1,0]
	v_pk_mul_f32 v[122:123], v[122:123], v[132:133] op_sel_hi:[1,0]
	v_pk_mul_f32 v[124:125], v[124:125], v[132:133] op_sel_hi:[1,0]
	v_pk_mul_f32 v[126:127], v[126:127], v[132:133] op_sel_hi:[1,0]
	v_pk_mul_f32 v[128:129], v[128:129], v[132:133] op_sel_hi:[1,0]
	v_pk_mul_f32 v[114:115], v[2:3], v[114:115]
	v_pk_mul_f32 v[116:117], v[4:5], v[116:117]
	v_pk_mul_f32 v[118:119], v[6:7], v[118:119]
	v_pk_mul_f32 v[120:121], v[8:9], v[120:121]
	v_pk_mul_f32 v[122:123], v[10:11], v[122:123]
	v_pk_mul_f32 v[124:125], v[12:13], v[124:125]
	v_pk_mul_f32 v[126:127], v[14:15], v[126:127]
	v_pk_mul_f32 v[128:129], v[16:17], v[128:129]
	v_pk_fma_f32 v[114:115], v[50:51], v[114:115], v[66:67]
	v_pk_fma_f32 v[116:117], v[52:53], v[116:117], v[68:69]
	v_pk_fma_f32 v[118:119], v[54:55], v[118:119], v[70:71]
	v_pk_fma_f32 v[120:121], v[56:57], v[120:121], v[72:73]
	v_pk_fma_f32 v[122:123], v[58:59], v[122:123], v[74:75]
	v_pk_fma_f32 v[124:125], v[60:61], v[124:125], v[76:77]
	v_pk_fma_f32 v[126:127], v[62:63], v[126:127], v[78:79]
	v_pk_fma_f32 v[128:129], v[64:65], v[128:129], v[80:81]
	v_cvt_pk_bf16_f32 v114, v114, v115
	v_cvt_pk_bf16_f32 v115, v116, v117
	v_cvt_pk_bf16_f32 v116, v118, v119
	v_cvt_pk_bf16_f32 v117, v120, v121
	v_cvt_pk_bf16_f32 v118, v122, v123
	v_cvt_pk_bf16_f32 v119, v124, v125
	v_cvt_pk_bf16_f32 v120, v126, v127
	v_cvt_pk_bf16_f32 v121, v128, v129
	global_store_dwordx2 v1, v[114:115], s[10:11] offset:0
	global_store_dwordx2 v1, v[116:117], s[10:11] offset:512
	global_store_dwordx2 v1, v[118:119], s[10:11] offset:1024
	global_store_dwordx2 v1, v[120:121], s[10:11] offset:1536
	s_add_u32 s10, s10, 0x800
	s_addc_u32 s11, s11, 0
	global_load_dwordx4 v[114:117], v0, s[6:7] offset:0
	global_load_dwordx4 v[118:121], v0, s[6:7] offset:1024
	global_load_dwordx4 v[122:125], v0, s[6:7] offset:2048
	global_load_dwordx4 v[126:129], v0, s[6:7] offset:3072
	s_waitcnt vmcnt(32)
	v_pk_mul_f32 v[130:131], v[138:139], v[138:139]
	v_pk_fma_f32 v[130:131], v[140:141], v[140:141], v[130:131]
	v_pk_fma_f32 v[130:131], v[142:143], v[142:143], v[130:131]
	v_pk_fma_f32 v[130:131], v[144:145], v[144:145], v[130:131]
	v_pk_fma_f32 v[130:131], v[146:147], v[146:147], v[130:131]
	v_pk_fma_f32 v[130:131], v[148:149], v[148:149], v[130:131]
	v_pk_fma_f32 v[130:131], v[150:151], v[150:151], v[130:131]
	v_pk_fma_f32 v[130:131], v[152:153], v[152:153], v[130:131]
	v_add_f32_e32 v130, v130, v131
	s_nop 1
	v_add_f32_dpp v130, v130, v130 row_ror:8 row_mask:0xf bank_mask:0xf
	s_nop 1
	v_add_f32_dpp v130, v130, v130 row_ror:4 row_mask:0xf bank_mask:0xf
	s_nop 1
	v_add_f32_dpp v130, v130, v130 row_ror:2 row_mask:0xf bank_mask:0xf
	s_nop 1
	v_add_f32_dpp v130, v130, v130 row_ror:1 row_mask:0xf bank_mask:0xf
	s_nop 1
	s_nop 0
	v_readlane_b32 s0, v130, 0
	v_readlane_b32 s1, v130, 16
	v_readlane_b32 s22, v130, 32
	v_readlane_b32 s23, v130, 48
	s_nop 1
	v_mov_b32_e32 v132, s0
	v_add_f32_e32 v132, s1, v132
	v_add_f32_e32 v132, s22, v132
	v_add_f32_e32 v132, s23, v132
	v_fmamk_f32 v132, v132, 0x3a800000, v197
	v_rsq_f32_e32 v132, v132
	s_nop 0
	v_pk_mul_f32 v[138:139], v[138:139], v[132:133] op_sel_hi:[1,0]
	v_pk_mul_f32 v[140:141], v[140:141], v[132:133] op_sel_hi:[1,0]
	v_pk_mul_f32 v[142:143], v[142:143], v[132:133] op_sel_hi:[1,0]
	v_pk_mul_f32 v[144:145], v[144:145], v[132:133] op_sel_hi:[1,0]
	v_pk_mul_f32 v[146:147], v[146:147], v[132:133] op_sel_hi:[1,0]
	v_pk_mul_f32 v[148:149], v[148:149], v[132:133] op_sel_hi:[1,0]
	v_pk_mul_f32 v[150:151], v[150:151], v[132:133] op_sel_hi:[1,0]
	v_pk_mul_f32 v[152:153], v[152:153], v[132:133] op_sel_hi:[1,0]
	v_pk_mul_f32 v[138:139], v[2:3], v[138:139]
	v_pk_mul_f32 v[140:141], v[4:5], v[140:141]
	v_pk_mul_f32 v[142:143], v[6:7], v[142:143]
	v_pk_mul_f32 v[144:145], v[8:9], v[144:145]
	v_pk_mul_f32 v[146:147], v[10:11], v[146:147]
	v_pk_mul_f32 v[148:149], v[12:13], v[148:149]
	v_pk_mul_f32 v[150:151], v[14:15], v[150:151]
	v_pk_mul_f32 v[152:153], v[16:17], v[152:153]
	v_pk_fma_f32 v[138:139], v[50:51], v[138:139], v[66:67]
	v_pk_fma_f32 v[140:141], v[52:53], v[140:141], v[68:69]
	v_pk_fma_f32 v[142:143], v[54:55], v[142:143], v[70:71]
	v_pk_fma_f32 v[144:145], v[56:57], v[144:145], v[72:73]
	v_pk_fma_f32 v[146:147], v[58:59], v[146:147], v[74:75]
	v_pk_fma_f32 v[148:149], v[60:61], v[148:149], v[76:77]
	v_pk_fma_f32 v[150:151], v[62:63], v[150:151], v[78:79]
	v_pk_fma_f32 v[152:153], v[64:65], v[152:153], v[80:81]
	v_cvt_pk_bf16_f32 v138, v138, v139
	v_cvt_pk_bf16_f32 v139, v140, v141
	v_cvt_pk_bf16_f32 v140, v142, v143
	v_cvt_pk_bf16_f32 v141, v144, v145
	v_cvt_pk_bf16_f32 v142, v146, v147
	v_cvt_pk_bf16_f32 v143, v148, v149
	v_cvt_pk_bf16_f32 v144, v150, v151
	v_cvt_pk_bf16_f32 v145, v152, v153
	global_store_dwordx2 v1, v[138:139], s[10:11] offset:0
	global_store_dwordx2 v1, v[140:141], s[10:11] offset:512
	global_store_dwordx2 v1, v[142:143], s[10:11] offset:1024
	global_store_dwordx2 v1, v[144:145], s[10:11] offset:1536
	s_add_u32 s10, s10, 0x800
	s_addc_u32 s11, s11, 0
	s_waitcnt vmcnt(32)
	v_pk_mul_f32 v[130:131], v[154:155], v[154:155]
	v_pk_fma_f32 v[130:131], v[156:157], v[156:157], v[130:131]
	v_pk_fma_f32 v[130:131], v[158:159], v[158:159], v[130:131]
	v_pk_fma_f32 v[130:131], v[160:161], v[160:161], v[130:131]
	v_pk_fma_f32 v[130:131], v[162:163], v[162:163], v[130:131]
	v_pk_fma_f32 v[130:131], v[164:165], v[164:165], v[130:131]
	v_pk_fma_f32 v[130:131], v[166:167], v[166:167], v[130:131]
	v_pk_fma_f32 v[130:131], v[168:169], v[168:169], v[130:131]
	v_add_f32_e32 v130, v130, v131
	s_nop 1
	v_add_f32_dpp v130, v130, v130 row_ror:8 row_mask:0xf bank_mask:0xf
	s_nop 1
	v_add_f32_dpp v130, v130, v130 row_ror:4 row_mask:0xf bank_mask:0xf
	s_nop 1
	v_add_f32_dpp v130, v130, v130 row_ror:2 row_mask:0xf bank_mask:0xf
	s_nop 1
	v_add_f32_dpp v130, v130, v130 row_ror:1 row_mask:0xf bank_mask:0xf
	s_nop 1
	s_nop 0
	v_readlane_b32 s0, v130, 0
	v_readlane_b32 s1, v130, 16
	v_readlane_b32 s22, v130, 32
	v_readlane_b32 s23, v130, 48
	s_nop 1
	v_mov_b32_e32 v132, s0
	v_add_f32_e32 v132, s1, v132
	v_add_f32_e32 v132, s22, v132
	v_add_f32_e32 v132, s23, v132
	v_fmamk_f32 v132, v132, 0x3a800000, v197
	v_rsq_f32_e32 v132, v132
	s_nop 0
	v_pk_mul_f32 v[154:155], v[154:155], v[132:133] op_sel_hi:[1,0]
	v_pk_mul_f32 v[156:157], v[156:157], v[132:133] op_sel_hi:[1,0]
	v_pk_mul_f32 v[158:159], v[158:159], v[132:133] op_sel_hi:[1,0]
	v_pk_mul_f32 v[160:161], v[160:161], v[132:133] op_sel_hi:[1,0]
	v_pk_mul_f32 v[162:163], v[162:163], v[132:133] op_sel_hi:[1,0]
	v_pk_mul_f32 v[164:165], v[164:165], v[132:133] op_sel_hi:[1,0]
	v_pk_mul_f32 v[166:167], v[166:167], v[132:133] op_sel_hi:[1,0]
	v_pk_mul_f32 v[168:169], v[168:169], v[132:133] op_sel_hi:[1,0]
	v_pk_mul_f32 v[154:155], v[2:3], v[154:155]
	v_pk_mul_f32 v[156:157], v[4:5], v[156:157]
	v_pk_mul_f32 v[158:159], v[6:7], v[158:159]
	v_pk_mul_f32 v[160:161], v[8:9], v[160:161]
	v_pk_mul_f32 v[162:163], v[10:11], v[162:163]
	v_pk_mul_f32 v[164:165], v[12:13], v[164:165]
	v_pk_mul_f32 v[166:167], v[14:15], v[166:167]
	v_pk_mul_f32 v[168:169], v[16:17], v[168:169]
	v_pk_fma_f32 v[154:155], v[50:51], v[154:155], v[66:67]
	v_pk_fma_f32 v[156:157], v[52:53], v[156:157], v[68:69]
	v_pk_fma_f32 v[158:159], v[54:55], v[158:159], v[70:71]
	v_pk_fma_f32 v[160:161], v[56:57], v[160:161], v[72:73]
	v_pk_fma_f32 v[162:163], v[58:59], v[162:163], v[74:75]
	v_pk_fma_f32 v[164:165], v[60:61], v[164:165], v[76:77]
	v_pk_fma_f32 v[166:167], v[62:63], v[166:167], v[78:79]
	v_pk_fma_f32 v[168:169], v[64:65], v[168:169], v[80:81]
	v_cvt_pk_bf16_f32 v154, v154, v155
	v_cvt_pk_bf16_f32 v155, v156, v157
	v_cvt_pk_bf16_f32 v156, v158, v159
	v_cvt_pk_bf16_f32 v157, v160, v161
	v_cvt_pk_bf16_f32 v158, v162, v163
	v_cvt_pk_bf16_f32 v159, v164, v165
	v_cvt_pk_bf16_f32 v160, v166, v167
	v_cvt_pk_bf16_f32 v161, v168, v169
	global_store_dwordx2 v1, v[154:155], s[10:11] offset:0
	global_store_dwordx2 v1, v[156:157], s[10:11] offset:512
	global_store_dwordx2 v1, v[158:159], s[10:11] offset:1024
	global_store_dwordx2 v1, v[160:161], s[10:11] offset:1536
	s_add_u32 s10, s10, 0x800
	s_addc_u32 s11, s11, 0
	s_waitcnt vmcnt(32)
	v_pk_mul_f32 v[130:131], v[170:171], v[170:171]
	v_pk_fma_f32 v[130:131], v[172:173], v[172:173], v[130:131]
	v_pk_fma_f32 v[130:131], v[174:175], v[174:175], v[130:131]
	v_pk_fma_f32 v[130:131], v[176:177], v[176:177], v[130:131]
	v_pk_fma_f32 v[130:131], v[178:179], v[178:179], v[130:131]
	v_pk_fma_f32 v[130:131], v[180:181], v[180:181], v[130:131]
	v_pk_fma_f32 v[130:131], v[182:183], v[182:183], v[130:131]
	v_pk_fma_f32 v[130:131], v[184:185], v[184:185], v[130:131]
	v_add_f32_e32 v130, v130, v131
	s_nop 1
	v_add_f32_dpp v130, v130, v130 row_ror:8 row_mask:0xf bank_mask:0xf
	s_nop 1
	v_add_f32_dpp v130, v130, v130 row_ror:4 row_mask:0xf bank_mask:0xf
	s_nop 1
	v_add_f32_dpp v130, v130, v130 row_ror:2 row_mask:0xf bank_mask:0xf
	s_nop 1
	v_add_f32_dpp v130, v130, v130 row_ror:1 row_mask:0xf bank_mask:0xf
	s_nop 1
	s_nop 0
	v_readlane_b32 s0, v130, 0
	v_readlane_b32 s1, v130, 16
	v_readlane_b32 s22, v130, 32
	v_readlane_b32 s23, v130, 48
	s_nop 1
	v_mov_b32_e32 v132, s0
	v_add_f32_e32 v132, s1, v132
	v_add_f32_e32 v132, s22, v132
	v_add_f32_e32 v132, s23, v132
	v_fmamk_f32 v132, v132, 0x3a800000, v197
	v_rsq_f32_e32 v132, v132
	s_nop 0
	v_pk_mul_f32 v[170:171], v[170:171], v[132:133] op_sel_hi:[1,0]
	v_pk_mul_f32 v[172:173], v[172:173], v[132:133] op_sel_hi:[1,0]
	v_pk_mul_f32 v[174:175], v[174:175], v[132:133] op_sel_hi:[1,0]
	v_pk_mul_f32 v[176:177], v[176:177], v[132:133] op_sel_hi:[1,0]
	v_pk_mul_f32 v[178:179], v[178:179], v[132:133] op_sel_hi:[1,0]
	v_pk_mul_f32 v[180:181], v[180:181], v[132:133] op_sel_hi:[1,0]
	v_pk_mul_f32 v[182:183], v[182:183], v[132:133] op_sel_hi:[1,0]
	v_pk_mul_f32 v[184:185], v[184:185], v[132:133] op_sel_hi:[1,0]
	v_pk_mul_f32 v[170:171], v[2:3], v[170:171]
	v_pk_mul_f32 v[172:173], v[4:5], v[172:173]
	v_pk_mul_f32 v[174:175], v[6:7], v[174:175]
	v_pk_mul_f32 v[176:177], v[8:9], v[176:177]
	v_pk_mul_f32 v[178:179], v[10:11], v[178:179]
	v_pk_mul_f32 v[180:181], v[12:13], v[180:181]
	v_pk_mul_f32 v[182:183], v[14:15], v[182:183]
	v_pk_mul_f32 v[184:185], v[16:17], v[184:185]
	v_pk_fma_f32 v[170:171], v[50:51], v[170:171], v[66:67]
	v_pk_fma_f32 v[172:173], v[52:53], v[172:173], v[68:69]
	v_pk_fma_f32 v[174:175], v[54:55], v[174:175], v[70:71]
	v_pk_fma_f32 v[176:177], v[56:57], v[176:177], v[72:73]
	v_pk_fma_f32 v[178:179], v[58:59], v[178:179], v[74:75]
	v_pk_fma_f32 v[180:181], v[60:61], v[180:181], v[76:77]
	v_pk_fma_f32 v[182:183], v[62:63], v[182:183], v[78:79]
	v_pk_fma_f32 v[184:185], v[64:65], v[184:185], v[80:81]
	v_cvt_pk_bf16_f32 v170, v170, v171
	v_cvt_pk_bf16_f32 v171, v172, v173
	v_cvt_pk_bf16_f32 v172, v174, v175
	v_cvt_pk_bf16_f32 v173, v176, v177
	v_cvt_pk_bf16_f32 v174, v178, v179
	v_cvt_pk_bf16_f32 v175, v180, v181
	v_cvt_pk_bf16_f32 v176, v182, v183
	v_cvt_pk_bf16_f32 v177, v184, v185
	global_store_dwordx2 v1, v[170:171], s[10:11] offset:0
	global_store_dwordx2 v1, v[172:173], s[10:11] offset:512
	global_store_dwordx2 v1, v[174:175], s[10:11] offset:1024
	global_store_dwordx2 v1, v[176:177], s[10:11] offset:1536
	s_add_u32 s10, s10, 0x800
	s_addc_u32 s11, s11, 0
	s_waitcnt vmcnt(28)
	v_pk_mul_f32 v[130:131], v[82:83], v[82:83]
	v_pk_fma_f32 v[130:131], v[84:85], v[84:85], v[130:131]
	v_pk_fma_f32 v[130:131], v[86:87], v[86:87], v[130:131]
	v_pk_fma_f32 v[130:131], v[88:89], v[88:89], v[130:131]
	v_pk_fma_f32 v[130:131], v[90:91], v[90:91], v[130:131]
	v_pk_fma_f32 v[130:131], v[92:93], v[92:93], v[130:131]
	v_pk_fma_f32 v[130:131], v[94:95], v[94:95], v[130:131]
	v_pk_fma_f32 v[130:131], v[96:97], v[96:97], v[130:131]
	v_add_f32_e32 v130, v130, v131
	s_nop 1
	v_add_f32_dpp v130, v130, v130 row_ror:8 row_mask:0xf bank_mask:0xf
	s_nop 1
	v_add_f32_dpp v130, v130, v130 row_ror:4 row_mask:0xf bank_mask:0xf
	s_nop 1
	v_add_f32_dpp v130, v130, v130 row_ror:2 row_mask:0xf bank_mask:0xf
	s_nop 1
	v_add_f32_dpp v130, v130, v130 row_ror:1 row_mask:0xf bank_mask:0xf
	s_nop 1
	s_nop 0
	v_readlane_b32 s0, v130, 0
	v_readlane_b32 s1, v130, 16
	v_readlane_b32 s22, v130, 32
	v_readlane_b32 s23, v130, 48
	s_nop 1
	v_mov_b32_e32 v132, s0
	v_add_f32_e32 v132, s1, v132
	v_add_f32_e32 v132, s22, v132
	v_add_f32_e32 v132, s23, v132
	v_fmamk_f32 v132, v132, 0x3a800000, v197
	v_rsq_f32_e32 v132, v132
	s_nop 0
	v_pk_mul_f32 v[82:83], v[82:83], v[132:133] op_sel_hi:[1,0]
	v_pk_mul_f32 v[84:85], v[84:85], v[132:133] op_sel_hi:[1,0]
	v_pk_mul_f32 v[86:87], v[86:87], v[132:133] op_sel_hi:[1,0]
	v_pk_mul_f32 v[88:89], v[88:89], v[132:133] op_sel_hi:[1,0]
	v_pk_mul_f32 v[90:91], v[90:91], v[132:133] op_sel_hi:[1,0]
	v_pk_mul_f32 v[92:93], v[92:93], v[132:133] op_sel_hi:[1,0]
	v_pk_mul_f32 v[94:95], v[94:95], v[132:133] op_sel_hi:[1,0]
	v_pk_mul_f32 v[96:97], v[96:97], v[132:133] op_sel_hi:[1,0]
	v_pk_mul_f32 v[82:83], v[2:3], v[82:83]
	v_pk_mul_f32 v[84:85], v[4:5], v[84:85]
	v_pk_mul_f32 v[86:87], v[6:7], v[86:87]
	v_pk_mul_f32 v[88:89], v[8:9], v[88:89]
	v_pk_mul_f32 v[90:91], v[10:11], v[90:91]
	v_pk_mul_f32 v[92:93], v[12:13], v[92:93]
	v_pk_mul_f32 v[94:95], v[14:15], v[94:95]
	v_pk_mul_f32 v[96:97], v[16:17], v[96:97]
	v_pk_fma_f32 v[82:83], v[50:51], v[82:83], v[66:67]
	v_pk_fma_f32 v[84:85], v[52:53], v[84:85], v[68:69]
	v_pk_fma_f32 v[86:87], v[54:55], v[86:87], v[70:71]
	v_pk_fma_f32 v[88:89], v[56:57], v[88:89], v[72:73]
	v_pk_fma_f32 v[90:91], v[58:59], v[90:91], v[74:75]
	v_pk_fma_f32 v[92:93], v[60:61], v[92:93], v[76:77]
	v_pk_fma_f32 v[94:95], v[62:63], v[94:95], v[78:79]
	v_pk_fma_f32 v[96:97], v[64:65], v[96:97], v[80:81]
	v_cvt_pk_bf16_f32 v82, v82, v83
	v_cvt_pk_bf16_f32 v83, v84, v85
	v_cvt_pk_bf16_f32 v84, v86, v87
	v_cvt_pk_bf16_f32 v85, v88, v89
	v_cvt_pk_bf16_f32 v86, v90, v91
	v_cvt_pk_bf16_f32 v87, v92, v93
	v_cvt_pk_bf16_f32 v88, v94, v95
	v_cvt_pk_bf16_f32 v89, v96, v97
	global_store_dwordx2 v1, v[82:83], s[10:11] offset:0
	global_store_dwordx2 v1, v[84:85], s[10:11] offset:512
	global_store_dwordx2 v1, v[86:87], s[10:11] offset:1024
	global_store_dwordx2 v1, v[88:89], s[10:11] offset:1536
	s_add_u32 s10, s10, 0x800
	s_addc_u32 s11, s11, 0
	s_waitcnt vmcnt(24)
	v_pk_mul_f32 v[130:131], v[98:99], v[98:99]
	v_pk_fma_f32 v[130:131], v[100:101], v[100:101], v[130:131]
	v_pk_fma_f32 v[130:131], v[102:103], v[102:103], v[130:131]
	v_pk_fma_f32 v[130:131], v[104:105], v[104:105], v[130:131]
	v_pk_fma_f32 v[130:131], v[106:107], v[106:107], v[130:131]
	v_pk_fma_f32 v[130:131], v[108:109], v[108:109], v[130:131]
	v_pk_fma_f32 v[130:131], v[110:111], v[110:111], v[130:131]
	v_pk_fma_f32 v[130:131], v[112:113], v[112:113], v[130:131]
	v_add_f32_e32 v130, v130, v131
	s_nop 1
	v_add_f32_dpp v130, v130, v130 row_ror:8 row_mask:0xf bank_mask:0xf
	s_nop 1
	v_add_f32_dpp v130, v130, v130 row_ror:4 row_mask:0xf bank_mask:0xf
	s_nop 1
	v_add_f32_dpp v130, v130, v130 row_ror:2 row_mask:0xf bank_mask:0xf
	s_nop 1
	v_add_f32_dpp v130, v130, v130 row_ror:1 row_mask:0xf bank_mask:0xf
	s_nop 1
	s_nop 0
	v_readlane_b32 s0, v130, 0
	v_readlane_b32 s1, v130, 16
	v_readlane_b32 s22, v130, 32
	v_readlane_b32 s23, v130, 48
	s_nop 1
	v_mov_b32_e32 v132, s0
	v_add_f32_e32 v132, s1, v132
	v_add_f32_e32 v132, s22, v132
	v_add_f32_e32 v132, s23, v132
	v_fmamk_f32 v132, v132, 0x3a800000, v197
	v_rsq_f32_e32 v132, v132
	s_nop 0
	v_pk_mul_f32 v[98:99], v[98:99], v[132:133] op_sel_hi:[1,0]
	v_pk_mul_f32 v[100:101], v[100:101], v[132:133] op_sel_hi:[1,0]
	v_pk_mul_f32 v[102:103], v[102:103], v[132:133] op_sel_hi:[1,0]
	v_pk_mul_f32 v[104:105], v[104:105], v[132:133] op_sel_hi:[1,0]
	v_pk_mul_f32 v[106:107], v[106:107], v[132:133] op_sel_hi:[1,0]
	v_pk_mul_f32 v[108:109], v[108:109], v[132:133] op_sel_hi:[1,0]
	v_pk_mul_f32 v[110:111], v[110:111], v[132:133] op_sel_hi:[1,0]
	v_pk_mul_f32 v[112:113], v[112:113], v[132:133] op_sel_hi:[1,0]
	v_pk_mul_f32 v[98:99], v[2:3], v[98:99]
	v_pk_mul_f32 v[100:101], v[4:5], v[100:101]
	v_pk_mul_f32 v[102:103], v[6:7], v[102:103]
	v_pk_mul_f32 v[104:105], v[8:9], v[104:105]
	v_pk_mul_f32 v[106:107], v[10:11], v[106:107]
	v_pk_mul_f32 v[108:109], v[12:13], v[108:109]
	v_pk_mul_f32 v[110:111], v[14:15], v[110:111]
	v_pk_mul_f32 v[112:113], v[16:17], v[112:113]
	v_pk_fma_f32 v[98:99], v[50:51], v[98:99], v[66:67]
	v_pk_fma_f32 v[100:101], v[52:53], v[100:101], v[68:69]
	v_pk_fma_f32 v[102:103], v[54:55], v[102:103], v[70:71]
	v_pk_fma_f32 v[104:105], v[56:57], v[104:105], v[72:73]
	v_pk_fma_f32 v[106:107], v[58:59], v[106:107], v[74:75]
	v_pk_fma_f32 v[108:109], v[60:61], v[108:109], v[76:77]
	v_pk_fma_f32 v[110:111], v[62:63], v[110:111], v[78:79]
	v_pk_fma_f32 v[112:113], v[64:65], v[112:113], v[80:81]
	v_cvt_pk_bf16_f32 v98, v98, v99
	v_cvt_pk_bf16_f32 v99, v100, v101
	v_cvt_pk_bf16_f32 v100, v102, v103
	v_cvt_pk_bf16_f32 v101, v104, v105
	v_cvt_pk_bf16_f32 v102, v106, v107
	v_cvt_pk_bf16_f32 v103, v108, v109
	v_cvt_pk_bf16_f32 v104, v110, v111
	v_cvt_pk_bf16_f32 v105, v112, v113
	global_store_dwordx2 v1, v[98:99], s[10:11] offset:0
	global_store_dwordx2 v1, v[100:101], s[10:11] offset:512
	global_store_dwordx2 v1, v[102:103], s[10:11] offset:1024
	global_store_dwordx2 v1, v[104:105], s[10:11] offset:1536
	s_add_u32 s10, s10, 0x800
	s_addc_u32 s11, s11, 0
	s_waitcnt vmcnt(20)
	v_pk_mul_f32 v[130:131], v[114:115], v[114:115]
	v_pk_fma_f32 v[130:131], v[116:117], v[116:117], v[130:131]
	v_pk_fma_f32 v[130:131], v[118:119], v[118:119], v[130:131]
	v_pk_fma_f32 v[130:131], v[120:121], v[120:121], v[130:131]
	v_pk_fma_f32 v[130:131], v[122:123], v[122:123], v[130:131]
	v_pk_fma_f32 v[130:131], v[124:125], v[124:125], v[130:131]
	v_pk_fma_f32 v[130:131], v[126:127], v[126:127], v[130:131]
	v_pk_fma_f32 v[130:131], v[128:129], v[128:129], v[130:131]
	v_add_f32_e32 v130, v130, v131
	s_nop 1
	v_add_f32_dpp v130, v130, v130 row_ror:8 row_mask:0xf bank_mask:0xf
	s_nop 1
	v_add_f32_dpp v130, v130, v130 row_ror:4 row_mask:0xf bank_mask:0xf
	s_nop 1
	v_add_f32_dpp v130, v130, v130 row_ror:2 row_mask:0xf bank_mask:0xf
	s_nop 1
	v_add_f32_dpp v130, v130, v130 row_ror:1 row_mask:0xf bank_mask:0xf
	s_nop 1
	s_nop 0
	v_readlane_b32 s0, v130, 0
	v_readlane_b32 s1, v130, 16
	v_readlane_b32 s22, v130, 32
	v_readlane_b32 s23, v130, 48
	s_nop 1
	v_mov_b32_e32 v132, s0
	v_add_f32_e32 v132, s1, v132
	v_add_f32_e32 v132, s22, v132
	v_add_f32_e32 v132, s23, v132
	v_fmamk_f32 v132, v132, 0x3a800000, v197
	v_rsq_f32_e32 v132, v132
	s_nop 0
	v_pk_mul_f32 v[114:115], v[114:115], v[132:133] op_sel_hi:[1,0]
	v_pk_mul_f32 v[116:117], v[116:117], v[132:133] op_sel_hi:[1,0]
	v_pk_mul_f32 v[118:119], v[118:119], v[132:133] op_sel_hi:[1,0]
	v_pk_mul_f32 v[120:121], v[120:121], v[132:133] op_sel_hi:[1,0]
	v_pk_mul_f32 v[122:123], v[122:123], v[132:133] op_sel_hi:[1,0]
	v_pk_mul_f32 v[124:125], v[124:125], v[132:133] op_sel_hi:[1,0]
	v_pk_mul_f32 v[126:127], v[126:127], v[132:133] op_sel_hi:[1,0]
	v_pk_mul_f32 v[128:129], v[128:129], v[132:133] op_sel_hi:[1,0]
	v_pk_mul_f32 v[114:115], v[2:3], v[114:115]
	v_pk_mul_f32 v[116:117], v[4:5], v[116:117]
	v_pk_mul_f32 v[118:119], v[6:7], v[118:119]
	v_pk_mul_f32 v[120:121], v[8:9], v[120:121]
	v_pk_mul_f32 v[122:123], v[10:11], v[122:123]
	v_pk_mul_f32 v[124:125], v[12:13], v[124:125]
	v_pk_mul_f32 v[126:127], v[14:15], v[126:127]
	v_pk_mul_f32 v[128:129], v[16:17], v[128:129]
	v_pk_fma_f32 v[114:115], v[50:51], v[114:115], v[66:67]
	v_pk_fma_f32 v[116:117], v[52:53], v[116:117], v[68:69]
	v_pk_fma_f32 v[118:119], v[54:55], v[118:119], v[70:71]
	v_pk_fma_f32 v[120:121], v[56:57], v[120:121], v[72:73]
	v_pk_fma_f32 v[122:123], v[58:59], v[122:123], v[74:75]
	v_pk_fma_f32 v[124:125], v[60:61], v[124:125], v[76:77]
	v_pk_fma_f32 v[126:127], v[62:63], v[126:127], v[78:79]
	v_pk_fma_f32 v[128:129], v[64:65], v[128:129], v[80:81]
	v_cvt_pk_bf16_f32 v114, v114, v115
	v_cvt_pk_bf16_f32 v115, v116, v117
	v_cvt_pk_bf16_f32 v116, v118, v119
	v_cvt_pk_bf16_f32 v117, v120, v121
	v_cvt_pk_bf16_f32 v118, v122, v123
	v_cvt_pk_bf16_f32 v119, v124, v125
	v_cvt_pk_bf16_f32 v120, v126, v127
	v_cvt_pk_bf16_f32 v121, v128, v129
	global_store_dwordx2 v1, v[114:115], s[10:11] offset:0
	global_store_dwordx2 v1, v[116:117], s[10:11] offset:512
	global_store_dwordx2 v1, v[118:119], s[10:11] offset:1024
	global_store_dwordx2 v1, v[120:121], s[10:11] offset:1536
	s_branch .Lrn_p1_end
.Lrn_p1_noctx:
	global_load_dwordx4 v[2:5], v0, s[14:15] offset:0
	global_load_dwordx4 v[6:9], v0, s[14:15] offset:1024
	global_load_dwordx4 v[10:13], v0, s[14:15] offset:2048
	global_load_dwordx4 v[14:17], v0, s[14:15] offset:3072
	s_add_u32 s20, s18, 0x1000
	s_addc_u32 s21, s19, 0
	global_load_dwordx4 v[50:53], v0, s[20:21] offset:0
	global_load_dwordx4 v[54:57], v0, s[20:21] offset:1024
	global_load_dwordx4 v[58:61], v0, s[20:21] offset:2048
	global_load_dwordx4 v[62:65], v0, s[20:21] offset:3072
	global_load_dwordx4 v[66:69], v0, s[18:19] offset:0
	global_load_dwordx4 v[70:73], v0, s[18:19] offset:1024
	global_load_dwordx4 v[74:77], v0, s[18:19] offset:2048
	global_load_dwordx4 v[78:81], v0, s[18:19] offset:3072
	global_load_dwordx4 v[82:85], v0, s[6:7] offset:0
	global_load_dwordx4 v[86:89], v0, s[6:7] offset:1024
	global_load_dwordx4 v[90:93], v0, s[6:7] offset:2048
	global_load_dwordx4 v[94:97], v0, s[6:7] offset:3072
	s_add_u32 s6, s6, 0x1000
	s_addc_u32 s7, s7, 0
	global_load_dwordx4 v[98:101], v0, s[6:7] offset:0
	global_load_dwordx4 v[102:105], v0, s[6:7] offset:1024
	global_load_dwordx4 v[106:109], v0, s[6:7] offset:2048
	global_load_dwordx4 v[110:113], v0, s[6:7] offset:3072
	s_add_u32 s6, s6, 0x1000
	s_addc_u32 s7, s7, 0
	global_load_dwordx4 v[114:117], v0, s[6:7] offset:0
	global_load_dwordx4 v[118:121], v0, s[6:7] offset:1024
	global_load_dwordx4 v[122:125], v0, s[6:7] offset:2048
	global_load_dwordx4 v[126:129], v0, s[6:7] offset:3072
	s_add_u32 s6, s6, 0x1000
	s_addc_u32 s7, s7, 0
	global_load_dwordx4 v[138:141], v0, s[6:7] offset:0
	global_load_dwordx4 v[142:145], v0, s[6:7] offset:1024
	global_load_dwordx4 v[146:149], v0, s[6:7] offset:2048
	global_load_dwordx4 v[150:153], v0, s[6:7] offset:3072
	s_add_u32 s6, s6, 0x1000
	s_addc_u32 s7, s7, 0
	global_load_dwordx4 v[154:157], v0, s[6:7] offset:0
	global_load_dwordx4 v[158:161], v0, s[6:7] offset:1024
	global_load_dwordx4 v[162:165], v0, s[6:7] offset:2048
	global_load_dwordx4 v[166:169], v0, s[6:7] offset:3072
	s_add_u32 s6, s6, 0x1000
	s_addc_u32 s7, s7, 0
	global_load_dwordx4 v[170:173], v0, s[6:7] offset:0
	global_load_dwordx4 v[174:177], v0, s[6:7] offset:1024
	global_load_dwordx4 v[178:181], v0, s[6:7] offset:2048
	global_load_dwordx4 v[182:185], v0, s[6:7] offset:3072
	s_add_u32 s6, s6, 0x1000
	s_addc_u32 s7, s7, 0
	s_waitcnt vmcnt(20)
	v_pk_mul_f32 v[130:131], v[82:83], v[82:83]
	v_pk_fma_f32 v[130:131], v[84:85], v[84:85], v[130:131]
	v_pk_fma_f32 v[130:131], v[86:87], v[86:87], v[130:131]
	v_pk_fma_f32 v[130:131], v[88:89], v[88:89], v[130:131]
	v_pk_fma_f32 v[130:131], v[90:91], v[90:91], v[130:131]
	v_pk_fma_f32 v[130:131], v[92:93], v[92:93], v[130:131]
	v_pk_fma_f32 v[130:131], v[94:95], v[94:95], v[130:131]
	v_pk_fma_f32 v[130:131], v[96:97], v[96:97], v[130:131]
	v_add_f32_e32 v130, v130, v131
	s_nop 1
	v_add_f32_dpp v130, v130, v130 row_ror:8 row_mask:0xf bank_mask:0xf
	s_nop 1
	v_add_f32_dpp v130, v130, v130 row_ror:4 row_mask:0xf bank_mask:0xf
	s_nop 1
	v_add_f32_dpp v130, v130, v130 row_ror:2 row_mask:0xf bank_mask:0xf
	s_nop 1
	v_add_f32_dpp v130, v130, v130 row_ror:1 row_mask:0xf bank_mask:0xf
	s_nop 1
	s_nop 0
	v_readlane_b32 s0, v130, 0
	v_readlane_b32 s1, v130, 16
	v_readlane_b32 s22, v130, 32
	v_readlane_b32 s23, v130, 48
	s_nop 1
	v_mov_b32_e32 v132, s0
	v_add_f32_e32 v132, s1, v132
	v_add_f32_e32 v132, s22, v132
	v_add_f32_e32 v132, s23, v132
	v_fmamk_f32 v132, v132, 0x3a800000, v197
	v_rsq_f32_e32 v132, v132
	s_nop 0
	v_pk_add_f32 v[50:51], v[50:51], 1.0 op_sel_hi:[1,0]
	v_pk_add_f32 v[52:53], v[52:53], 1.0 op_sel_hi:[1,0]
	v_pk_add_f32 v[54:55], v[54:55], 1.0 op_sel_hi:[1,0]
	v_pk_add_f32 v[56:57], v[56:57], 1.0 op_sel_hi:[1,0]
	v_pk_add_f32 v[58:59], v[58:59], 1.0 op_sel_hi:[1,0]
	v_pk_add_f32 v[60:61], v[60:61], 1.0 op_sel_hi:[1,0]
	v_pk_add_f32 v[62:63], v[62:63], 1.0 op_sel_hi:[1,0]
	v_pk_add_f32 v[64:65], v[64:65], 1.0 op_sel_hi:[1,0]
	v_pk_mul_f32 v[82:83], v[82:83], v[132:133] op_sel_hi:[1,0]
	v_pk_mul_f32 v[84:85], v[84:85], v[132:133] op_sel_hi:[1,0]
	v_pk_mul_f32 v[86:87], v[86:87], v[132:133] op_sel_hi:[1,0]
	v_pk_mul_f32 v[88:89], v[88:89], v[132:133] op_sel_hi:[1,0]
	v_pk_mul_f32 v[90:91], v[90:91], v[132:133] op_sel_hi:[1,0]
	v_pk_mul_f32 v[92:93], v[92:93], v[132:133] op_sel_hi:[1,0]
	v_pk_mul_f32 v[94:95], v[94:95], v[132:133] op_sel_hi:[1,0]
	v_pk_mul_f32 v[96:97], v[96:97], v[132:133] op_sel_hi:[1,0]
	v_pk_mul_f32 v[82:83], v[2:3], v[82:83]
	v_pk_mul_f32 v[84:85], v[4:5], v[84:85]
	v_pk_mul_f32 v[86:87], v[6:7], v[86:87]
	v_pk_mul_f32 v[88:89], v[8:9], v[88:89]
	v_pk_mul_f32 v[90:91], v[10:11], v[90:91]
	v_pk_mul_f32 v[92:93], v[12:13], v[92:93]
	v_pk_mul_f32 v[94:95], v[14:15], v[94:95]
	v_pk_mul_f32 v[96:97], v[16:17], v[96:97]
	v_pk_fma_f32 v[82:83], v[50:51], v[82:83], v[66:67]
	v_pk_fma_f32 v[84:85], v[52:53], v[84:85], v[68:69]
	v_pk_fma_f32 v[86:87], v[54:55], v[86:87], v[70:71]
	v_pk_fma_f32 v[88:89], v[56:57], v[88:89], v[72:73]
	v_pk_fma_f32 v[90:91], v[58:59], v[90:91], v[74:75]
	v_pk_fma_f32 v[92:93], v[60:61], v[92:93], v[76:77]
	v_pk_fma_f32 v[94:95], v[62:63], v[94:95], v[78:79]
	v_pk_fma_f32 v[96:97], v[64:65], v[96:97], v[80:81]
	v_cvt_pk_bf16_f32 v82, v82, v83
	v_cvt_pk_bf16_f32 v83, v84, v85
	v_cvt_pk_bf16_f32 v84, v86, v87
	v_cvt_pk_bf16_f32 v85, v88, v89
	v_cvt_pk_bf16_f32 v86, v90, v91
	v_cvt_pk_bf16_f32 v87, v92, v93
	v_cvt_pk_bf16_f32 v88, v94, v95
	v_cvt_pk_bf16_f32 v89, v96, v97
	global_store_dwordx2 v1, v[82:83], s[10:11] offset:0
	global_store_dwordx2 v1, v[84:85], s[10:11] offset:512
	global_store_dwordx2 v1, v[86:87], s[10:11] offset:1024
	global_store_dwordx2 v1, v[88:89], s[10:11] offset:1536
	s_add_u32 s10, s10, 0x800
	s_addc_u32 s11, s11, 0
	global_load_dwordx4 v[82:85], v0, s[6:7] offset:0
	global_load_dwordx4 v[86:89], v0, s[6:7] offset:1024
	global_load_dwordx4 v[90:93], v0, s[6:7] offset:2048
	global_load_dwordx4 v[94:97], v0, s[6:7] offset:3072
	s_add_u32 s6, s6, 0x1000
	s_addc_u32 s7, s7, 0
	s_waitcnt vmcnt(24)
	v_pk_mul_f32 v[130:131], v[98:99], v[98:99]
	v_pk_fma_f32 v[130:131], v[100:101], v[100:101], v[130:131]
	v_pk_fma_f32 v[130:131], v[102:103], v[102:103], v[130:131]
	v_pk_fma_f32 v[130:131], v[104:105], v[104:105], v[130:131]
	v_pk_fma_f32 v[130:131], v[106:107], v[106:107], v[130:131]
	v_pk_fma_f32 v[130:131], v[108:109], v[108:109], v[130:131]
	v_pk_fma_f32 v[130:131], v[110:111], v[110:111], v[130:131]
	v_pk_fma_f32 v[130:131], v[112:113], v[112:113], v[130:131]
	v_add_f32_e32 v130, v130, v131
	s_nop 1
	v_add_f32_dpp v130, v130, v130 row_ror:8 row_mask:0xf bank_mask:0xf
	s_nop 1
	v_add_f32_dpp v130, v130, v130 row_ror:4 row_mask:0xf bank_mask:0xf
	s_nop 1
	v_add_f32_dpp v130, v130, v130 row_ror:2 row_mask:0xf bank_mask:0xf
	s_nop 1
	v_add_f32_dpp v130, v130, v130 row_ror:1 row_mask:0xf bank_mask:0xf
	s_nop 1
	s_nop 0
	v_readlane_b32 s0, v130, 0
	v_readlane_b32 s1, v130, 16
	v_readlane_b32 s22, v130, 32
	v_readlane_b32 s23, v130, 48
	s_nop 1
	v_mov_b32_e32 v132, s0
	v_add_f32_e32 v132, s1, v132
	v_add_f32_e32 v132, s22, v132
	v_add_f32_e32 v132, s23, v132
	v_fmamk_f32 v132, v132, 0x3a800000, v197
	v_rsq_f32_e32 v132, v132
	s_nop 0
	v_pk_mul_f32 v[98:99], v[98:99], v[132:133] op_sel_hi:[1,0]
	v_pk_mul_f32 v[100:101], v[100:101], v[132:133] op_sel_hi:[1,0]
	v_pk_mul_f32 v[102:103], v[102:103], v[132:133] op_sel_hi:[1,0]
	v_pk_mul_f32 v[104:105], v[104:105], v[132:133] op_sel_hi:[1,0]
	v_pk_mul_f32 v[106:107], v[106:107], v[132:133] op_sel_hi:[1,0]
	v_pk_mul_f32 v[108:109], v[108:109], v[132:133] op_sel_hi:[1,0]
	v_pk_mul_f32 v[110:111], v[110:111], v[132:133] op_sel_hi:[1,0]
	v_pk_mul_f32 v[112:113], v[112:113], v[132:133] op_sel_hi:[1,0]
	v_pk_mul_f32 v[98:99], v[2:3], v[98:99]
	v_pk_mul_f32 v[100:101], v[4:5], v[100:101]
	v_pk_mul_f32 v[102:103], v[6:7], v[102:103]
	v_pk_mul_f32 v[104:105], v[8:9], v[104:105]
	v_pk_mul_f32 v[106:107], v[10:11], v[106:107]
	v_pk_mul_f32 v[108:109], v[12:13], v[108:109]
	v_pk_mul_f32 v[110:111], v[14:15], v[110:111]
	v_pk_mul_f32 v[112:113], v[16:17], v[112:113]
	v_pk_fma_f32 v[98:99], v[50:51], v[98:99], v[66:67]
	v_pk_fma_f32 v[100:101], v[52:53], v[100:101], v[68:69]
	v_pk_fma_f32 v[102:103], v[54:55], v[102:103], v[70:71]
	v_pk_fma_f32 v[104:105], v[56:57], v[104:105], v[72:73]
	v_pk_fma_f32 v[106:107], v[58:59], v[106:107], v[74:75]
	v_pk_fma_f32 v[108:109], v[60:61], v[108:109], v[76:77]
	v_pk_fma_f32 v[110:111], v[62:63], v[110:111], v[78:79]
	v_pk_fma_f32 v[112:113], v[64:65], v[112:113], v[80:81]
	v_cvt_pk_bf16_f32 v98, v98, v99
	v_cvt_pk_bf16_f32 v99, v100, v101
	v_cvt_pk_bf16_f32 v100, v102, v103
	v_cvt_pk_bf16_f32 v101, v104, v105
	v_cvt_pk_bf16_f32 v102, v106, v107
	v_cvt_pk_bf16_f32 v103, v108, v109
	v_cvt_pk_bf16_f32 v104, v110, v111
	v_cvt_pk_bf16_f32 v105, v112, v113
	global_store_dwordx2 v1, v[98:99], s[10:11] offset:0
	global_store_dwordx2 v1, v[100:101], s[10:11] offset:512
	global_store_dwordx2 v1, v[102:103], s[10:11] offset:1024
	global_store_dwordx2 v1, v[104:105], s[10:11] offset:1536
	s_add_u32 s10, s10, 0x800
	s_addc_u32 s11, s11, 0
	global_load_dwordx4 v[98:101], v0, s[6:7] offset:0
	global_load_dwordx4 v[102:105], v0, s[6:7] offset:1024
	global_load_dwordx4 v[106:109], v0, s[6:7] offset:2048
	global_load_dwordx4 v[110:113], v0, s[6:7] offset:3072
	s_waitcnt vmcnt(28)
	v_pk_mul_f32 v[130:131], v[114:115], v[114:115]
	v_pk_fma_f32 v[130:131], v[116:117], v[116:117], v[130:131]
	v_pk_fma_f32 v[130:131], v[118:119], v[118:119], v[130:131]
	v_pk_fma_f32 v[130:131], v[120:121], v[120:121], v[130:131]
	v_pk_fma_f32 v[130:131], v[122:123], v[122:123], v[130:131]
	v_pk_fma_f32 v[130:131], v[124:125], v[124:125], v[130:131]
	v_pk_fma_f32 v[130:131], v[126:127], v[126:127], v[130:131]
	v_pk_fma_f32 v[130:131], v[128:129], v[128:129], v[130:131]
	v_add_f32_e32 v130, v130, v131
	s_nop 1
	v_add_f32_dpp v130, v130, v130 row_ror:8 row_mask:0xf bank_mask:0xf
	s_nop 1
	v_add_f32_dpp v130, v130, v130 row_ror:4 row_mask:0xf bank_mask:0xf
	s_nop 1
	v_add_f32_dpp v130, v130, v130 row_ror:2 row_mask:0xf bank_mask:0xf
	s_nop 1
	v_add_f32_dpp v130, v130, v130 row_ror:1 row_mask:0xf bank_mask:0xf
	s_nop 1
	s_nop 0
	v_readlane_b32 s0, v130, 0
	v_readlane_b32 s1, v130, 16
	v_readlane_b32 s22, v130, 32
	v_readlane_b32 s23, v130, 48
	s_nop 1
	v_mov_b32_e32 v132, s0
	v_add_f32_e32 v132, s1, v132
	v_add_f32_e32 v132, s22, v132
	v_add_f32_e32 v132, s23, v132
	v_fmamk_f32 v132, v132, 0x3a800000, v197
	v_rsq_f32_e32 v132, v132
	s_nop 0
	v_pk_mul_f32 v[114:115], v[114:115], v[132:133] op_sel_hi:[1,0]
	v_pk_mul_f32 v[116:117], v[116:117], v[132:133] op_sel_hi:[1,0]
	v_pk_mul_f32 v[118:119], v[118:119], v[132:133] op_sel_hi:[1,0]
	v_pk_mul_f32 v[120:121], v[120:121], v[132:133] op_sel_hi:[1,0]
	v_pk_mul_f32 v[122:123], v[122:123], v[132:133] op_sel_hi:[1,0]
	v_pk_mul_f32 v[124:125], v[124:125], v[132:133] op_sel_hi:[1,0]
	v_pk_mul_f32 v[126:127], v[126:127], v[132:133] op_sel_hi:[1,0]
	v_pk_mul_f32 v[128:129], v[128:129], v[132:133] op_sel_hi:[1,0]
	v_pk_mul_f32 v[114:115], v[2:3], v[114:115]
	v_pk_mul_f32 v[116:117], v[4:5], v[116:117]
	v_pk_mul_f32 v[118:119], v[6:7], v[118:119]
	v_pk_mul_f32 v[120:121], v[8:9], v[120:121]
	v_pk_mul_f32 v[122:123], v[10:11], v[122:123]
	v_pk_mul_f32 v[124:125], v[12:13], v[124:125]
	v_pk_mul_f32 v[126:127], v[14:15], v[126:127]
	v_pk_mul_f32 v[128:129], v[16:17], v[128:129]
	v_pk_fma_f32 v[114:115], v[50:51], v[114:115], v[66:67]
	v_pk_fma_f32 v[116:117], v[52:53], v[116:117], v[68:69]
	v_pk_fma_f32 v[118:119], v[54:55], v[118:119], v[70:71]
	v_pk_fma_f32 v[120:121], v[56:57], v[120:121], v[72:73]
	v_pk_fma_f32 v[122:123], v[58:59], v[122:123], v[74:75]
	v_pk_fma_f32 v[124:125], v[60:61], v[124:125], v[76:77]
	v_pk_fma_f32 v[126:127], v[62:63], v[126:127], v[78:79]
	v_pk_fma_f32 v[128:129], v[64:65], v[128:129], v[80:81]
	v_cvt_pk_bf16_f32 v114, v114, v115
	v_cvt_pk_bf16_f32 v115, v116, v117
	v_cvt_pk_bf16_f32 v116, v118, v119
	v_cvt_pk_bf16_f32 v117, v120, v121
	v_cvt_pk_bf16_f32 v118, v122, v123
	v_cvt_pk_bf16_f32 v119, v124, v125
	v_cvt_pk_bf16_f32 v120, v126, v127
	v_cvt_pk_bf16_f32 v121, v128, v129
	global_store_dwordx2 v1, v[114:115], s[10:11] offset:0
	global_store_dwordx2 v1, v[116:117], s[10:11] offset:512
	global_store_dwordx2 v1, v[118:119], s[10:11] offset:1024
	global_store_dwordx2 v1, v[120:121], s[10:11] offset:1536
	s_add_u32 s10, s10, 0x800
	s_addc_u32 s11, s11, 0
	s_waitcnt vmcnt(28)
	v_pk_mul_f32 v[130:131], v[138:139], v[138:139]
	v_pk_fma_f32 v[130:131], v[140:141], v[140:141], v[130:131]
	v_pk_fma_f32 v[130:131], v[142:143], v[142:143], v[130:131]
	v_pk_fma_f32 v[130:131], v[144:145], v[144:145], v[130:131]
	v_pk_fma_f32 v[130:131], v[146:147], v[146:147], v[130:131]
	v_pk_fma_f32 v[130:131], v[148:149], v[148:149], v[130:131]
	v_pk_fma_f32 v[130:131], v[150:151], v[150:151], v[130:131]
	v_pk_fma_f32 v[130:131], v[152:153], v[152:153], v[130:131]
	v_add_f32_e32 v130, v130, v131
	s_nop 1
	v_add_f32_dpp v130, v130, v130 row_ror:8 row_mask:0xf bank_mask:0xf
	s_nop 1
	v_add_f32_dpp v130, v130, v130 row_ror:4 row_mask:0xf bank_mask:0xf
	s_nop 1
	v_add_f32_dpp v130, v130, v130 row_ror:2 row_mask:0xf bank_mask:0xf
	s_nop 1
	v_add_f32_dpp v130, v130, v130 row_ror:1 row_mask:0xf bank_mask:0xf
	s_nop 1
	s_nop 0
	v_readlane_b32 s0, v130, 0
	v_readlane_b32 s1, v130, 16
	v_readlane_b32 s22, v130, 32
	v_readlane_b32 s23, v130, 48
	s_nop 1
	v_mov_b32_e32 v132, s0
	v_add_f32_e32 v132, s1, v132
	v_add_f32_e32 v132, s22, v132
	v_add_f32_e32 v132, s23, v132
	v_fmamk_f32 v132, v132, 0x3a800000, v197
	v_rsq_f32_e32 v132, v132
	s_nop 0
	v_pk_mul_f32 v[138:139], v[138:139], v[132:133] op_sel_hi:[1,0]
	v_pk_mul_f32 v[140:141], v[140:141], v[132:133] op_sel_hi:[1,0]
	v_pk_mul_f32 v[142:143], v[142:143], v[132:133] op_sel_hi:[1,0]
	v_pk_mul_f32 v[144:145], v[144:145], v[132:133] op_sel_hi:[1,0]
	v_pk_mul_f32 v[146:147], v[146:147], v[132:133] op_sel_hi:[1,0]
	v_pk_mul_f32 v[148:149], v[148:149], v[132:133] op_sel_hi:[1,0]
	v_pk_mul_f32 v[150:151], v[150:151], v[132:133] op_sel_hi:[1,0]
	v_pk_mul_f32 v[152:153], v[152:153], v[132:133] op_sel_hi:[1,0]
	v_pk_mul_f32 v[138:139], v[2:3], v[138:139]
	v_pk_mul_f32 v[140:141], v[4:5], v[140:141]
	v_pk_mul_f32 v[142:143], v[6:7], v[142:143]
	v_pk_mul_f32 v[144:145], v[8:9], v[144:145]
	v_pk_mul_f32 v[146:147], v[10:11], v[146:147]
	v_pk_mul_f32 v[148:149], v[12:13], v[148:149]
	v_pk_mul_f32 v[150:151], v[14:15], v[150:151]
	v_pk_mul_f32 v[152:153], v[16:17], v[152:153]
	v_pk_fma_f32 v[138:139], v[50:51], v[138:139], v[66:67]
	v_pk_fma_f32 v[140:141], v[52:53], v[140:141], v[68:69]
	v_pk_fma_f32 v[142:143], v[54:55], v[142:143], v[70:71]
	v_pk_fma_f32 v[144:145], v[56:57], v[144:145], v[72:73]
	v_pk_fma_f32 v[146:147], v[58:59], v[146:147], v[74:75]
	v_pk_fma_f32 v[148:149], v[60:61], v[148:149], v[76:77]
	v_pk_fma_f32 v[150:151], v[62:63], v[150:151], v[78:79]
	v_pk_fma_f32 v[152:153], v[64:65], v[152:153], v[80:81]
	v_cvt_pk_bf16_f32 v138, v138, v139
	v_cvt_pk_bf16_f32 v139, v140, v141
	v_cvt_pk_bf16_f32 v140, v142, v143
	v_cvt_pk_bf16_f32 v141, v144, v145
	v_cvt_pk_bf16_f32 v142, v146, v147
	v_cvt_pk_bf16_f32 v143, v148, v149
	v_cvt_pk_bf16_f32 v144, v150, v151
	v_cvt_pk_bf16_f32 v145, v152, v153
	global_store_dwordx2 v1, v[138:139], s[10:11] offset:0
	global_store_dwordx2 v1, v[140:141], s[10:11] offset:512
	global_store_dwordx2 v1, v[142:143], s[10:11] offset:1024
	global_store_dwordx2 v1, v[144:145], s[10:11] offset:1536
	s_add_u32 s10, s10, 0x800
	s_addc_u32 s11, s11, 0
	s_waitcnt vmcnt(28)
	v_pk_mul_f32 v[130:131], v[154:155], v[154:155]
	v_pk_fma_f32 v[130:131], v[156:157], v[156:157], v[130:131]
	v_pk_fma_f32 v[130:131], v[158:159], v[158:159], v[130:131]
	v_pk_fma_f32 v[130:131], v[160:161], v[160:161], v[130:131]
	v_pk_fma_f32 v[130:131], v[162:163], v[162:163], v[130:131]
	v_pk_fma_f32 v[130:131], v[164:165], v[164:165], v[130:131]
	v_pk_fma_f32 v[130:131], v[166:167], v[166:167], v[130:131]
	v_pk_fma_f32 v[130:131], v[168:169], v[168:169], v[130:131]
	v_add_f32_e32 v130, v130, v131
	s_nop 1
	v_add_f32_dpp v130, v130, v130 row_ror:8 row_mask:0xf bank_mask:0xf
	s_nop 1
	v_add_f32_dpp v130, v130, v130 row_ror:4 row_mask:0xf bank_mask:0xf
	s_nop 1
	v_add_f32_dpp v130, v130, v130 row_ror:2 row_mask:0xf bank_mask:0xf
	s_nop 1
	v_add_f32_dpp v130, v130, v130 row_ror:1 row_mask:0xf bank_mask:0xf
	s_nop 1
	s_nop 0
	v_readlane_b32 s0, v130, 0
	v_readlane_b32 s1, v130, 16
	v_readlane_b32 s22, v130, 32
	v_readlane_b32 s23, v130, 48
	s_nop 1
	v_mov_b32_e32 v132, s0
	v_add_f32_e32 v132, s1, v132
	v_add_f32_e32 v132, s22, v132
	v_add_f32_e32 v132, s23, v132
	v_fmamk_f32 v132, v132, 0x3a800000, v197
	v_rsq_f32_e32 v132, v132
	s_nop 0
	v_pk_mul_f32 v[154:155], v[154:155], v[132:133] op_sel_hi:[1,0]
	v_pk_mul_f32 v[156:157], v[156:157], v[132:133] op_sel_hi:[1,0]
	v_pk_mul_f32 v[158:159], v[158:159], v[132:133] op_sel_hi:[1,0]
	v_pk_mul_f32 v[160:161], v[160:161], v[132:133] op_sel_hi:[1,0]
	v_pk_mul_f32 v[162:163], v[162:163], v[132:133] op_sel_hi:[1,0]
	v_pk_mul_f32 v[164:165], v[164:165], v[132:133] op_sel_hi:[1,0]
	v_pk_mul_f32 v[166:167], v[166:167], v[132:133] op_sel_hi:[1,0]
	v_pk_mul_f32 v[168:169], v[168:169], v[132:133] op_sel_hi:[1,0]
	v_pk_mul_f32 v[154:155], v[2:3], v[154:155]
	v_pk_mul_f32 v[156:157], v[4:5], v[156:157]
	v_pk_mul_f32 v[158:159], v[6:7], v[158:159]
	v_pk_mul_f32 v[160:161], v[8:9], v[160:161]
	v_pk_mul_f32 v[162:163], v[10:11], v[162:163]
	v_pk_mul_f32 v[164:165], v[12:13], v[164:165]
	v_pk_mul_f32 v[166:167], v[14:15], v[166:167]
	v_pk_mul_f32 v[168:169], v[16:17], v[168:169]
	v_pk_fma_f32 v[154:155], v[50:51], v[154:155], v[66:67]
	v_pk_fma_f32 v[156:157], v[52:53], v[156:157], v[68:69]
	v_pk_fma_f32 v[158:159], v[54:55], v[158:159], v[70:71]
	v_pk_fma_f32 v[160:161], v[56:57], v[160:161], v[72:73]
	v_pk_fma_f32 v[162:163], v[58:59], v[162:163], v[74:75]
	v_pk_fma_f32 v[164:165], v[60:61], v[164:165], v[76:77]
	v_pk_fma_f32 v[166:167], v[62:63], v[166:167], v[78:79]
	v_pk_fma_f32 v[168:169], v[64:65], v[168:169], v[80:81]
	v_cvt_pk_bf16_f32 v154, v154, v155
	v_cvt_pk_bf16_f32 v155, v156, v157
	v_cvt_pk_bf16_f32 v156, v158, v159
	v_cvt_pk_bf16_f32 v157, v160, v161
	v_cvt_pk_bf16_f32 v158, v162, v163
	v_cvt_pk_bf16_f32 v159, v164, v165
	v_cvt_pk_bf16_f32 v160, v166, v167
	v_cvt_pk_bf16_f32 v161, v168, v169
	global_store_dwordx2 v1, v[154:155], s[10:11] offset:0
	global_store_dwordx2 v1, v[156:157], s[10:11] offset:512
	global_store_dwordx2 v1, v[158:159], s[10:11] offset:1024
	global_store_dwordx2 v1, v[160:161], s[10:11] offset:1536
	s_add_u32 s10, s10, 0x800
	s_addc_u32 s11, s11, 0
	s_waitcnt vmcnt(28)
	v_pk_mul_f32 v[130:131], v[170:171], v[170:171]
	v_pk_fma_f32 v[130:131], v[172:173], v[172:173], v[130:131]
	v_pk_fma_f32 v[130:131], v[174:175], v[174:175], v[130:131]
	v_pk_fma_f32 v[130:131], v[176:177], v[176:177], v[130:131]
	v_pk_fma_f32 v[130:131], v[178:179], v[178:179], v[130:131]
	v_pk_fma_f32 v[130:131], v[180:181], v[180:181], v[130:131]
	v_pk_fma_f32 v[130:131], v[182:183], v[182:183], v[130:131]
	v_pk_fma_f32 v[130:131], v[184:185], v[184:185], v[130:131]
	v_add_f32_e32 v130, v130, v131
	s_nop 1
	v_add_f32_dpp v130, v130, v130 row_ror:8 row_mask:0xf bank_mask:0xf
	s_nop 1
	v_add_f32_dpp v130, v130, v130 row_ror:4 row_mask:0xf bank_mask:0xf
	s_nop 1
	v_add_f32_dpp v130, v130, v130 row_ror:2 row_mask:0xf bank_mask:0xf
	s_nop 1
	v_add_f32_dpp v130, v130, v130 row_ror:1 row_mask:0xf bank_mask:0xf
	s_nop 1
	s_nop 0
	v_readlane_b32 s0, v130, 0
	v_readlane_b32 s1, v130, 16
	v_readlane_b32 s22, v130, 32
	v_readlane_b32 s23, v130, 48
	s_nop 1
	v_mov_b32_e32 v132, s0
	v_add_f32_e32 v132, s1, v132
	v_add_f32_e32 v132, s22, v132
	v_add_f32_e32 v132, s23, v132
	v_fmamk_f32 v132, v132, 0x3a800000, v197
	v_rsq_f32_e32 v132, v132
	s_nop 0
	v_pk_mul_f32 v[170:171], v[170:171], v[132:133] op_sel_hi:[1,0]
	v_pk_mul_f32 v[172:173], v[172:173], v[132:133] op_sel_hi:[1,0]
	v_pk_mul_f32 v[174:175], v[174:175], v[132:133] op_sel_hi:[1,0]
	v_pk_mul_f32 v[176:177], v[176:177], v[132:133] op_sel_hi:[1,0]
	v_pk_mul_f32 v[178:179], v[178:179], v[132:133] op_sel_hi:[1,0]
	v_pk_mul_f32 v[180:181], v[180:181], v[132:133] op_sel_hi:[1,0]
	v_pk_mul_f32 v[182:183], v[182:183], v[132:133] op_sel_hi:[1,0]
	v_pk_mul_f32 v[184:185], v[184:185], v[132:133] op_sel_hi:[1,0]
	v_pk_mul_f32 v[170:171], v[2:3], v[170:171]
	v_pk_mul_f32 v[172:173], v[4:5], v[172:173]
	v_pk_mul_f32 v[174:175], v[6:7], v[174:175]
	v_pk_mul_f32 v[176:177], v[8:9], v[176:177]
	v_pk_mul_f32 v[178:179], v[10:11], v[178:179]
	v_pk_mul_f32 v[180:181], v[12:13], v[180:181]
	v_pk_mul_f32 v[182:183], v[14:15], v[182:183]
	v_pk_mul_f32 v[184:185], v[16:17], v[184:185]
	v_pk_fma_f32 v[170:171], v[50:51], v[170:171], v[66:67]
	v_pk_fma_f32 v[172:173], v[52:53], v[172:173], v[68:69]
	v_pk_fma_f32 v[174:175], v[54:55], v[174:175], v[70:71]
	v_pk_fma_f32 v[176:177], v[56:57], v[176:177], v[72:73]
	v_pk_fma_f32 v[178:179], v[58:59], v[178:179], v[74:75]
	v_pk_fma_f32 v[180:181], v[60:61], v[180:181], v[76:77]
	v_pk_fma_f32 v[182:183], v[62:63], v[182:183], v[78:79]
	v_pk_fma_f32 v[184:185], v[64:65], v[184:185], v[80:81]
	v_cvt_pk_bf16_f32 v170, v170, v171
	v_cvt_pk_bf16_f32 v171, v172, v173
	v_cvt_pk_bf16_f32 v172, v174, v175
	v_cvt_pk_bf16_f32 v173, v176, v177
	v_cvt_pk_bf16_f32 v174, v178, v179
	v_cvt_pk_bf16_f32 v175, v180, v181
	v_cvt_pk_bf16_f32 v176, v182, v183
	v_cvt_pk_bf16_f32 v177, v184, v185
	global_store_dwordx2 v1, v[170:171], s[10:11] offset:0
	global_store_dwordx2 v1, v[172:173], s[10:11] offset:512
	global_store_dwordx2 v1, v[174:175], s[10:11] offset:1024
	global_store_dwordx2 v1, v[176:177], s[10:11] offset:1536
	s_add_u32 s10, s10, 0x800
	s_addc_u32 s11, s11, 0
	s_waitcnt vmcnt(24)
	v_pk_mul_f32 v[130:131], v[82:83], v[82:83]
	v_pk_fma_f32 v[130:131], v[84:85], v[84:85], v[130:131]
	v_pk_fma_f32 v[130:131], v[86:87], v[86:87], v[130:131]
	v_pk_fma_f32 v[130:131], v[88:89], v[88:89], v[130:131]
	v_pk_fma_f32 v[130:131], v[90:91], v[90:91], v[130:131]
	v_pk_fma_f32 v[130:131], v[92:93], v[92:93], v[130:131]
	v_pk_fma_f32 v[130:131], v[94:95], v[94:95], v[130:131]
	v_pk_fma_f32 v[130:131], v[96:97], v[96:97], v[130:131]
	v_add_f32_e32 v130, v130, v131
	s_nop 1
	v_add_f32_dpp v130, v130, v130 row_ror:8 row_mask:0xf bank_mask:0xf
	s_nop 1
	v_add_f32_dpp v130, v130, v130 row_ror:4 row_mask:0xf bank_mask:0xf
	s_nop 1
	v_add_f32_dpp v130, v130, v130 row_ror:2 row_mask:0xf bank_mask:0xf
	s_nop 1
	v_add_f32_dpp v130, v130, v130 row_ror:1 row_mask:0xf bank_mask:0xf
	s_nop 1
	s_nop 0
	v_readlane_b32 s0, v130, 0
	v_readlane_b32 s1, v130, 16
	v_readlane_b32 s22, v130, 32
	v_readlane_b32 s23, v130, 48
	s_nop 1
	v_mov_b32_e32 v132, s0
	v_add_f32_e32 v132, s1, v132
	v_add_f32_e32 v132, s22, v132
	v_add_f32_e32 v132, s23, v132
	v_fmamk_f32 v132, v132, 0x3a800000, v197
	v_rsq_f32_e32 v132, v132
	s_nop 0
	v_pk_mul_f32 v[82:83], v[82:83], v[132:133] op_sel_hi:[1,0]
	v_pk_mul_f32 v[84:85], v[84:85], v[132:133] op_sel_hi:[1,0]
	v_pk_mul_f32 v[86:87], v[86:87], v[132:133] op_sel_hi:[1,0]
	v_pk_mul_f32 v[88:89], v[88:89], v[132:133] op_sel_hi:[1,0]
	v_pk_mul_f32 v[90:91], v[90:91], v[132:133] op_sel_hi:[1,0]
	v_pk_mul_f32 v[92:93], v[92:93], v[132:133] op_sel_hi:[1,0]
	v_pk_mul_f32 v[94:95], v[94:95], v[132:133] op_sel_hi:[1,0]
	v_pk_mul_f32 v[96:97], v[96:97], v[132:133] op_sel_hi:[1,0]
	v_pk_mul_f32 v[82:83], v[2:3], v[82:83]
	v_pk_mul_f32 v[84:85], v[4:5], v[84:85]
	v_pk_mul_f32 v[86:87], v[6:7], v[86:87]
	v_pk_mul_f32 v[88:89], v[8:9], v[88:89]
	v_pk_mul_f32 v[90:91], v[10:11], v[90:91]
	v_pk_mul_f32 v[92:93], v[12:13], v[92:93]
	v_pk_mul_f32 v[94:95], v[14:15], v[94:95]
	v_pk_mul_f32 v[96:97], v[16:17], v[96:97]
	v_pk_fma_f32 v[82:83], v[50:51], v[82:83], v[66:67]
	v_pk_fma_f32 v[84:85], v[52:53], v[84:85], v[68:69]
	v_pk_fma_f32 v[86:87], v[54:55], v[86:87], v[70:71]
	v_pk_fma_f32 v[88:89], v[56:57], v[88:89], v[72:73]
	v_pk_fma_f32 v[90:91], v[58:59], v[90:91], v[74:75]
	v_pk_fma_f32 v[92:93], v[60:61], v[92:93], v[76:77]
	v_pk_fma_f32 v[94:95], v[62:63], v[94:95], v[78:79]
	v_pk_fma_f32 v[96:97], v[64:65], v[96:97], v[80:81]
	v_cvt_pk_bf16_f32 v82, v82, v83
	v_cvt_pk_bf16_f32 v83, v84, v85
	v_cvt_pk_bf16_f32 v84, v86, v87
	v_cvt_pk_bf16_f32 v85, v88, v89
	v_cvt_pk_bf16_f32 v86, v90, v91
	v_cvt_pk_bf16_f32 v87, v92, v93
	v_cvt_pk_bf16_f32 v88, v94, v95
	v_cvt_pk_bf16_f32 v89, v96, v97
	global_store_dwordx2 v1, v[82:83], s[10:11] offset:0
	global_store_dwordx2 v1, v[84:85], s[10:11] offset:512
	global_store_dwordx2 v1, v[86:87], s[10:11] offset:1024
	global_store_dwordx2 v1, v[88:89], s[10:11] offset:1536
	s_add_u32 s10, s10, 0x800
	s_addc_u32 s11, s11, 0
	s_waitcnt vmcnt(20)
	v_pk_mul_f32 v[130:131], v[98:99], v[98:99]
	v_pk_fma_f32 v[130:131], v[100:101], v[100:101], v[130:131]
	v_pk_fma_f32 v[130:131], v[102:103], v[102:103], v[130:131]
	v_pk_fma_f32 v[130:131], v[104:105], v[104:105], v[130:131]
	v_pk_fma_f32 v[130:131], v[106:107], v[106:107], v[130:131]
	v_pk_fma_f32 v[130:131], v[108:109], v[108:109], v[130:131]
	v_pk_fma_f32 v[130:131], v[110:111], v[110:111], v[130:131]
	v_pk_fma_f32 v[130:131], v[112:113], v[112:113], v[130:131]
	v_add_f32_e32 v130, v130, v131
	s_nop 1
	v_add_f32_dpp v130, v130, v130 row_ror:8 row_mask:0xf bank_mask:0xf
	s_nop 1
	v_add_f32_dpp v130, v130, v130 row_ror:4 row_mask:0xf bank_mask:0xf
	s_nop 1
	v_add_f32_dpp v130, v130, v130 row_ror:2 row_mask:0xf bank_mask:0xf
	s_nop 1
	v_add_f32_dpp v130, v130, v130 row_ror:1 row_mask:0xf bank_mask:0xf
	s_nop 1
	s_nop 0
	v_readlane_b32 s0, v130, 0
	v_readlane_b32 s1, v130, 16
	v_readlane_b32 s22, v130, 32
	v_readlane_b32 s23, v130, 48
	s_nop 1
	v_mov_b32_e32 v132, s0
	v_add_f32_e32 v132, s1, v132
	v_add_f32_e32 v132, s22, v132
	v_add_f32_e32 v132, s23, v132
	v_fmamk_f32 v132, v132, 0x3a800000, v197
	v_rsq_f32_e32 v132, v132
	s_nop 0
	v_pk_mul_f32 v[98:99], v[98:99], v[132:133] op_sel_hi:[1,0]
	v_pk_mul_f32 v[100:101], v[100:101], v[132:133] op_sel_hi:[1,0]
	v_pk_mul_f32 v[102:103], v[102:103], v[132:133] op_sel_hi:[1,0]
	v_pk_mul_f32 v[104:105], v[104:105], v[132:133] op_sel_hi:[1,0]
	v_pk_mul_f32 v[106:107], v[106:107], v[132:133] op_sel_hi:[1,0]
	v_pk_mul_f32 v[108:109], v[108:109], v[132:133] op_sel_hi:[1,0]
	v_pk_mul_f32 v[110:111], v[110:111], v[132:133] op_sel_hi:[1,0]
	v_pk_mul_f32 v[112:113], v[112:113], v[132:133] op_sel_hi:[1,0]
	v_pk_mul_f32 v[98:99], v[2:3], v[98:99]
	v_pk_mul_f32 v[100:101], v[4:5], v[100:101]
	v_pk_mul_f32 v[102:103], v[6:7], v[102:103]
	v_pk_mul_f32 v[104:105], v[8:9], v[104:105]
	v_pk_mul_f32 v[106:107], v[10:11], v[106:107]
	v_pk_mul_f32 v[108:109], v[12:13], v[108:109]
	v_pk_mul_f32 v[110:111], v[14:15], v[110:111]
	v_pk_mul_f32 v[112:113], v[16:17], v[112:113]
	v_pk_fma_f32 v[98:99], v[50:51], v[98:99], v[66:67]
	v_pk_fma_f32 v[100:101], v[52:53], v[100:101], v[68:69]
	v_pk_fma_f32 v[102:103], v[54:55], v[102:103], v[70:71]
	v_pk_fma_f32 v[104:105], v[56:57], v[104:105], v[72:73]
	v_pk_fma_f32 v[106:107], v[58:59], v[106:107], v[74:75]
	v_pk_fma_f32 v[108:109], v[60:61], v[108:109], v[76:77]
	v_pk_fma_f32 v[110:111], v[62:63], v[110:111], v[78:79]
	v_pk_fma_f32 v[112:113], v[64:65], v[112:113], v[80:81]
	v_cvt_pk_bf16_f32 v98, v98, v99
	v_cvt_pk_bf16_f32 v99, v100, v101
	v_cvt_pk_bf16_f32 v100, v102, v103
	v_cvt_pk_bf16_f32 v101, v104, v105
	v_cvt_pk_bf16_f32 v102, v106, v107
	v_cvt_pk_bf16_f32 v103, v108, v109
	v_cvt_pk_bf16_f32 v104, v110, v111
	v_cvt_pk_bf16_f32 v105, v112, v113
	global_store_dwordx2 v1, v[98:99], s[10:11] offset:0
	global_store_dwordx2 v1, v[100:101], s[10:11] offset:512
	global_store_dwordx2 v1, v[102:103], s[10:11] offset:1024
	global_store_dwordx2 v1, v[104:105], s[10:11] offset:1536
.Lrn_p1_end:
.LBB0_620:
	s_bitcmp0_b32 s94, 14
	s_cbranch_scc1 .LBB0_624
	v_lshlrev_b32_e32 v0, 4, v205
	v_lshlrev_b32_e32 v1, 3, v205
	v_readlane_b32 s0, v245, 21
	s_lshl_b32 s1, s24, 12
	s_add_u32 s1, s1, 0x221320
	s_add_u32 s14, s4, s1
	s_addc_u32 s15, s5, 0
	global_load_dwordx4 v[2:5], v0, s[14:15] offset:0
	global_load_dwordx4 v[6:9], v0, s[14:15] offset:1024
	global_load_dwordx4 v[10:13], v0, s[14:15] offset:2048
	global_load_dwordx4 v[14:17], v0, s[14:15] offset:3072
	s_lshl_b32 s1, s0, 3
	s_addk_i32 s1, 0x400
	s_mul_i32 s18, s1, 0x600
	s_add_u32 s18, s18, 0xdf00000
	s_add_u32 s6, s4, s18
	s_addc_u32 s7, s5, 0
	s_lshl_b32 s18, s1, 10
	s_add_u32 s18, s18, 0xce00000
	s_add_u32 s8, s4, s18
	s_addc_u32 s9, s5, 0
	s_lshl_b32 s18, s1, 11
	s_add_u32 s18, s18, 0x3c00000
	s_add_u32 s10, s4, s18
	s_addc_u32 s11, s5, 0
	s_cmp_lt_u32 s0, 0x400
	s_cselect_b32 s1, 1, 0
	s_cmp_eq_u32 s27, 0
	s_cselect_b32 s1, s1, 0
	s_cmp_eq_u32 s1, 1
	s_cbranch_scc0 .Lrn_gn_noctx
	s_mul_i32 s18, s0, 0x600
	s_add_u32 s18, s18, 0xdf00000
	s_add_u32 s12, s4, s18
	s_addc_u32 s13, s5, 0
	s_lshl_b32 s18, s0, 10
	s_add_u32 s18, s18, 0xce00000
	s_add_u32 s14, s4, s18
	s_addc_u32 s15, s5, 0
	s_lshl_b32 s18, s0, 11
	s_add_u32 s18, s18, 0x3c00000
	s_add_u32 s16, s4, s18
	s_addc_u32 s17, s5, 0
	global_load_dwordx2 v[18:19], v1, s[12:13] offset:0
	global_load_dwordx2 v[20:21], v1, s[12:13] offset:512
	global_load_dwordx2 v[22:23], v1, s[12:13] offset:1024
	global_load_dwordx2 v[24:25], v1, s[14:15]
	global_load_dwordx2 v[26:27], v1, s[14:15] offset:512
	global_load_dwordx2 v[28:29], v1, s[6:7] offset:0
	global_load_dwordx2 v[30:31], v1, s[6:7] offset:512
	global_load_dwordx2 v[32:33], v1, s[6:7] offset:1024
	global_load_dwordx2 v[34:35], v1, s[8:9]
	global_load_dwordx2 v[36:37], v1, s[8:9] offset:512
	s_add_u32 s6, s6, 0x600
	s_addc_u32 s7, s7, 0
	s_add_u32 s8, s8, 0x400
	s_addc_u32 s9, s9, 0
	global_load_dwordx2 v[38:39], v1, s[6:7] offset:0
	global_load_dwordx2 v[40:41], v1, s[6:7] offset:512
	global_load_dwordx2 v[42:43], v1, s[6:7] offset:1024
	global_load_dwordx2 v[44:45], v1, s[8:9]
	global_load_dwordx2 v[46:47], v1, s[8:9] offset:512
	s_add_u32 s6, s6, 0x600
	s_addc_u32 s7, s7, 0
	s_add_u32 s8, s8, 0x400
	s_addc_u32 s9, s9, 0
	global_load_dwordx2 v[48:49], v1, s[6:7] offset:0
	global_load_dwordx2 v[50:51], v1, s[6:7] offset:512
	global_load_dwordx2 v[52:53], v1, s[6:7] offset:1024
	global_load_dwordx2 v[54:55], v1, s[8:9]
	global_load_dwordx2 v[56:57], v1, s[8:9] offset:512
	s_add_u32 s6, s6, 0x600
	s_addc_u32 s7, s7, 0
	s_add_u32 s8, s8, 0x400
	s_addc_u32 s9, s9, 0
	global_load_dwordx2 v[58:59], v1, s[6:7] offset:0
	global_load_dwordx2 v[60:61], v1, s[6:7] offset:512
	global_load_dwordx2 v[62:63], v1, s[6:7] offset:1024
	global_load_dwordx2 v[64:65], v1, s[8:9]
	global_load_dwordx2 v[66:67], v1, s[8:9] offset:512
	s_add_u32 s6, s6, 0x600
	s_addc_u32 s7, s7, 0
	s_add_u32 s8, s8, 0x400
	s_addc_u32 s9, s9, 0
	global_load_dwordx2 v[68:69], v1, s[6:7] offset:0
	global_load_dwordx2 v[70:71], v1, s[6:7] offset:512
	global_load_dwordx2 v[72:73], v1, s[6:7] offset:1024
	global_load_dwordx2 v[74:75], v1, s[8:9]
	global_load_dwordx2 v[76:77], v1, s[8:9] offset:512
	s_add_u32 s6, s6, 0x600
	s_addc_u32 s7, s7, 0
	s_add_u32 s8, s8, 0x400
	s_addc_u32 s9, s9, 0
	s_waitcnt vmcnt(25)
	v_lshlrev_b32_e32 v80, 16, v18
	v_and_b32_e32 v81, 0xffff0000, v18
	v_lshlrev_b32_e32 v82, 16, v19
	v_and_b32_e32 v83, 0xffff0000, v19
	v_lshlrev_b32_e32 v84, 16, v20
	v_and_b32_e32 v85, 0xffff0000, v20
	v_lshlrev_b32_e32 v86, 16, v21
	v_and_b32_e32 v87, 0xffff0000, v21
	v_lshlrev_b32_e32 v88, 16, v22
	v_and_b32_e32 v89, 0xffff0000, v22
	v_lshlrev_b32_e32 v90, 16, v23
	v_and_b32_e32 v91, 0xffff0000, v23
	v_lshlrev_b32_e32 v92, 16, v24
	v_and_b32_e32 v93, 0xffff0000, v24
	v_lshlrev_b32_e32 v94, 16, v25
	v_and_b32_e32 v95, 0xffff0000, v25
	v_lshlrev_b32_e32 v114, 16, v26
	v_and_b32_e32 v115, 0xffff0000, v26
	v_lshlrev_b32_e32 v116, 16, v27
	v_and_b32_e32 v117, 0xffff0000, v27
	v_mul_f32_e32 v114, 0xbfb8aa3b, v114
	v_mul_f32_e32 v115, 0xbfb8aa3b, v115
	v_mul_f32_e32 v116, 0xbfb8aa3b, v116
	v_mul_f32_e32 v117, 0xbfb8aa3b, v117
	v_exp_f32_e32 v114, v114
	v_exp_f32_e32 v115, v115
	v_exp_f32_e32 v116, v116
	v_exp_f32_e32 v117, v117
	s_nop 0
	v_add_f32_e32 v114, 1.0, v114
	v_add_f32_e32 v115, 1.0, v115
	v_add_f32_e32 v116, 1.0, v116
	v_add_f32_e32 v117, 1.0, v117
	v_div_scale_f32 v108, s[22:23], v114, v114, 1.0
	v_rcp_f32_e32 v109, v108
	s_nop 0
	v_fma_f32 v110, -v108, v109, 1.0
	v_fmac_f32_e32 v109, v110, v109
	v_div_scale_f32 v110, vcc, 1.0, v114, 1.0
	v_mul_f32_e32 v111, v110, v109
	v_fma_f32 v112, -v108, v111, v110
	v_fmac_f32_e32 v111, v112, v109
	v_fma_f32 v108, -v108, v111, v110
	v_div_fmas_f32 v108, v108, v109, v111
	v_div_fixup_f32 v114, v108, v114, 1.0
	v_mul_f32_e32 v92, v114, v92
	v_div_scale_f32 v108, s[22:23], v115, v115, 1.0
	v_rcp_f32_e32 v109, v108
	s_nop 0
	v_fma_f32 v110, -v108, v109, 1.0
	v_fmac_f32_e32 v109, v110, v109
	v_div_scale_f32 v110, vcc, 1.0, v115, 1.0
	v_mul_f32_e32 v111, v110, v109
	v_fma_f32 v112, -v108, v111, v110
	v_fmac_f32_e32 v111, v112, v109
	v_fma_f32 v108, -v108, v111, v110
	v_div_fmas_f32 v108, v108, v109, v111
	v_div_fixup_f32 v115, v108, v115, 1.0
	v_mul_f32_e32 v93, v115, v93
	v_div_scale_f32 v108, s[22:23], v116, v116, 1.0
	v_rcp_f32_e32 v109, v108
	s_nop 0
	v_fma_f32 v110, -v108, v109, 1.0
	v_fmac_f32_e32 v109, v110, v109
	v_div_scale_f32 v110, vcc, 1.0, v116, 1.0
	v_mul_f32_e32 v111, v110, v109
	v_fma_f32 v112, -v108, v111, v110
	v_fmac_f32_e32 v111, v112, v109
	v_fma_f32 v108, -v108, v111, v110
	v_div_fmas_f32 v108, v108, v109, v111
	v_div_fixup_f32 v116, v108, v116, 1.0
	v_mul_f32_e32 v94, v116, v94
	v_div_scale_f32 v108, s[22:23], v117, v117, 1.0
	v_rcp_f32_e32 v109, v108
	s_nop 0
	v_fma_f32 v110, -v108, v109, 1.0
	v_fmac_f32_e32 v109, v110, v109
	v_div_scale_f32 v110, vcc, 1.0, v117, 1.0
	v_mul_f32_e32 v111, v110, v109
	v_fma_f32 v112, -v108, v111, v110
	v_fmac_f32_e32 v111, v112, v109
	v_fma_f32 v108, -v108, v111, v110
	v_div_fmas_f32 v108, v108, v109, v111
	v_div_fixup_f32 v117, v108, v117, 1.0
	v_mul_f32_e32 v95, v117, v95
	v_pk_mul_f32 v[108:109], v[80:81], v[80:81]
	v_pk_fma_f32 v[108:109], v[82:83], v[82:83], v[108:109]
	v_add_f32_e32 v96, v108, v109
	v_pk_mul_f32 v[110:111], v[84:85], v[84:85]
	v_pk_fma_f32 v[110:111], v[86:87], v[86:87], v[110:111]
	v_add_f32_e32 v97, v110, v111
	v_pk_mul_f32 v[108:109], v[88:89], v[88:89]
	v_pk_fma_f32 v[108:109], v[90:91], v[90:91], v[108:109]
	v_add_f32_e32 v98, v108, v109
	v_pk_mul_f32 v[110:111], v[92:93], v[92:93]
	v_pk_fma_f32 v[110:111], v[94:95], v[94:95], v[110:111]
	v_add_f32_e32 v99, v110, v111
	v_add_f32_dpp v96, v96, v96 row_ror:8 row_mask:0xf bank_mask:0xf
	s_nop 0
	v_add_f32_dpp v97, v97, v97 row_ror:8 row_mask:0xf bank_mask:0xf
	s_nop 0
	v_add_f32_dpp v96, v96, v96 row_ror:4 row_mask:0xf bank_mask:0xf
	s_nop 0
	v_add_f32_dpp v97, v97, v97 row_ror:4 row_mask:0xf bank_mask:0xf
	s_nop 0
	v_add_f32_dpp v96, v96, v96 row_ror:2 row_mask:0xf bank_mask:0xf
	s_nop 0
	v_add_f32_dpp v97, v97, v97 row_ror:2 row_mask:0xf bank_mask:0xf
	s_nop 0
	v_add_f32_dpp v96, v96, v96 row_ror:1 row_mask:0xf bank_mask:0xf
	s_nop 0
	v_add_f32_dpp v97, v97, v97 row_ror:1 row_mask:0xf bank_mask:0xf
	s_nop 0
	v_readlane_b32 s0, v96, 0
	v_readlane_b32 s1, v96, 16
	v_readlane_b32 s18, v96, 32
	v_readlane_b32 s19, v96, 48
	v_readlane_b32 s20, v97, 0
	v_readlane_b32 s21, v97, 16
	v_readlane_b32 s22, v97, 32
	v_readlane_b32 s23, v97, 48
	s_nop 1
	v_mov_b32_e32 v100, s0
	v_mov_b32_e32 v102, s20
	v_add_f32_e32 v100, s1, v100
	v_add_f32_e32 v102, s21, v102
	v_add_f32_e32 v100, s18, v100
	v_add_f32_e32 v102, s22, v102
	v_add_f32_e32 v100, s19, v100
	v_add_f32_e32 v102, s23, v102
	v_add_f32_dpp v98, v98, v98 row_ror:8 row_mask:0xf bank_mask:0xf
	s_nop 0
	v_add_f32_dpp v99, v99, v99 row_ror:8 row_mask:0xf bank_mask:0xf
	s_nop 0
	v_add_f32_dpp v98, v98, v98 row_ror:4 row_mask:0xf bank_mask:0xf
	s_nop 0
	v_add_f32_dpp v99, v99, v99 row_ror:4 row_mask:0xf bank_mask:0xf
	s_nop 0
	v_add_f32_dpp v98, v98, v98 row_ror:2 row_mask:0xf bank_mask:0xf
	s_nop 0
	v_add_f32_dpp v99, v99, v99 row_ror:2 row_mask:0xf bank_mask:0xf
	s_nop 0
	v_add_f32_dpp v98, v98, v98 row_ror:1 row_mask:0xf bank_mask:0xf
	s_nop 0
	v_add_f32_dpp v99, v99, v99 row_ror:1 row_mask:0xf bank_mask:0xf
	s_nop 0
	v_readlane_b32 s0, v98, 0
	v_readlane_b32 s1, v98, 16
	v_readlane_b32 s18, v98, 32
	v_readlane_b32 s19, v98, 48
	v_readlane_b32 s20, v99, 0
	v_readlane_b32 s21, v99, 16
	v_readlane_b32 s22, v99, 32
	v_readlane_b32 s23, v99, 48
	s_nop 1
	v_mov_b32_e32 v104, s0
	v_mov_b32_e32 v106, s20
	v_add_f32_e32 v104, s1, v104
	v_add_f32_e32 v106, s21, v106
	v_add_f32_e32 v104, s18, v104
	v_add_f32_e32 v106, s22, v106
	v_add_f32_e32 v104, s19, v104
	v_add_f32_e32 v106, s23, v106
	v_fmamk_f32 v100, v100, 0x3b800000, v197
	v_fmamk_f32 v102, v102, 0x3b800000, v197
	v_fmamk_f32 v104, v104, 0x3b800000, v197
	v_fmamk_f32 v106, v106, 0x3b800000, v197
	v_rsq_f32_e32 v100, v100
	v_rsq_f32_e32 v102, v102
	v_rsq_f32_e32 v104, v104
	v_rsq_f32_e32 v106, v106
	s_nop 0
	v_pk_mul_f32 v[80:81], v[100:101], v[80:81] op_sel_hi:[0,1]
	v_pk_mul_f32 v[82:83], v[100:101], v[82:83] op_sel_hi:[0,1]
	v_pk_mul_f32 v[84:85], v[102:103], v[84:85] op_sel_hi:[0,1]
	v_pk_mul_f32 v[86:87], v[102:103], v[86:87] op_sel_hi:[0,1]
	v_pk_mul_f32 v[88:89], v[104:105], v[88:89] op_sel_hi:[0,1]
	v_pk_mul_f32 v[90:91], v[104:105], v[90:91] op_sel_hi:[0,1]
	v_pk_mul_f32 v[92:93], v[106:107], v[92:93] op_sel_hi:[0,1]
	v_pk_mul_f32 v[94:95], v[106:107], v[94:95] op_sel_hi:[0,1]
	v_pk_mul_f32 v[80:81], v[2:3], v[80:81]
	v_pk_mul_f32 v[82:83], v[4:5], v[82:83]
	v_pk_mul_f32 v[84:85], v[6:7], v[84:85]
	v_pk_mul_f32 v[86:87], v[8:9], v[86:87]
	v_pk_mul_f32 v[88:89], v[10:11], v[88:89]
	v_pk_mul_f32 v[90:91], v[12:13], v[90:91]
	v_pk_mul_f32 v[92:93], v[14:15], v[92:93]
	v_pk_mul_f32 v[94:95], v[16:17], v[94:95]
	v_cvt_pk_bf16_f32 v18, v80, v81
	v_cvt_pk_bf16_f32 v19, v82, v83
	v_cvt_pk_bf16_f32 v20, v84, v85
	v_cvt_pk_bf16_f32 v21, v86, v87
	v_cvt_pk_bf16_f32 v22, v88, v89
	v_cvt_pk_bf16_f32 v23, v90, v91
	v_cvt_pk_bf16_f32 v24, v92, v93
	v_cvt_pk_bf16_f32 v25, v94, v95
	global_store_dwordx2 v1, v[18:19], s[16:17] offset:0
	global_store_dwordx2 v1, v[20:21], s[16:17] offset:512
	global_store_dwordx2 v1, v[22:23], s[16:17] offset:1024
	global_store_dwordx2 v1, v[24:25], s[16:17] offset:1536
	global_load_dwordx2 v[18:19], v1, s[6:7] offset:0
	global_load_dwordx2 v[20:21], v1, s[6:7] offset:512
	global_load_dwordx2 v[22:23], v1, s[6:7] offset:1024
	global_load_dwordx2 v[24:25], v1, s[8:9]
	global_load_dwordx2 v[26:27], v1, s[8:9] offset:512
	s_add_u32 s6, s6, 0x600
	s_addc_u32 s7, s7, 0
	s_add_u32 s8, s8, 0x400
	s_addc_u32 s9, s9, 0
	s_waitcnt vmcnt(29)
	v_lshlrev_b32_e32 v80, 16, v28
	v_and_b32_e32 v81, 0xffff0000, v28
	v_lshlrev_b32_e32 v82, 16, v29
	v_and_b32_e32 v83, 0xffff0000, v29
	v_lshlrev_b32_e32 v84, 16, v30
	v_and_b32_e32 v85, 0xffff0000, v30
	v_lshlrev_b32_e32 v86, 16, v31
	v_and_b32_e32 v87, 0xffff0000, v31
	v_lshlrev_b32_e32 v88, 16, v32
	v_and_b32_e32 v89, 0xffff0000, v32
	v_lshlrev_b32_e32 v90, 16, v33
	v_and_b32_e32 v91, 0xffff0000, v33
	v_lshlrev_b32_e32 v92, 16, v34
	v_and_b32_e32 v93, 0xffff0000, v34
	v_lshlrev_b32_e32 v94, 16, v35
	v_and_b32_e32 v95, 0xffff0000, v35
	v_lshlrev_b32_e32 v114, 16, v36
	v_and_b32_e32 v115, 0xffff0000, v36
	v_lshlrev_b32_e32 v116, 16, v37
	v_and_b32_e32 v117, 0xffff0000, v37
	v_mul_f32_e32 v114, 0xbfb8aa3b, v114
	v_mul_f32_e32 v115, 0xbfb8aa3b, v115
	v_mul_f32_e32 v116, 0xbfb8aa3b, v116
	v_mul_f32_e32 v117, 0xbfb8aa3b, v117
	v_exp_f32_e32 v114, v114
	v_exp_f32_e32 v115, v115
	v_exp_f32_e32 v116, v116
	v_exp_f32_e32 v117, v117
	s_nop 0
	v_add_f32_e32 v114, 1.0, v114
	v_add_f32_e32 v115, 1.0, v115
	v_add_f32_e32 v116, 1.0, v116
	v_add_f32_e32 v117, 1.0, v117
	v_div_scale_f32 v108, s[22:23], v114, v114, 1.0
	v_rcp_f32_e32 v109, v108
	s_nop 0
	v_fma_f32 v110, -v108, v109, 1.0
	v_fmac_f32_e32 v109, v110, v109
	v_div_scale_f32 v110, vcc, 1.0, v114, 1.0
	v_mul_f32_e32 v111, v110, v109
	v_fma_f32 v112, -v108, v111, v110
	v_fmac_f32_e32 v111, v112, v109
	v_fma_f32 v108, -v108, v111, v110
	v_div_fmas_f32 v108, v108, v109, v111
	v_div_fixup_f32 v114, v108, v114, 1.0
	v_mul_f32_e32 v92, v114, v92
	v_div_scale_f32 v108, s[22:23], v115, v115, 1.0
	v_rcp_f32_e32 v109, v108
	s_nop 0
	v_fma_f32 v110, -v108, v109, 1.0
	v_fmac_f32_e32 v109, v110, v109
	v_div_scale_f32 v110, vcc, 1.0, v115, 1.0
	v_mul_f32_e32 v111, v110, v109
	v_fma_f32 v112, -v108, v111, v110
	v_fmac_f32_e32 v111, v112, v109
	v_fma_f32 v108, -v108, v111, v110
	v_div_fmas_f32 v108, v108, v109, v111
	v_div_fixup_f32 v115, v108, v115, 1.0
	v_mul_f32_e32 v93, v115, v93
	v_div_scale_f32 v108, s[22:23], v116, v116, 1.0
	v_rcp_f32_e32 v109, v108
	s_nop 0
	v_fma_f32 v110, -v108, v109, 1.0
	v_fmac_f32_e32 v109, v110, v109
	v_div_scale_f32 v110, vcc, 1.0, v116, 1.0
	v_mul_f32_e32 v111, v110, v109
	v_fma_f32 v112, -v108, v111, v110
	v_fmac_f32_e32 v111, v112, v109
	v_fma_f32 v108, -v108, v111, v110
	v_div_fmas_f32 v108, v108, v109, v111
	v_div_fixup_f32 v116, v108, v116, 1.0
	v_mul_f32_e32 v94, v116, v94
	v_div_scale_f32 v108, s[22:23], v117, v117, 1.0
	v_rcp_f32_e32 v109, v108
	s_nop 0
	v_fma_f32 v110, -v108, v109, 1.0
	v_fmac_f32_e32 v109, v110, v109
	v_div_scale_f32 v110, vcc, 1.0, v117, 1.0
	v_mul_f32_e32 v111, v110, v109
	v_fma_f32 v112, -v108, v111, v110
	v_fmac_f32_e32 v111, v112, v109
	v_fma_f32 v108, -v108, v111, v110
	v_div_fmas_f32 v108, v108, v109, v111
	v_div_fixup_f32 v117, v108, v117, 1.0
	v_mul_f32_e32 v95, v117, v95
	v_pk_mul_f32 v[108:109], v[80:81], v[80:81]
	v_pk_fma_f32 v[108:109], v[82:83], v[82:83], v[108:109]
	v_add_f32_e32 v96, v108, v109
	v_pk_mul_f32 v[110:111], v[84:85], v[84:85]
	v_pk_fma_f32 v[110:111], v[86:87], v[86:87], v[110:111]
	v_add_f32_e32 v97, v110, v111
	v_pk_mul_f32 v[108:109], v[88:89], v[88:89]
	v_pk_fma_f32 v[108:109], v[90:91], v[90:91], v[108:109]
	v_add_f32_e32 v98, v108, v109
	v_pk_mul_f32 v[110:111], v[92:93], v[92:93]
	v_pk_fma_f32 v[110:111], v[94:95], v[94:95], v[110:111]
	v_add_f32_e32 v99, v110, v111
	v_add_f32_dpp v96, v96, v96 row_ror:8 row_mask:0xf bank_mask:0xf
	s_nop 0
	v_add_f32_dpp v97, v97, v97 row_ror:8 row_mask:0xf bank_mask:0xf
	s_nop 0
	v_add_f32_dpp v96, v96, v96 row_ror:4 row_mask:0xf bank_mask:0xf
	s_nop 0
	v_add_f32_dpp v97, v97, v97 row_ror:4 row_mask:0xf bank_mask:0xf
	s_nop 0
	v_add_f32_dpp v96, v96, v96 row_ror:2 row_mask:0xf bank_mask:0xf
	s_nop 0
	v_add_f32_dpp v97, v97, v97 row_ror:2 row_mask:0xf bank_mask:0xf
	s_nop 0
	v_add_f32_dpp v96, v96, v96 row_ror:1 row_mask:0xf bank_mask:0xf
	s_nop 0
	v_add_f32_dpp v97, v97, v97 row_ror:1 row_mask:0xf bank_mask:0xf
	s_nop 0
	v_readlane_b32 s0, v96, 0
	v_readlane_b32 s1, v96, 16
	v_readlane_b32 s18, v96, 32
	v_readlane_b32 s19, v96, 48
	v_readlane_b32 s20, v97, 0
	v_readlane_b32 s21, v97, 16
	v_readlane_b32 s22, v97, 32
	v_readlane_b32 s23, v97, 48
	s_nop 1
	v_mov_b32_e32 v100, s0
	v_mov_b32_e32 v102, s20
	v_add_f32_e32 v100, s1, v100
	v_add_f32_e32 v102, s21, v102
	v_add_f32_e32 v100, s18, v100
	v_add_f32_e32 v102, s22, v102
	v_add_f32_e32 v100, s19, v100
	v_add_f32_e32 v102, s23, v102
	v_add_f32_dpp v98, v98, v98 row_ror:8 row_mask:0xf bank_mask:0xf
	s_nop 0
	v_add_f32_dpp v99, v99, v99 row_ror:8 row_mask:0xf bank_mask:0xf
	s_nop 0
	v_add_f32_dpp v98, v98, v98 row_ror:4 row_mask:0xf bank_mask:0xf
	s_nop 0
	v_add_f32_dpp v99, v99, v99 row_ror:4 row_mask:0xf bank_mask:0xf
	s_nop 0
	v_add_f32_dpp v98, v98, v98 row_ror:2 row_mask:0xf bank_mask:0xf
	s_nop 0
	v_add_f32_dpp v99, v99, v99 row_ror:2 row_mask:0xf bank_mask:0xf
	s_nop 0
	v_add_f32_dpp v98, v98, v98 row_ror:1 row_mask:0xf bank_mask:0xf
	s_nop 0
	v_add_f32_dpp v99, v99, v99 row_ror:1 row_mask:0xf bank_mask:0xf
	s_nop 0
	v_readlane_b32 s0, v98, 0
	v_readlane_b32 s1, v98, 16
	v_readlane_b32 s18, v98, 32
	v_readlane_b32 s19, v98, 48
	v_readlane_b32 s20, v99, 0
	v_readlane_b32 s21, v99, 16
	v_readlane_b32 s22, v99, 32
	v_readlane_b32 s23, v99, 48
	s_nop 1
	v_mov_b32_e32 v104, s0
	v_mov_b32_e32 v106, s20
	v_add_f32_e32 v104, s1, v104
	v_add_f32_e32 v106, s21, v106
	v_add_f32_e32 v104, s18, v104
	v_add_f32_e32 v106, s22, v106
	v_add_f32_e32 v104, s19, v104
	v_add_f32_e32 v106, s23, v106
	v_fmamk_f32 v100, v100, 0x3b800000, v197
	v_fmamk_f32 v102, v102, 0x3b800000, v197
	v_fmamk_f32 v104, v104, 0x3b800000, v197
	v_fmamk_f32 v106, v106, 0x3b800000, v197
	v_rsq_f32_e32 v100, v100
	v_rsq_f32_e32 v102, v102
	v_rsq_f32_e32 v104, v104
	v_rsq_f32_e32 v106, v106
	s_nop 0
	v_pk_mul_f32 v[80:81], v[100:101], v[80:81] op_sel_hi:[0,1]
	v_pk_mul_f32 v[82:83], v[100:101], v[82:83] op_sel_hi:[0,1]
	v_pk_mul_f32 v[84:85], v[102:103], v[84:85] op_sel_hi:[0,1]
	v_pk_mul_f32 v[86:87], v[102:103], v[86:87] op_sel_hi:[0,1]
	v_pk_mul_f32 v[88:89], v[104:105], v[88:89] op_sel_hi:[0,1]
	v_pk_mul_f32 v[90:91], v[104:105], v[90:91] op_sel_hi:[0,1]
	v_pk_mul_f32 v[92:93], v[106:107], v[92:93] op_sel_hi:[0,1]
	v_pk_mul_f32 v[94:95], v[106:107], v[94:95] op_sel_hi:[0,1]
	v_pk_mul_f32 v[80:81], v[2:3], v[80:81]
	v_pk_mul_f32 v[82:83], v[4:5], v[82:83]
	v_pk_mul_f32 v[84:85], v[6:7], v[84:85]
	v_pk_mul_f32 v[86:87], v[8:9], v[86:87]
	v_pk_mul_f32 v[88:89], v[10:11], v[88:89]
	v_pk_mul_f32 v[90:91], v[12:13], v[90:91]
	v_pk_mul_f32 v[92:93], v[14:15], v[92:93]
	v_pk_mul_f32 v[94:95], v[16:17], v[94:95]
	v_cvt_pk_bf16_f32 v28, v80, v81
	v_cvt_pk_bf16_f32 v29, v82, v83
	v_cvt_pk_bf16_f32 v30, v84, v85
	v_cvt_pk_bf16_f32 v31, v86, v87
	v_cvt_pk_bf16_f32 v32, v88, v89
	v_cvt_pk_bf16_f32 v33, v90, v91
	v_cvt_pk_bf16_f32 v34, v92, v93
	v_cvt_pk_bf16_f32 v35, v94, v95
	global_store_dwordx2 v1, v[28:29], s[10:11] offset:0
	global_store_dwordx2 v1, v[30:31], s[10:11] offset:512
	global_store_dwordx2 v1, v[32:33], s[10:11] offset:1024
	global_store_dwordx2 v1, v[34:35], s[10:11] offset:1536
	s_add_u32 s10, s10, 0x800
	s_addc_u32 s11, s11, 0
	global_load_dwordx2 v[28:29], v1, s[6:7] offset:0
	global_load_dwordx2 v[30:31], v1, s[6:7] offset:512
	global_load_dwordx2 v[32:33], v1, s[6:7] offset:1024
	global_load_dwordx2 v[34:35], v1, s[8:9]
	global_load_dwordx2 v[36:37], v1, s[8:9] offset:512
	s_add_u32 s6, s6, 0x600
	s_addc_u32 s7, s7, 0
	s_add_u32 s8, s8, 0x400
	s_addc_u32 s9, s9, 0
	s_waitcnt vmcnt(33)
	v_lshlrev_b32_e32 v80, 16, v38
	v_and_b32_e32 v81, 0xffff0000, v38
	v_lshlrev_b32_e32 v82, 16, v39
	v_and_b32_e32 v83, 0xffff0000, v39
	v_lshlrev_b32_e32 v84, 16, v40
	v_and_b32_e32 v85, 0xffff0000, v40
	v_lshlrev_b32_e32 v86, 16, v41
	v_and_b32_e32 v87, 0xffff0000, v41
	v_lshlrev_b32_e32 v88, 16, v42
	v_and_b32_e32 v89, 0xffff0000, v42
	v_lshlrev_b32_e32 v90, 16, v43
	v_and_b32_e32 v91, 0xffff0000, v43
	v_lshlrev_b32_e32 v92, 16, v44
	v_and_b32_e32 v93, 0xffff0000, v44
	v_lshlrev_b32_e32 v94, 16, v45
	v_and_b32_e32 v95, 0xffff0000, v45
	v_lshlrev_b32_e32 v114, 16, v46
	v_and_b32_e32 v115, 0xffff0000, v46
	v_lshlrev_b32_e32 v116, 16, v47
	v_and_b32_e32 v117, 0xffff0000, v47
	v_mul_f32_e32 v114, 0xbfb8aa3b, v114
	v_mul_f32_e32 v115, 0xbfb8aa3b, v115
	v_mul_f32_e32 v116, 0xbfb8aa3b, v116
	v_mul_f32_e32 v117, 0xbfb8aa3b, v117
	v_exp_f32_e32 v114, v114
	v_exp_f32_e32 v115, v115
	v_exp_f32_e32 v116, v116
	v_exp_f32_e32 v117, v117
	s_nop 0
	v_add_f32_e32 v114, 1.0, v114
	v_add_f32_e32 v115, 1.0, v115
	v_add_f32_e32 v116, 1.0, v116
	v_add_f32_e32 v117, 1.0, v117
	v_div_scale_f32 v108, s[22:23], v114, v114, 1.0
	v_rcp_f32_e32 v109, v108
	s_nop 0
	v_fma_f32 v110, -v108, v109, 1.0
	v_fmac_f32_e32 v109, v110, v109
	v_div_scale_f32 v110, vcc, 1.0, v114, 1.0
	v_mul_f32_e32 v111, v110, v109
	v_fma_f32 v112, -v108, v111, v110
	v_fmac_f32_e32 v111, v112, v109
	v_fma_f32 v108, -v108, v111, v110
	v_div_fmas_f32 v108, v108, v109, v111
	v_div_fixup_f32 v114, v108, v114, 1.0
	v_mul_f32_e32 v92, v114, v92
	v_div_scale_f32 v108, s[22:23], v115, v115, 1.0
	v_rcp_f32_e32 v109, v108
	s_nop 0
	v_fma_f32 v110, -v108, v109, 1.0
	v_fmac_f32_e32 v109, v110, v109
	v_div_scale_f32 v110, vcc, 1.0, v115, 1.0
	v_mul_f32_e32 v111, v110, v109
	v_fma_f32 v112, -v108, v111, v110
	v_fmac_f32_e32 v111, v112, v109
	v_fma_f32 v108, -v108, v111, v110
	v_div_fmas_f32 v108, v108, v109, v111
	v_div_fixup_f32 v115, v108, v115, 1.0
	v_mul_f32_e32 v93, v115, v93
	v_div_scale_f32 v108, s[22:23], v116, v116, 1.0
	v_rcp_f32_e32 v109, v108
	s_nop 0
	v_fma_f32 v110, -v108, v109, 1.0
	v_fmac_f32_e32 v109, v110, v109
	v_div_scale_f32 v110, vcc, 1.0, v116, 1.0
	v_mul_f32_e32 v111, v110, v109
	v_fma_f32 v112, -v108, v111, v110
	v_fmac_f32_e32 v111, v112, v109
	v_fma_f32 v108, -v108, v111, v110
	v_div_fmas_f32 v108, v108, v109, v111
	v_div_fixup_f32 v116, v108, v116, 1.0
	v_mul_f32_e32 v94, v116, v94
	v_div_scale_f32 v108, s[22:23], v117, v117, 1.0
	v_rcp_f32_e32 v109, v108
	s_nop 0
	v_fma_f32 v110, -v108, v109, 1.0
	v_fmac_f32_e32 v109, v110, v109
	v_div_scale_f32 v110, vcc, 1.0, v117, 1.0
	v_mul_f32_e32 v111, v110, v109
	v_fma_f32 v112, -v108, v111, v110
	v_fmac_f32_e32 v111, v112, v109
	v_fma_f32 v108, -v108, v111, v110
	v_div_fmas_f32 v108, v108, v109, v111
	v_div_fixup_f32 v117, v108, v117, 1.0
	v_mul_f32_e32 v95, v117, v95
	v_pk_mul_f32 v[108:109], v[80:81], v[80:81]
	v_pk_fma_f32 v[108:109], v[82:83], v[82:83], v[108:109]
	v_add_f32_e32 v96, v108, v109
	v_pk_mul_f32 v[110:111], v[84:85], v[84:85]
	v_pk_fma_f32 v[110:111], v[86:87], v[86:87], v[110:111]
	v_add_f32_e32 v97, v110, v111
	v_pk_mul_f32 v[108:109], v[88:89], v[88:89]
	v_pk_fma_f32 v[108:109], v[90:91], v[90:91], v[108:109]
	v_add_f32_e32 v98, v108, v109
	v_pk_mul_f32 v[110:111], v[92:93], v[92:93]
	v_pk_fma_f32 v[110:111], v[94:95], v[94:95], v[110:111]
	v_add_f32_e32 v99, v110, v111
	v_add_f32_dpp v96, v96, v96 row_ror:8 row_mask:0xf bank_mask:0xf
	s_nop 0
	v_add_f32_dpp v97, v97, v97 row_ror:8 row_mask:0xf bank_mask:0xf
	s_nop 0
	v_add_f32_dpp v96, v96, v96 row_ror:4 row_mask:0xf bank_mask:0xf
	s_nop 0
	v_add_f32_dpp v97, v97, v97 row_ror:4 row_mask:0xf bank_mask:0xf
	s_nop 0
	v_add_f32_dpp v96, v96, v96 row_ror:2 row_mask:0xf bank_mask:0xf
	s_nop 0
	v_add_f32_dpp v97, v97, v97 row_ror:2 row_mask:0xf bank_mask:0xf
	s_nop 0
	v_add_f32_dpp v96, v96, v96 row_ror:1 row_mask:0xf bank_mask:0xf
	s_nop 0
	v_add_f32_dpp v97, v97, v97 row_ror:1 row_mask:0xf bank_mask:0xf
	s_nop 0
	v_readlane_b32 s0, v96, 0
	v_readlane_b32 s1, v96, 16
	v_readlane_b32 s18, v96, 32
	v_readlane_b32 s19, v96, 48
	v_readlane_b32 s20, v97, 0
	v_readlane_b32 s21, v97, 16
	v_readlane_b32 s22, v97, 32
	v_readlane_b32 s23, v97, 48
	s_nop 1
	v_mov_b32_e32 v100, s0
	v_mov_b32_e32 v102, s20
	v_add_f32_e32 v100, s1, v100
	v_add_f32_e32 v102, s21, v102
	v_add_f32_e32 v100, s18, v100
	v_add_f32_e32 v102, s22, v102
	v_add_f32_e32 v100, s19, v100
	v_add_f32_e32 v102, s23, v102
	v_add_f32_dpp v98, v98, v98 row_ror:8 row_mask:0xf bank_mask:0xf
	s_nop 0
	v_add_f32_dpp v99, v99, v99 row_ror:8 row_mask:0xf bank_mask:0xf
	s_nop 0
	v_add_f32_dpp v98, v98, v98 row_ror:4 row_mask:0xf bank_mask:0xf
	s_nop 0
	v_add_f32_dpp v99, v99, v99 row_ror:4 row_mask:0xf bank_mask:0xf
	s_nop 0
	v_add_f32_dpp v98, v98, v98 row_ror:2 row_mask:0xf bank_mask:0xf
	s_nop 0
	v_add_f32_dpp v99, v99, v99 row_ror:2 row_mask:0xf bank_mask:0xf
	s_nop 0
	v_add_f32_dpp v98, v98, v98 row_ror:1 row_mask:0xf bank_mask:0xf
	s_nop 0
	v_add_f32_dpp v99, v99, v99 row_ror:1 row_mask:0xf bank_mask:0xf
	s_nop 0
	v_readlane_b32 s0, v98, 0
	v_readlane_b32 s1, v98, 16
	v_readlane_b32 s18, v98, 32
	v_readlane_b32 s19, v98, 48
	v_readlane_b32 s20, v99, 0
	v_readlane_b32 s21, v99, 16
	v_readlane_b32 s22, v99, 32
	v_readlane_b32 s23, v99, 48
	s_nop 1
	v_mov_b32_e32 v104, s0
	v_mov_b32_e32 v106, s20
	v_add_f32_e32 v104, s1, v104
	v_add_f32_e32 v106, s21, v106
	v_add_f32_e32 v104, s18, v104
	v_add_f32_e32 v106, s22, v106
	v_add_f32_e32 v104, s19, v104
	v_add_f32_e32 v106, s23, v106
	v_fmamk_f32 v100, v100, 0x3b800000, v197
	v_fmamk_f32 v102, v102, 0x3b800000, v197
	v_fmamk_f32 v104, v104, 0x3b800000, v197
	v_fmamk_f32 v106, v106, 0x3b800000, v197
	v_rsq_f32_e32 v100, v100
	v_rsq_f32_e32 v102, v102
	v_rsq_f32_e32 v104, v104
	v_rsq_f32_e32 v106, v106
	s_nop 0
	v_pk_mul_f32 v[80:81], v[100:101], v[80:81] op_sel_hi:[0,1]
	v_pk_mul_f32 v[82:83], v[100:101], v[82:83] op_sel_hi:[0,1]
	v_pk_mul_f32 v[84:85], v[102:103], v[84:85] op_sel_hi:[0,1]
	v_pk_mul_f32 v[86:87], v[102:103], v[86:87] op_sel_hi:[0,1]
	v_pk_mul_f32 v[88:89], v[104:105], v[88:89] op_sel_hi:[0,1]
	v_pk_mul_f32 v[90:91], v[104:105], v[90:91] op_sel_hi:[0,1]
	v_pk_mul_f32 v[92:93], v[106:107], v[92:93] op_sel_hi:[0,1]
	v_pk_mul_f32 v[94:95], v[106:107], v[94:95] op_sel_hi:[0,1]
	v_pk_mul_f32 v[80:81], v[2:3], v[80:81]
	v_pk_mul_f32 v[82:83], v[4:5], v[82:83]
	v_pk_mul_f32 v[84:85], v[6:7], v[84:85]
	v_pk_mul_f32 v[86:87], v[8:9], v[86:87]
	v_pk_mul_f32 v[88:89], v[10:11], v[88:89]
	v_pk_mul_f32 v[90:91], v[12:13], v[90:91]
	v_pk_mul_f32 v[92:93], v[14:15], v[92:93]
	v_pk_mul_f32 v[94:95], v[16:17], v[94:95]
	v_cvt_pk_bf16_f32 v38, v80, v81
	v_cvt_pk_bf16_f32 v39, v82, v83
	v_cvt_pk_bf16_f32 v40, v84, v85
	v_cvt_pk_bf16_f32 v41, v86, v87
	v_cvt_pk_bf16_f32 v42, v88, v89
	v_cvt_pk_bf16_f32 v43, v90, v91
	v_cvt_pk_bf16_f32 v44, v92, v93
	v_cvt_pk_bf16_f32 v45, v94, v95
	global_store_dwordx2 v1, v[38:39], s[10:11] offset:0
	global_store_dwordx2 v1, v[40:41], s[10:11] offset:512
	global_store_dwordx2 v1, v[42:43], s[10:11] offset:1024
	global_store_dwordx2 v1, v[44:45], s[10:11] offset:1536
	s_add_u32 s10, s10, 0x800
	s_addc_u32 s11, s11, 0
	global_load_dwordx2 v[38:39], v1, s[6:7] offset:0
	global_load_dwordx2 v[40:41], v1, s[6:7] offset:512
	global_load_dwordx2 v[42:43], v1, s[6:7] offset:1024
	global_load_dwordx2 v[44:45], v1, s[8:9]
	global_load_dwordx2 v[46:47], v1, s[8:9] offset:512
	s_waitcnt vmcnt(37)
	v_lshlrev_b32_e32 v80, 16, v48
	v_and_b32_e32 v81, 0xffff0000, v48
	v_lshlrev_b32_e32 v82, 16, v49
	v_and_b32_e32 v83, 0xffff0000, v49
	v_lshlrev_b32_e32 v84, 16, v50
	v_and_b32_e32 v85, 0xffff0000, v50
	v_lshlrev_b32_e32 v86, 16, v51
	v_and_b32_e32 v87, 0xffff0000, v51
	v_lshlrev_b32_e32 v88, 16, v52
	v_and_b32_e32 v89, 0xffff0000, v52
	v_lshlrev_b32_e32 v90, 16, v53
	v_and_b32_e32 v91, 0xffff0000, v53
	v_lshlrev_b32_e32 v92, 16, v54
	v_and_b32_e32 v93, 0xffff0000, v54
	v_lshlrev_b32_e32 v94, 16, v55
	v_and_b32_e32 v95, 0xffff0000, v55
	v_lshlrev_b32_e32 v114, 16, v56
	v_and_b32_e32 v115, 0xffff0000, v56
	v_lshlrev_b32_e32 v116, 16, v57
	v_and_b32_e32 v117, 0xffff0000, v57
	v_mul_f32_e32 v114, 0xbfb8aa3b, v114
	v_mul_f32_e32 v115, 0xbfb8aa3b, v115
	v_mul_f32_e32 v116, 0xbfb8aa3b, v116
	v_mul_f32_e32 v117, 0xbfb8aa3b, v117
	v_exp_f32_e32 v114, v114
	v_exp_f32_e32 v115, v115
	v_exp_f32_e32 v116, v116
	v_exp_f32_e32 v117, v117
	s_nop 0
	v_add_f32_e32 v114, 1.0, v114
	v_add_f32_e32 v115, 1.0, v115
	v_add_f32_e32 v116, 1.0, v116
	v_add_f32_e32 v117, 1.0, v117
	v_div_scale_f32 v108, s[22:23], v114, v114, 1.0
	v_rcp_f32_e32 v109, v108
	s_nop 0
	v_fma_f32 v110, -v108, v109, 1.0
	v_fmac_f32_e32 v109, v110, v109
	v_div_scale_f32 v110, vcc, 1.0, v114, 1.0
	v_mul_f32_e32 v111, v110, v109
	v_fma_f32 v112, -v108, v111, v110
	v_fmac_f32_e32 v111, v112, v109
	v_fma_f32 v108, -v108, v111, v110
	v_div_fmas_f32 v108, v108, v109, v111
	v_div_fixup_f32 v114, v108, v114, 1.0
	v_mul_f32_e32 v92, v114, v92
	v_div_scale_f32 v108, s[22:23], v115, v115, 1.0
	v_rcp_f32_e32 v109, v108
	s_nop 0
	v_fma_f32 v110, -v108, v109, 1.0
	v_fmac_f32_e32 v109, v110, v109
	v_div_scale_f32 v110, vcc, 1.0, v115, 1.0
	v_mul_f32_e32 v111, v110, v109
	v_fma_f32 v112, -v108, v111, v110
	v_fmac_f32_e32 v111, v112, v109
	v_fma_f32 v108, -v108, v111, v110
	v_div_fmas_f32 v108, v108, v109, v111
	v_div_fixup_f32 v115, v108, v115, 1.0
	v_mul_f32_e32 v93, v115, v93
	v_div_scale_f32 v108, s[22:23], v116, v116, 1.0
	v_rcp_f32_e32 v109, v108
	s_nop 0
	v_fma_f32 v110, -v108, v109, 1.0
	v_fmac_f32_e32 v109, v110, v109
	v_div_scale_f32 v110, vcc, 1.0, v116, 1.0
	v_mul_f32_e32 v111, v110, v109
	v_fma_f32 v112, -v108, v111, v110
	v_fmac_f32_e32 v111, v112, v109
	v_fma_f32 v108, -v108, v111, v110
	v_div_fmas_f32 v108, v108, v109, v111
	v_div_fixup_f32 v116, v108, v116, 1.0
	v_mul_f32_e32 v94, v116, v94
	v_div_scale_f32 v108, s[22:23], v117, v117, 1.0
	v_rcp_f32_e32 v109, v108
	s_nop 0
	v_fma_f32 v110, -v108, v109, 1.0
	v_fmac_f32_e32 v109, v110, v109
	v_div_scale_f32 v110, vcc, 1.0, v117, 1.0
	v_mul_f32_e32 v111, v110, v109
	v_fma_f32 v112, -v108, v111, v110
	v_fmac_f32_e32 v111, v112, v109
	v_fma_f32 v108, -v108, v111, v110
	v_div_fmas_f32 v108, v108, v109, v111
	v_div_fixup_f32 v117, v108, v117, 1.0
	v_mul_f32_e32 v95, v117, v95
	v_pk_mul_f32 v[108:109], v[80:81], v[80:81]
	v_pk_fma_f32 v[108:109], v[82:83], v[82:83], v[108:109]
	v_add_f32_e32 v96, v108, v109
	v_pk_mul_f32 v[110:111], v[84:85], v[84:85]
	v_pk_fma_f32 v[110:111], v[86:87], v[86:87], v[110:111]
	v_add_f32_e32 v97, v110, v111
	v_pk_mul_f32 v[108:109], v[88:89], v[88:89]
	v_pk_fma_f32 v[108:109], v[90:91], v[90:91], v[108:109]
	v_add_f32_e32 v98, v108, v109
	v_pk_mul_f32 v[110:111], v[92:93], v[92:93]
	v_pk_fma_f32 v[110:111], v[94:95], v[94:95], v[110:111]
	v_add_f32_e32 v99, v110, v111
	v_add_f32_dpp v96, v96, v96 row_ror:8 row_mask:0xf bank_mask:0xf
	s_nop 0
	v_add_f32_dpp v97, v97, v97 row_ror:8 row_mask:0xf bank_mask:0xf
	s_nop 0
	v_add_f32_dpp v96, v96, v96 row_ror:4 row_mask:0xf bank_mask:0xf
	s_nop 0
	v_add_f32_dpp v97, v97, v97 row_ror:4 row_mask:0xf bank_mask:0xf
	s_nop 0
	v_add_f32_dpp v96, v96, v96 row_ror:2 row_mask:0xf bank_mask:0xf
	s_nop 0
	v_add_f32_dpp v97, v97, v97 row_ror:2 row_mask:0xf bank_mask:0xf
	s_nop 0
	v_add_f32_dpp v96, v96, v96 row_ror:1 row_mask:0xf bank_mask:0xf
	s_nop 0
	v_add_f32_dpp v97, v97, v97 row_ror:1 row_mask:0xf bank_mask:0xf
	s_nop 0
	v_readlane_b32 s0, v96, 0
	v_readlane_b32 s1, v96, 16
	v_readlane_b32 s18, v96, 32
	v_readlane_b32 s19, v96, 48
	v_readlane_b32 s20, v97, 0
	v_readlane_b32 s21, v97, 16
	v_readlane_b32 s22, v97, 32
	v_readlane_b32 s23, v97, 48
	s_nop 1
	v_mov_b32_e32 v100, s0
	v_mov_b32_e32 v102, s20
	v_add_f32_e32 v100, s1, v100
	v_add_f32_e32 v102, s21, v102
	v_add_f32_e32 v100, s18, v100
	v_add_f32_e32 v102, s22, v102
	v_add_f32_e32 v100, s19, v100
	v_add_f32_e32 v102, s23, v102
	v_add_f32_dpp v98, v98, v98 row_ror:8 row_mask:0xf bank_mask:0xf
	s_nop 0
	v_add_f32_dpp v99, v99, v99 row_ror:8 row_mask:0xf bank_mask:0xf
	s_nop 0
	v_add_f32_dpp v98, v98, v98 row_ror:4 row_mask:0xf bank_mask:0xf
	s_nop 0
	v_add_f32_dpp v99, v99, v99 row_ror:4 row_mask:0xf bank_mask:0xf
	s_nop 0
	v_add_f32_dpp v98, v98, v98 row_ror:2 row_mask:0xf bank_mask:0xf
	s_nop 0
	v_add_f32_dpp v99, v99, v99 row_ror:2 row_mask:0xf bank_mask:0xf
	s_nop 0
	v_add_f32_dpp v98, v98, v98 row_ror:1 row_mask:0xf bank_mask:0xf
	s_nop 0
	v_add_f32_dpp v99, v99, v99 row_ror:1 row_mask:0xf bank_mask:0xf
	s_nop 0
	v_readlane_b32 s0, v98, 0
	v_readlane_b32 s1, v98, 16
	v_readlane_b32 s18, v98, 32
	v_readlane_b32 s19, v98, 48
	v_readlane_b32 s20, v99, 0
	v_readlane_b32 s21, v99, 16
	v_readlane_b32 s22, v99, 32
	v_readlane_b32 s23, v99, 48
	s_nop 1
	v_mov_b32_e32 v104, s0
	v_mov_b32_e32 v106, s20
	v_add_f32_e32 v104, s1, v104
	v_add_f32_e32 v106, s21, v106
	v_add_f32_e32 v104, s18, v104
	v_add_f32_e32 v106, s22, v106
	v_add_f32_e32 v104, s19, v104
	v_add_f32_e32 v106, s23, v106
	v_fmamk_f32 v100, v100, 0x3b800000, v197
	v_fmamk_f32 v102, v102, 0x3b800000, v197
	v_fmamk_f32 v104, v104, 0x3b800000, v197
	v_fmamk_f32 v106, v106, 0x3b800000, v197
	v_rsq_f32_e32 v100, v100
	v_rsq_f32_e32 v102, v102
	v_rsq_f32_e32 v104, v104
	v_rsq_f32_e32 v106, v106
	s_nop 0
	v_pk_mul_f32 v[80:81], v[100:101], v[80:81] op_sel_hi:[0,1]
	v_pk_mul_f32 v[82:83], v[100:101], v[82:83] op_sel_hi:[0,1]
	v_pk_mul_f32 v[84:85], v[102:103], v[84:85] op_sel_hi:[0,1]
	v_pk_mul_f32 v[86:87], v[102:103], v[86:87] op_sel_hi:[0,1]
	v_pk_mul_f32 v[88:89], v[104:105], v[88:89] op_sel_hi:[0,1]
	v_pk_mul_f32 v[90:91], v[104:105], v[90:91] op_sel_hi:[0,1]
	v_pk_mul_f32 v[92:93], v[106:107], v[92:93] op_sel_hi:[0,1]
	v_pk_mul_f32 v[94:95], v[106:107], v[94:95] op_sel_hi:[0,1]
	v_pk_mul_f32 v[80:81], v[2:3], v[80:81]
	v_pk_mul_f32 v[82:83], v[4:5], v[82:83]
	v_pk_mul_f32 v[84:85], v[6:7], v[84:85]
	v_pk_mul_f32 v[86:87], v[8:9], v[86:87]
	v_pk_mul_f32 v[88:89], v[10:11], v[88:89]
	v_pk_mul_f32 v[90:91], v[12:13], v[90:91]
	v_pk_mul_f32 v[92:93], v[14:15], v[92:93]
	v_pk_mul_f32 v[94:95], v[16:17], v[94:95]
	v_cvt_pk_bf16_f32 v48, v80, v81
	v_cvt_pk_bf16_f32 v49, v82, v83
	v_cvt_pk_bf16_f32 v50, v84, v85
	v_cvt_pk_bf16_f32 v51, v86, v87
	v_cvt_pk_bf16_f32 v52, v88, v89
	v_cvt_pk_bf16_f32 v53, v90, v91
	v_cvt_pk_bf16_f32 v54, v92, v93
	v_cvt_pk_bf16_f32 v55, v94, v95
	global_store_dwordx2 v1, v[48:49], s[10:11] offset:0
	global_store_dwordx2 v1, v[50:51], s[10:11] offset:512
	global_store_dwordx2 v1, v[52:53], s[10:11] offset:1024
	global_store_dwordx2 v1, v[54:55], s[10:11] offset:1536
	s_add_u32 s10, s10, 0x800
	s_addc_u32 s11, s11, 0
	s_waitcnt vmcnt(36)
	v_lshlrev_b32_e32 v80, 16, v58
	v_and_b32_e32 v81, 0xffff0000, v58
	v_lshlrev_b32_e32 v82, 16, v59
	v_and_b32_e32 v83, 0xffff0000, v59
	v_lshlrev_b32_e32 v84, 16, v60
	v_and_b32_e32 v85, 0xffff0000, v60
	v_lshlrev_b32_e32 v86, 16, v61
	v_and_b32_e32 v87, 0xffff0000, v61
	v_lshlrev_b32_e32 v88, 16, v62
	v_and_b32_e32 v89, 0xffff0000, v62
	v_lshlrev_b32_e32 v90, 16, v63
	v_and_b32_e32 v91, 0xffff0000, v63
	v_lshlrev_b32_e32 v92, 16, v64
	v_and_b32_e32 v93, 0xffff0000, v64
	v_lshlrev_b32_e32 v94, 16, v65
	v_and_b32_e32 v95, 0xffff0000, v65
	v_lshlrev_b32_e32 v114, 16, v66
	v_and_b32_e32 v115, 0xffff0000, v66
	v_lshlrev_b32_e32 v116, 16, v67
	v_and_b32_e32 v117, 0xffff0000, v67
	v_mul_f32_e32 v114, 0xbfb8aa3b, v114
	v_mul_f32_e32 v115, 0xbfb8aa3b, v115
	v_mul_f32_e32 v116, 0xbfb8aa3b, v116
	v_mul_f32_e32 v117, 0xbfb8aa3b, v117
	v_exp_f32_e32 v114, v114
	v_exp_f32_e32 v115, v115
	v_exp_f32_e32 v116, v116
	v_exp_f32_e32 v117, v117
	s_nop 0
	v_add_f32_e32 v114, 1.0, v114
	v_add_f32_e32 v115, 1.0, v115
	v_add_f32_e32 v116, 1.0, v116
	v_add_f32_e32 v117, 1.0, v117
	v_div_scale_f32 v108, s[22:23], v114, v114, 1.0
	v_rcp_f32_e32 v109, v108
	s_nop 0
	v_fma_f32 v110, -v108, v109, 1.0
	v_fmac_f32_e32 v109, v110, v109
	v_div_scale_f32 v110, vcc, 1.0, v114, 1.0
	v_mul_f32_e32 v111, v110, v109
	v_fma_f32 v112, -v108, v111, v110
	v_fmac_f32_e32 v111, v112, v109
	v_fma_f32 v108, -v108, v111, v110
	v_div_fmas_f32 v108, v108, v109, v111
	v_div_fixup_f32 v114, v108, v114, 1.0
	v_mul_f32_e32 v92, v114, v92
	v_div_scale_f32 v108, s[22:23], v115, v115, 1.0
	v_rcp_f32_e32 v109, v108
	s_nop 0
	v_fma_f32 v110, -v108, v109, 1.0
	v_fmac_f32_e32 v109, v110, v109
	v_div_scale_f32 v110, vcc, 1.0, v115, 1.0
	v_mul_f32_e32 v111, v110, v109
	v_fma_f32 v112, -v108, v111, v110
	v_fmac_f32_e32 v111, v112, v109
	v_fma_f32 v108, -v108, v111, v110
	v_div_fmas_f32 v108, v108, v109, v111
	v_div_fixup_f32 v115, v108, v115, 1.0
	v_mul_f32_e32 v93, v115, v93
	v_div_scale_f32 v108, s[22:23], v116, v116, 1.0
	v_rcp_f32_e32 v109, v108
	s_nop 0
	v_fma_f32 v110, -v108, v109, 1.0
	v_fmac_f32_e32 v109, v110, v109
	v_div_scale_f32 v110, vcc, 1.0, v116, 1.0
	v_mul_f32_e32 v111, v110, v109
	v_fma_f32 v112, -v108, v111, v110
	v_fmac_f32_e32 v111, v112, v109
	v_fma_f32 v108, -v108, v111, v110
	v_div_fmas_f32 v108, v108, v109, v111
	v_div_fixup_f32 v116, v108, v116, 1.0
	v_mul_f32_e32 v94, v116, v94
	v_div_scale_f32 v108, s[22:23], v117, v117, 1.0
	v_rcp_f32_e32 v109, v108
	s_nop 0
	v_fma_f32 v110, -v108, v109, 1.0
	v_fmac_f32_e32 v109, v110, v109
	v_div_scale_f32 v110, vcc, 1.0, v117, 1.0
	v_mul_f32_e32 v111, v110, v109
	v_fma_f32 v112, -v108, v111, v110
	v_fmac_f32_e32 v111, v112, v109
	v_fma_f32 v108, -v108, v111, v110
	v_div_fmas_f32 v108, v108, v109, v111
	v_div_fixup_f32 v117, v108, v117, 1.0
	v_mul_f32_e32 v95, v117, v95
	v_pk_mul_f32 v[108:109], v[80:81], v[80:81]
	v_pk_fma_f32 v[108:109], v[82:83], v[82:83], v[108:109]
	v_add_f32_e32 v96, v108, v109
	v_pk_mul_f32 v[110:111], v[84:85], v[84:85]
	v_pk_fma_f32 v[110:111], v[86:87], v[86:87], v[110:111]
	v_add_f32_e32 v97, v110, v111
	v_pk_mul_f32 v[108:109], v[88:89], v[88:89]
	v_pk_fma_f32 v[108:109], v[90:91], v[90:91], v[108:109]
	v_add_f32_e32 v98, v108, v109
	v_pk_mul_f32 v[110:111], v[92:93], v[92:93]
	v_pk_fma_f32 v[110:111], v[94:95], v[94:95], v[110:111]
	v_add_f32_e32 v99, v110, v111
	v_add_f32_dpp v96, v96, v96 row_ror:8 row_mask:0xf bank_mask:0xf
	s_nop 0
	v_add_f32_dpp v97, v97, v97 row_ror:8 row_mask:0xf bank_mask:0xf
	s_nop 0
	v_add_f32_dpp v96, v96, v96 row_ror:4 row_mask:0xf bank_mask:0xf
	s_nop 0
	v_add_f32_dpp v97, v97, v97 row_ror:4 row_mask:0xf bank_mask:0xf
	s_nop 0
	v_add_f32_dpp v96, v96, v96 row_ror:2 row_mask:0xf bank_mask:0xf
	s_nop 0
	v_add_f32_dpp v97, v97, v97 row_ror:2 row_mask:0xf bank_mask:0xf
	s_nop 0
	v_add_f32_dpp v96, v96, v96 row_ror:1 row_mask:0xf bank_mask:0xf
	s_nop 0
	v_add_f32_dpp v97, v97, v97 row_ror:1 row_mask:0xf bank_mask:0xf
	s_nop 0
	v_readlane_b32 s0, v96, 0
	v_readlane_b32 s1, v96, 16
	v_readlane_b32 s18, v96, 32
	v_readlane_b32 s19, v96, 48
	v_readlane_b32 s20, v97, 0
	v_readlane_b32 s21, v97, 16
	v_readlane_b32 s22, v97, 32
	v_readlane_b32 s23, v97, 48
	s_nop 1
	v_mov_b32_e32 v100, s0
	v_mov_b32_e32 v102, s20
	v_add_f32_e32 v100, s1, v100
	v_add_f32_e32 v102, s21, v102
	v_add_f32_e32 v100, s18, v100
	v_add_f32_e32 v102, s22, v102
	v_add_f32_e32 v100, s19, v100
	v_add_f32_e32 v102, s23, v102
	v_add_f32_dpp v98, v98, v98 row_ror:8 row_mask:0xf bank_mask:0xf
	s_nop 0
	v_add_f32_dpp v99, v99, v99 row_ror:8 row_mask:0xf bank_mask:0xf
	s_nop 0
	v_add_f32_dpp v98, v98, v98 row_ror:4 row_mask:0xf bank_mask:0xf
	s_nop 0
	v_add_f32_dpp v99, v99, v99 row_ror:4 row_mask:0xf bank_mask:0xf
	s_nop 0
	v_add_f32_dpp v98, v98, v98 row_ror:2 row_mask:0xf bank_mask:0xf
	s_nop 0
	v_add_f32_dpp v99, v99, v99 row_ror:2 row_mask:0xf bank_mask:0xf
	s_nop 0
	v_add_f32_dpp v98, v98, v98 row_ror:1 row_mask:0xf bank_mask:0xf
	s_nop 0
	v_add_f32_dpp v99, v99, v99 row_ror:1 row_mask:0xf bank_mask:0xf
	s_nop 0
	v_readlane_b32 s0, v98, 0
	v_readlane_b32 s1, v98, 16
	v_readlane_b32 s18, v98, 32
	v_readlane_b32 s19, v98, 48
	v_readlane_b32 s20, v99, 0
	v_readlane_b32 s21, v99, 16
	v_readlane_b32 s22, v99, 32
	v_readlane_b32 s23, v99, 48
	s_nop 1
	v_mov_b32_e32 v104, s0
	v_mov_b32_e32 v106, s20
	v_add_f32_e32 v104, s1, v104
	v_add_f32_e32 v106, s21, v106
	v_add_f32_e32 v104, s18, v104
	v_add_f32_e32 v106, s22, v106
	v_add_f32_e32 v104, s19, v104
	v_add_f32_e32 v106, s23, v106
	v_fmamk_f32 v100, v100, 0x3b800000, v197
	v_fmamk_f32 v102, v102, 0x3b800000, v197
	v_fmamk_f32 v104, v104, 0x3b800000, v197
	v_fmamk_f32 v106, v106, 0x3b800000, v197
	v_rsq_f32_e32 v100, v100
	v_rsq_f32_e32 v102, v102
	v_rsq_f32_e32 v104, v104
	v_rsq_f32_e32 v106, v106
	s_nop 0
	v_pk_mul_f32 v[80:81], v[100:101], v[80:81] op_sel_hi:[0,1]
	v_pk_mul_f32 v[82:83], v[100:101], v[82:83] op_sel_hi:[0,1]
	v_pk_mul_f32 v[84:85], v[102:103], v[84:85] op_sel_hi:[0,1]
	v_pk_mul_f32 v[86:87], v[102:103], v[86:87] op_sel_hi:[0,1]
	v_pk_mul_f32 v[88:89], v[104:105], v[88:89] op_sel_hi:[0,1]
	v_pk_mul_f32 v[90:91], v[104:105], v[90:91] op_sel_hi:[0,1]
	v_pk_mul_f32 v[92:93], v[106:107], v[92:93] op_sel_hi:[0,1]
	v_pk_mul_f32 v[94:95], v[106:107], v[94:95] op_sel_hi:[0,1]
	v_pk_mul_f32 v[80:81], v[2:3], v[80:81]
	v_pk_mul_f32 v[82:83], v[4:5], v[82:83]
	v_pk_mul_f32 v[84:85], v[6:7], v[84:85]
	v_pk_mul_f32 v[86:87], v[8:9], v[86:87]
	v_pk_mul_f32 v[88:89], v[10:11], v[88:89]
	v_pk_mul_f32 v[90:91], v[12:13], v[90:91]
	v_pk_mul_f32 v[92:93], v[14:15], v[92:93]
	v_pk_mul_f32 v[94:95], v[16:17], v[94:95]
	v_cvt_pk_bf16_f32 v58, v80, v81
	v_cvt_pk_bf16_f32 v59, v82, v83
	v_cvt_pk_bf16_f32 v60, v84, v85
	v_cvt_pk_bf16_f32 v61, v86, v87
	v_cvt_pk_bf16_f32 v62, v88, v89
	v_cvt_pk_bf16_f32 v63, v90, v91
	v_cvt_pk_bf16_f32 v64, v92, v93
	v_cvt_pk_bf16_f32 v65, v94, v95
	global_store_dwordx2 v1, v[58:59], s[10:11] offset:0
	global_store_dwordx2 v1, v[60:61], s[10:11] offset:512
	global_store_dwordx2 v1, v[62:63], s[10:11] offset:1024
	global_store_dwordx2 v1, v[64:65], s[10:11] offset:1536
	s_add_u32 s10, s10, 0x800
	s_addc_u32 s11, s11, 0
	s_waitcnt vmcnt(35)
	v_lshlrev_b32_e32 v80, 16, v68
	v_and_b32_e32 v81, 0xffff0000, v68
	v_lshlrev_b32_e32 v82, 16, v69
	v_and_b32_e32 v83, 0xffff0000, v69
	v_lshlrev_b32_e32 v84, 16, v70
	v_and_b32_e32 v85, 0xffff0000, v70
	v_lshlrev_b32_e32 v86, 16, v71
	v_and_b32_e32 v87, 0xffff0000, v71
	v_lshlrev_b32_e32 v88, 16, v72
	v_and_b32_e32 v89, 0xffff0000, v72
	v_lshlrev_b32_e32 v90, 16, v73
	v_and_b32_e32 v91, 0xffff0000, v73
	v_lshlrev_b32_e32 v92, 16, v74
	v_and_b32_e32 v93, 0xffff0000, v74
	v_lshlrev_b32_e32 v94, 16, v75
	v_and_b32_e32 v95, 0xffff0000, v75
	v_lshlrev_b32_e32 v114, 16, v76
	v_and_b32_e32 v115, 0xffff0000, v76
	v_lshlrev_b32_e32 v116, 16, v77
	v_and_b32_e32 v117, 0xffff0000, v77
	v_mul_f32_e32 v114, 0xbfb8aa3b, v114
	v_mul_f32_e32 v115, 0xbfb8aa3b, v115
	v_mul_f32_e32 v116, 0xbfb8aa3b, v116
	v_mul_f32_e32 v117, 0xbfb8aa3b, v117
	v_exp_f32_e32 v114, v114
	v_exp_f32_e32 v115, v115
	v_exp_f32_e32 v116, v116
	v_exp_f32_e32 v117, v117
	s_nop 0
	v_add_f32_e32 v114, 1.0, v114
	v_add_f32_e32 v115, 1.0, v115
	v_add_f32_e32 v116, 1.0, v116
	v_add_f32_e32 v117, 1.0, v117
	v_div_scale_f32 v108, s[22:23], v114, v114, 1.0
	v_rcp_f32_e32 v109, v108
	s_nop 0
	v_fma_f32 v110, -v108, v109, 1.0
	v_fmac_f32_e32 v109, v110, v109
	v_div_scale_f32 v110, vcc, 1.0, v114, 1.0
	v_mul_f32_e32 v111, v110, v109
	v_fma_f32 v112, -v108, v111, v110
	v_fmac_f32_e32 v111, v112, v109
	v_fma_f32 v108, -v108, v111, v110
	v_div_fmas_f32 v108, v108, v109, v111
	v_div_fixup_f32 v114, v108, v114, 1.0
	v_mul_f32_e32 v92, v114, v92
	v_div_scale_f32 v108, s[22:23], v115, v115, 1.0
	v_rcp_f32_e32 v109, v108
	s_nop 0
	v_fma_f32 v110, -v108, v109, 1.0
	v_fmac_f32_e32 v109, v110, v109
	v_div_scale_f32 v110, vcc, 1.0, v115, 1.0
	v_mul_f32_e32 v111, v110, v109
	v_fma_f32 v112, -v108, v111, v110
	v_fmac_f32_e32 v111, v112, v109
	v_fma_f32 v108, -v108, v111, v110
	v_div_fmas_f32 v108, v108, v109, v111
	v_div_fixup_f32 v115, v108, v115, 1.0
	v_mul_f32_e32 v93, v115, v93
	v_div_scale_f32 v108, s[22:23], v116, v116, 1.0
	v_rcp_f32_e32 v109, v108
	s_nop 0
	v_fma_f32 v110, -v108, v109, 1.0
	v_fmac_f32_e32 v109, v110, v109
	v_div_scale_f32 v110, vcc, 1.0, v116, 1.0
	v_mul_f32_e32 v111, v110, v109
	v_fma_f32 v112, -v108, v111, v110
	v_fmac_f32_e32 v111, v112, v109
	v_fma_f32 v108, -v108, v111, v110
	v_div_fmas_f32 v108, v108, v109, v111
	v_div_fixup_f32 v116, v108, v116, 1.0
	v_mul_f32_e32 v94, v116, v94
	v_div_scale_f32 v108, s[22:23], v117, v117, 1.0
	v_rcp_f32_e32 v109, v108
	s_nop 0
	v_fma_f32 v110, -v108, v109, 1.0
	v_fmac_f32_e32 v109, v110, v109
	v_div_scale_f32 v110, vcc, 1.0, v117, 1.0
	v_mul_f32_e32 v111, v110, v109
	v_fma_f32 v112, -v108, v111, v110
	v_fmac_f32_e32 v111, v112, v109
	v_fma_f32 v108, -v108, v111, v110
	v_div_fmas_f32 v108, v108, v109, v111
	v_div_fixup_f32 v117, v108, v117, 1.0
	v_mul_f32_e32 v95, v117, v95
	v_pk_mul_f32 v[108:109], v[80:81], v[80:81]
	v_pk_fma_f32 v[108:109], v[82:83], v[82:83], v[108:109]
	v_add_f32_e32 v96, v108, v109
	v_pk_mul_f32 v[110:111], v[84:85], v[84:85]
	v_pk_fma_f32 v[110:111], v[86:87], v[86:87], v[110:111]
	v_add_f32_e32 v97, v110, v111
	v_pk_mul_f32 v[108:109], v[88:89], v[88:89]
	v_pk_fma_f32 v[108:109], v[90:91], v[90:91], v[108:109]
	v_add_f32_e32 v98, v108, v109
	v_pk_mul_f32 v[110:111], v[92:93], v[92:93]
	v_pk_fma_f32 v[110:111], v[94:95], v[94:95], v[110:111]
	v_add_f32_e32 v99, v110, v111
	v_add_f32_dpp v96, v96, v96 row_ror:8 row_mask:0xf bank_mask:0xf
	s_nop 0
	v_add_f32_dpp v97, v97, v97 row_ror:8 row_mask:0xf bank_mask:0xf
	s_nop 0
	v_add_f32_dpp v96, v96, v96 row_ror:4 row_mask:0xf bank_mask:0xf
	s_nop 0
	v_add_f32_dpp v97, v97, v97 row_ror:4 row_mask:0xf bank_mask:0xf
	s_nop 0
	v_add_f32_dpp v96, v96, v96 row_ror:2 row_mask:0xf bank_mask:0xf
	s_nop 0
	v_add_f32_dpp v97, v97, v97 row_ror:2 row_mask:0xf bank_mask:0xf
	s_nop 0
	v_add_f32_dpp v96, v96, v96 row_ror:1 row_mask:0xf bank_mask:0xf
	s_nop 0
	v_add_f32_dpp v97, v97, v97 row_ror:1 row_mask:0xf bank_mask:0xf
	s_nop 0
	v_readlane_b32 s0, v96, 0
	v_readlane_b32 s1, v96, 16
	v_readlane_b32 s18, v96, 32
	v_readlane_b32 s19, v96, 48
	v_readlane_b32 s20, v97, 0
	v_readlane_b32 s21, v97, 16
	v_readlane_b32 s22, v97, 32
	v_readlane_b32 s23, v97, 48
	s_nop 1
	v_mov_b32_e32 v100, s0
	v_mov_b32_e32 v102, s20
	v_add_f32_e32 v100, s1, v100
	v_add_f32_e32 v102, s21, v102
	v_add_f32_e32 v100, s18, v100
	v_add_f32_e32 v102, s22, v102
	v_add_f32_e32 v100, s19, v100
	v_add_f32_e32 v102, s23, v102
	v_add_f32_dpp v98, v98, v98 row_ror:8 row_mask:0xf bank_mask:0xf
	s_nop 0
	v_add_f32_dpp v99, v99, v99 row_ror:8 row_mask:0xf bank_mask:0xf
	s_nop 0
	v_add_f32_dpp v98, v98, v98 row_ror:4 row_mask:0xf bank_mask:0xf
	s_nop 0
	v_add_f32_dpp v99, v99, v99 row_ror:4 row_mask:0xf bank_mask:0xf
	s_nop 0
	v_add_f32_dpp v98, v98, v98 row_ror:2 row_mask:0xf bank_mask:0xf
	s_nop 0
	v_add_f32_dpp v99, v99, v99 row_ror:2 row_mask:0xf bank_mask:0xf
	s_nop 0
	v_add_f32_dpp v98, v98, v98 row_ror:1 row_mask:0xf bank_mask:0xf
	s_nop 0
	v_add_f32_dpp v99, v99, v99 row_ror:1 row_mask:0xf bank_mask:0xf
	s_nop 0
	v_readlane_b32 s0, v98, 0
	v_readlane_b32 s1, v98, 16
	v_readlane_b32 s18, v98, 32
	v_readlane_b32 s19, v98, 48
	v_readlane_b32 s20, v99, 0
	v_readlane_b32 s21, v99, 16
	v_readlane_b32 s22, v99, 32
	v_readlane_b32 s23, v99, 48
	s_nop 1
	v_mov_b32_e32 v104, s0
	v_mov_b32_e32 v106, s20
	v_add_f32_e32 v104, s1, v104
	v_add_f32_e32 v106, s21, v106
	v_add_f32_e32 v104, s18, v104
	v_add_f32_e32 v106, s22, v106
	v_add_f32_e32 v104, s19, v104
	v_add_f32_e32 v106, s23, v106
	v_fmamk_f32 v100, v100, 0x3b800000, v197
	v_fmamk_f32 v102, v102, 0x3b800000, v197
	v_fmamk_f32 v104, v104, 0x3b800000, v197
	v_fmamk_f32 v106, v106, 0x3b800000, v197
	v_rsq_f32_e32 v100, v100
	v_rsq_f32_e32 v102, v102
	v_rsq_f32_e32 v104, v104
	v_rsq_f32_e32 v106, v106
	s_nop 0
	v_pk_mul_f32 v[80:81], v[100:101], v[80:81] op_sel_hi:[0,1]
	v_pk_mul_f32 v[82:83], v[100:101], v[82:83] op_sel_hi:[0,1]
	v_pk_mul_f32 v[84:85], v[102:103], v[84:85] op_sel_hi:[0,1]
	v_pk_mul_f32 v[86:87], v[102:103], v[86:87] op_sel_hi:[0,1]
	v_pk_mul_f32 v[88:89], v[104:105], v[88:89] op_sel_hi:[0,1]
	v_pk_mul_f32 v[90:91], v[104:105], v[90:91] op_sel_hi:[0,1]
	v_pk_mul_f32 v[92:93], v[106:107], v[92:93] op_sel_hi:[0,1]
	v_pk_mul_f32 v[94:95], v[106:107], v[94:95] op_sel_hi:[0,1]
	v_pk_mul_f32 v[80:81], v[2:3], v[80:81]
	v_pk_mul_f32 v[82:83], v[4:5], v[82:83]
	v_pk_mul_f32 v[84:85], v[6:7], v[84:85]
	v_pk_mul_f32 v[86:87], v[8:9], v[86:87]
	v_pk_mul_f32 v[88:89], v[10:11], v[88:89]
	v_pk_mul_f32 v[90:91], v[12:13], v[90:91]
	v_pk_mul_f32 v[92:93], v[14:15], v[92:93]
	v_pk_mul_f32 v[94:95], v[16:17], v[94:95]
	v_cvt_pk_bf16_f32 v68, v80, v81
	v_cvt_pk_bf16_f32 v69, v82, v83
	v_cvt_pk_bf16_f32 v70, v84, v85
	v_cvt_pk_bf16_f32 v71, v86, v87
	v_cvt_pk_bf16_f32 v72, v88, v89
	v_cvt_pk_bf16_f32 v73, v90, v91
	v_cvt_pk_bf16_f32 v74, v92, v93
	v_cvt_pk_bf16_f32 v75, v94, v95
	global_store_dwordx2 v1, v[68:69], s[10:11] offset:0
	global_store_dwordx2 v1, v[70:71], s[10:11] offset:512
	global_store_dwordx2 v1, v[72:73], s[10:11] offset:1024
	global_store_dwordx2 v1, v[74:75], s[10:11] offset:1536
	s_add_u32 s10, s10, 0x800
	s_addc_u32 s11, s11, 0
	s_waitcnt vmcnt(30)
	v_lshlrev_b32_e32 v80, 16, v18
	v_and_b32_e32 v81, 0xffff0000, v18
	v_lshlrev_b32_e32 v82, 16, v19
	v_and_b32_e32 v83, 0xffff0000, v19
	v_lshlrev_b32_e32 v84, 16, v20
	v_and_b32_e32 v85, 0xffff0000, v20
	v_lshlrev_b32_e32 v86, 16, v21
	v_and_b32_e32 v87, 0xffff0000, v21
	v_lshlrev_b32_e32 v88, 16, v22
	v_and_b32_e32 v89, 0xffff0000, v22
	v_lshlrev_b32_e32 v90, 16, v23
	v_and_b32_e32 v91, 0xffff0000, v23
	v_lshlrev_b32_e32 v92, 16, v24
	v_and_b32_e32 v93, 0xffff0000, v24
	v_lshlrev_b32_e32 v94, 16, v25
	v_and_b32_e32 v95, 0xffff0000, v25
	v_lshlrev_b32_e32 v114, 16, v26
	v_and_b32_e32 v115, 0xffff0000, v26
	v_lshlrev_b32_e32 v116, 16, v27
	v_and_b32_e32 v117, 0xffff0000, v27
	v_mul_f32_e32 v114, 0xbfb8aa3b, v114
	v_mul_f32_e32 v115, 0xbfb8aa3b, v115
	v_mul_f32_e32 v116, 0xbfb8aa3b, v116
	v_mul_f32_e32 v117, 0xbfb8aa3b, v117
	v_exp_f32_e32 v114, v114
	v_exp_f32_e32 v115, v115
	v_exp_f32_e32 v116, v116
	v_exp_f32_e32 v117, v117
	s_nop 0
	v_add_f32_e32 v114, 1.0, v114
	v_add_f32_e32 v115, 1.0, v115
	v_add_f32_e32 v116, 1.0, v116
	v_add_f32_e32 v117, 1.0, v117
	v_div_scale_f32 v108, s[22:23], v114, v114, 1.0
	v_rcp_f32_e32 v109, v108
	s_nop 0
	v_fma_f32 v110, -v108, v109, 1.0
	v_fmac_f32_e32 v109, v110, v109
	v_div_scale_f32 v110, vcc, 1.0, v114, 1.0
	v_mul_f32_e32 v111, v110, v109
	v_fma_f32 v112, -v108, v111, v110
	v_fmac_f32_e32 v111, v112, v109
	v_fma_f32 v108, -v108, v111, v110
	v_div_fmas_f32 v108, v108, v109, v111
	v_div_fixup_f32 v114, v108, v114, 1.0
	v_mul_f32_e32 v92, v114, v92
	v_div_scale_f32 v108, s[22:23], v115, v115, 1.0
	v_rcp_f32_e32 v109, v108
	s_nop 0
	v_fma_f32 v110, -v108, v109, 1.0
	v_fmac_f32_e32 v109, v110, v109
	v_div_scale_f32 v110, vcc, 1.0, v115, 1.0
	v_mul_f32_e32 v111, v110, v109
	v_fma_f32 v112, -v108, v111, v110
	v_fmac_f32_e32 v111, v112, v109
	v_fma_f32 v108, -v108, v111, v110
	v_div_fmas_f32 v108, v108, v109, v111
	v_div_fixup_f32 v115, v108, v115, 1.0
	v_mul_f32_e32 v93, v115, v93
	v_div_scale_f32 v108, s[22:23], v116, v116, 1.0
	v_rcp_f32_e32 v109, v108
	s_nop 0
	v_fma_f32 v110, -v108, v109, 1.0
	v_fmac_f32_e32 v109, v110, v109
	v_div_scale_f32 v110, vcc, 1.0, v116, 1.0
	v_mul_f32_e32 v111, v110, v109
	v_fma_f32 v112, -v108, v111, v110
	v_fmac_f32_e32 v111, v112, v109
	v_fma_f32 v108, -v108, v111, v110
	v_div_fmas_f32 v108, v108, v109, v111
	v_div_fixup_f32 v116, v108, v116, 1.0
	v_mul_f32_e32 v94, v116, v94
	v_div_scale_f32 v108, s[22:23], v117, v117, 1.0
	v_rcp_f32_e32 v109, v108
	s_nop 0
	v_fma_f32 v110, -v108, v109, 1.0
	v_fmac_f32_e32 v109, v110, v109
	v_div_scale_f32 v110, vcc, 1.0, v117, 1.0
	v_mul_f32_e32 v111, v110, v109
	v_fma_f32 v112, -v108, v111, v110
	v_fmac_f32_e32 v111, v112, v109
	v_fma_f32 v108, -v108, v111, v110
	v_div_fmas_f32 v108, v108, v109, v111
	v_div_fixup_f32 v117, v108, v117, 1.0
	v_mul_f32_e32 v95, v117, v95
	v_pk_mul_f32 v[108:109], v[80:81], v[80:81]
	v_pk_fma_f32 v[108:109], v[82:83], v[82:83], v[108:109]
	v_add_f32_e32 v96, v108, v109
	v_pk_mul_f32 v[110:111], v[84:85], v[84:85]
	v_pk_fma_f32 v[110:111], v[86:87], v[86:87], v[110:111]
	v_add_f32_e32 v97, v110, v111
	v_pk_mul_f32 v[108:109], v[88:89], v[88:89]
	v_pk_fma_f32 v[108:109], v[90:91], v[90:91], v[108:109]
	v_add_f32_e32 v98, v108, v109
	v_pk_mul_f32 v[110:111], v[92:93], v[92:93]
	v_pk_fma_f32 v[110:111], v[94:95], v[94:95], v[110:111]
	v_add_f32_e32 v99, v110, v111
	v_add_f32_dpp v96, v96, v96 row_ror:8 row_mask:0xf bank_mask:0xf
	s_nop 0
	v_add_f32_dpp v97, v97, v97 row_ror:8 row_mask:0xf bank_mask:0xf
	s_nop 0
	v_add_f32_dpp v96, v96, v96 row_ror:4 row_mask:0xf bank_mask:0xf
	s_nop 0
	v_add_f32_dpp v97, v97, v97 row_ror:4 row_mask:0xf bank_mask:0xf
	s_nop 0
	v_add_f32_dpp v96, v96, v96 row_ror:2 row_mask:0xf bank_mask:0xf
	s_nop 0
	v_add_f32_dpp v97, v97, v97 row_ror:2 row_mask:0xf bank_mask:0xf
	s_nop 0
	v_add_f32_dpp v96, v96, v96 row_ror:1 row_mask:0xf bank_mask:0xf
	s_nop 0
	v_add_f32_dpp v97, v97, v97 row_ror:1 row_mask:0xf bank_mask:0xf
	s_nop 0
	v_readlane_b32 s0, v96, 0
	v_readlane_b32 s1, v96, 16
	v_readlane_b32 s18, v96, 32
	v_readlane_b32 s19, v96, 48
	v_readlane_b32 s20, v97, 0
	v_readlane_b32 s21, v97, 16
	v_readlane_b32 s22, v97, 32
	v_readlane_b32 s23, v97, 48
	s_nop 1
	v_mov_b32_e32 v100, s0
	v_mov_b32_e32 v102, s20
	v_add_f32_e32 v100, s1, v100
	v_add_f32_e32 v102, s21, v102
	v_add_f32_e32 v100, s18, v100
	v_add_f32_e32 v102, s22, v102
	v_add_f32_e32 v100, s19, v100
	v_add_f32_e32 v102, s23, v102
	v_add_f32_dpp v98, v98, v98 row_ror:8 row_mask:0xf bank_mask:0xf
	s_nop 0
	v_add_f32_dpp v99, v99, v99 row_ror:8 row_mask:0xf bank_mask:0xf
	s_nop 0
	v_add_f32_dpp v98, v98, v98 row_ror:4 row_mask:0xf bank_mask:0xf
	s_nop 0
	v_add_f32_dpp v99, v99, v99 row_ror:4 row_mask:0xf bank_mask:0xf
	s_nop 0
	v_add_f32_dpp v98, v98, v98 row_ror:2 row_mask:0xf bank_mask:0xf
	s_nop 0
	v_add_f32_dpp v99, v99, v99 row_ror:2 row_mask:0xf bank_mask:0xf
	s_nop 0
	v_add_f32_dpp v98, v98, v98 row_ror:1 row_mask:0xf bank_mask:0xf
	s_nop 0
	v_add_f32_dpp v99, v99, v99 row_ror:1 row_mask:0xf bank_mask:0xf
	s_nop 0
	v_readlane_b32 s0, v98, 0
	v_readlane_b32 s1, v98, 16
	v_readlane_b32 s18, v98, 32
	v_readlane_b32 s19, v98, 48
	v_readlane_b32 s20, v99, 0
	v_readlane_b32 s21, v99, 16
	v_readlane_b32 s22, v99, 32
	v_readlane_b32 s23, v99, 48
	s_nop 1
	v_mov_b32_e32 v104, s0
	v_mov_b32_e32 v106, s20
	v_add_f32_e32 v104, s1, v104
	v_add_f32_e32 v106, s21, v106
	v_add_f32_e32 v104, s18, v104
	v_add_f32_e32 v106, s22, v106
	v_add_f32_e32 v104, s19, v104
	v_add_f32_e32 v106, s23, v106
	v_fmamk_f32 v100, v100, 0x3b800000, v197
	v_fmamk_f32 v102, v102, 0x3b800000, v197
	v_fmamk_f32 v104, v104, 0x3b800000, v197
	v_fmamk_f32 v106, v106, 0x3b800000, v197
	v_rsq_f32_e32 v100, v100
	v_rsq_f32_e32 v102, v102
	v_rsq_f32_e32 v104, v104
	v_rsq_f32_e32 v106, v106
	s_nop 0
	v_pk_mul_f32 v[80:81], v[100:101], v[80:81] op_sel_hi:[0,1]
	v_pk_mul_f32 v[82:83], v[100:101], v[82:83] op_sel_hi:[0,1]
	v_pk_mul_f32 v[84:85], v[102:103], v[84:85] op_sel_hi:[0,1]
	v_pk_mul_f32 v[86:87], v[102:103], v[86:87] op_sel_hi:[0,1]
	v_pk_mul_f32 v[88:89], v[104:105], v[88:89] op_sel_hi:[0,1]
	v_pk_mul_f32 v[90:91], v[104:105], v[90:91] op_sel_hi:[0,1]
	v_pk_mul_f32 v[92:93], v[106:107], v[92:93] op_sel_hi:[0,1]
	v_pk_mul_f32 v[94:95], v[106:107], v[94:95] op_sel_hi:[0,1]
	v_pk_mul_f32 v[80:81], v[2:3], v[80:81]
	v_pk_mul_f32 v[82:83], v[4:5], v[82:83]
	v_pk_mul_f32 v[84:85], v[6:7], v[84:85]
	v_pk_mul_f32 v[86:87], v[8:9], v[86:87]
	v_pk_mul_f32 v[88:89], v[10:11], v[88:89]
	v_pk_mul_f32 v[90:91], v[12:13], v[90:91]
	v_pk_mul_f32 v[92:93], v[14:15], v[92:93]
	v_pk_mul_f32 v[94:95], v[16:17], v[94:95]
	v_cvt_pk_bf16_f32 v18, v80, v81
	v_cvt_pk_bf16_f32 v19, v82, v83
	v_cvt_pk_bf16_f32 v20, v84, v85
	v_cvt_pk_bf16_f32 v21, v86, v87
	v_cvt_pk_bf16_f32 v22, v88, v89
	v_cvt_pk_bf16_f32 v23, v90, v91
	v_cvt_pk_bf16_f32 v24, v92, v93
	v_cvt_pk_bf16_f32 v25, v94, v95
	global_store_dwordx2 v1, v[18:19], s[10:11] offset:0
	global_store_dwordx2 v1, v[20:21], s[10:11] offset:512
	global_store_dwordx2 v1, v[22:23], s[10:11] offset:1024
	global_store_dwordx2 v1, v[24:25], s[10:11] offset:1536
	s_add_u32 s10, s10, 0x800
	s_addc_u32 s11, s11, 0
	s_waitcnt vmcnt(25)
	v_lshlrev_b32_e32 v80, 16, v28
	v_and_b32_e32 v81, 0xffff0000, v28
	v_lshlrev_b32_e32 v82, 16, v29
	v_and_b32_e32 v83, 0xffff0000, v29
	v_lshlrev_b32_e32 v84, 16, v30
	v_and_b32_e32 v85, 0xffff0000, v30
	v_lshlrev_b32_e32 v86, 16, v31
	v_and_b32_e32 v87, 0xffff0000, v31
	v_lshlrev_b32_e32 v88, 16, v32
	v_and_b32_e32 v89, 0xffff0000, v32
	v_lshlrev_b32_e32 v90, 16, v33
	v_and_b32_e32 v91, 0xffff0000, v33
	v_lshlrev_b32_e32 v92, 16, v34
	v_and_b32_e32 v93, 0xffff0000, v34
	v_lshlrev_b32_e32 v94, 16, v35
	v_and_b32_e32 v95, 0xffff0000, v35
	v_lshlrev_b32_e32 v114, 16, v36
	v_and_b32_e32 v115, 0xffff0000, v36
	v_lshlrev_b32_e32 v116, 16, v37
	v_and_b32_e32 v117, 0xffff0000, v37
	v_mul_f32_e32 v114, 0xbfb8aa3b, v114
	v_mul_f32_e32 v115, 0xbfb8aa3b, v115
	v_mul_f32_e32 v116, 0xbfb8aa3b, v116
	v_mul_f32_e32 v117, 0xbfb8aa3b, v117
	v_exp_f32_e32 v114, v114
	v_exp_f32_e32 v115, v115
	v_exp_f32_e32 v116, v116
	v_exp_f32_e32 v117, v117
	s_nop 0
	v_add_f32_e32 v114, 1.0, v114
	v_add_f32_e32 v115, 1.0, v115
	v_add_f32_e32 v116, 1.0, v116
	v_add_f32_e32 v117, 1.0, v117
	v_div_scale_f32 v108, s[22:23], v114, v114, 1.0
	v_rcp_f32_e32 v109, v108
	s_nop 0
	v_fma_f32 v110, -v108, v109, 1.0
	v_fmac_f32_e32 v109, v110, v109
	v_div_scale_f32 v110, vcc, 1.0, v114, 1.0
	v_mul_f32_e32 v111, v110, v109
	v_fma_f32 v112, -v108, v111, v110
	v_fmac_f32_e32 v111, v112, v109
	v_fma_f32 v108, -v108, v111, v110
	v_div_fmas_f32 v108, v108, v109, v111
	v_div_fixup_f32 v114, v108, v114, 1.0
	v_mul_f32_e32 v92, v114, v92
	v_div_scale_f32 v108, s[22:23], v115, v115, 1.0
	v_rcp_f32_e32 v109, v108
	s_nop 0
	v_fma_f32 v110, -v108, v109, 1.0
	v_fmac_f32_e32 v109, v110, v109
	v_div_scale_f32 v110, vcc, 1.0, v115, 1.0
	v_mul_f32_e32 v111, v110, v109
	v_fma_f32 v112, -v108, v111, v110
	v_fmac_f32_e32 v111, v112, v109
	v_fma_f32 v108, -v108, v111, v110
	v_div_fmas_f32 v108, v108, v109, v111
	v_div_fixup_f32 v115, v108, v115, 1.0
	v_mul_f32_e32 v93, v115, v93
	v_div_scale_f32 v108, s[22:23], v116, v116, 1.0
	v_rcp_f32_e32 v109, v108
	s_nop 0
	v_fma_f32 v110, -v108, v109, 1.0
	v_fmac_f32_e32 v109, v110, v109
	v_div_scale_f32 v110, vcc, 1.0, v116, 1.0
	v_mul_f32_e32 v111, v110, v109
	v_fma_f32 v112, -v108, v111, v110
	v_fmac_f32_e32 v111, v112, v109
	v_fma_f32 v108, -v108, v111, v110
	v_div_fmas_f32 v108, v108, v109, v111
	v_div_fixup_f32 v116, v108, v116, 1.0
	v_mul_f32_e32 v94, v116, v94
	v_div_scale_f32 v108, s[22:23], v117, v117, 1.0
	v_rcp_f32_e32 v109, v108
	s_nop 0
	v_fma_f32 v110, -v108, v109, 1.0
	v_fmac_f32_e32 v109, v110, v109
	v_div_scale_f32 v110, vcc, 1.0, v117, 1.0
	v_mul_f32_e32 v111, v110, v109
	v_fma_f32 v112, -v108, v111, v110
	v_fmac_f32_e32 v111, v112, v109
	v_fma_f32 v108, -v108, v111, v110
	v_div_fmas_f32 v108, v108, v109, v111
	v_div_fixup_f32 v117, v108, v117, 1.0
	v_mul_f32_e32 v95, v117, v95
	v_pk_mul_f32 v[108:109], v[80:81], v[80:81]
	v_pk_fma_f32 v[108:109], v[82:83], v[82:83], v[108:109]
	v_add_f32_e32 v96, v108, v109
	v_pk_mul_f32 v[110:111], v[84:85], v[84:85]
	v_pk_fma_f32 v[110:111], v[86:87], v[86:87], v[110:111]
	v_add_f32_e32 v97, v110, v111
	v_pk_mul_f32 v[108:109], v[88:89], v[88:89]
	v_pk_fma_f32 v[108:109], v[90:91], v[90:91], v[108:109]
	v_add_f32_e32 v98, v108, v109
	v_pk_mul_f32 v[110:111], v[92:93], v[92:93]
	v_pk_fma_f32 v[110:111], v[94:95], v[94:95], v[110:111]
	v_add_f32_e32 v99, v110, v111
	v_add_f32_dpp v96, v96, v96 row_ror:8 row_mask:0xf bank_mask:0xf
	s_nop 0
	v_add_f32_dpp v97, v97, v97 row_ror:8 row_mask:0xf bank_mask:0xf
	s_nop 0
	v_add_f32_dpp v96, v96, v96 row_ror:4 row_mask:0xf bank_mask:0xf
	s_nop 0
	v_add_f32_dpp v97, v97, v97 row_ror:4 row_mask:0xf bank_mask:0xf
	s_nop 0
	v_add_f32_dpp v96, v96, v96 row_ror:2 row_mask:0xf bank_mask:0xf
	s_nop 0
	v_add_f32_dpp v97, v97, v97 row_ror:2 row_mask:0xf bank_mask:0xf
	s_nop 0
	v_add_f32_dpp v96, v96, v96 row_ror:1 row_mask:0xf bank_mask:0xf
	s_nop 0
	v_add_f32_dpp v97, v97, v97 row_ror:1 row_mask:0xf bank_mask:0xf
	s_nop 0
	v_readlane_b32 s0, v96, 0
	v_readlane_b32 s1, v96, 16
	v_readlane_b32 s18, v96, 32
	v_readlane_b32 s19, v96, 48
	v_readlane_b32 s20, v97, 0
	v_readlane_b32 s21, v97, 16
	v_readlane_b32 s22, v97, 32
	v_readlane_b32 s23, v97, 48
	s_nop 1
	v_mov_b32_e32 v100, s0
	v_mov_b32_e32 v102, s20
	v_add_f32_e32 v100, s1, v100
	v_add_f32_e32 v102, s21, v102
	v_add_f32_e32 v100, s18, v100
	v_add_f32_e32 v102, s22, v102
	v_add_f32_e32 v100, s19, v100
	v_add_f32_e32 v102, s23, v102
	v_add_f32_dpp v98, v98, v98 row_ror:8 row_mask:0xf bank_mask:0xf
	s_nop 0
	v_add_f32_dpp v99, v99, v99 row_ror:8 row_mask:0xf bank_mask:0xf
	s_nop 0
	v_add_f32_dpp v98, v98, v98 row_ror:4 row_mask:0xf bank_mask:0xf
	s_nop 0
	v_add_f32_dpp v99, v99, v99 row_ror:4 row_mask:0xf bank_mask:0xf
	s_nop 0
	v_add_f32_dpp v98, v98, v98 row_ror:2 row_mask:0xf bank_mask:0xf
	s_nop 0
	v_add_f32_dpp v99, v99, v99 row_ror:2 row_mask:0xf bank_mask:0xf
	s_nop 0
	v_add_f32_dpp v98, v98, v98 row_ror:1 row_mask:0xf bank_mask:0xf
	s_nop 0
	v_add_f32_dpp v99, v99, v99 row_ror:1 row_mask:0xf bank_mask:0xf
	s_nop 0
	v_readlane_b32 s0, v98, 0
	v_readlane_b32 s1, v98, 16
	v_readlane_b32 s18, v98, 32
	v_readlane_b32 s19, v98, 48
	v_readlane_b32 s20, v99, 0
	v_readlane_b32 s21, v99, 16
	v_readlane_b32 s22, v99, 32
	v_readlane_b32 s23, v99, 48
	s_nop 1
	v_mov_b32_e32 v104, s0
	v_mov_b32_e32 v106, s20
	v_add_f32_e32 v104, s1, v104
	v_add_f32_e32 v106, s21, v106
	v_add_f32_e32 v104, s18, v104
	v_add_f32_e32 v106, s22, v106
	v_add_f32_e32 v104, s19, v104
	v_add_f32_e32 v106, s23, v106
	v_fmamk_f32 v100, v100, 0x3b800000, v197
	v_fmamk_f32 v102, v102, 0x3b800000, v197
	v_fmamk_f32 v104, v104, 0x3b800000, v197
	v_fmamk_f32 v106, v106, 0x3b800000, v197
	v_rsq_f32_e32 v100, v100
	v_rsq_f32_e32 v102, v102
	v_rsq_f32_e32 v104, v104
	v_rsq_f32_e32 v106, v106
	s_nop 0
	v_pk_mul_f32 v[80:81], v[100:101], v[80:81] op_sel_hi:[0,1]
	v_pk_mul_f32 v[82:83], v[100:101], v[82:83] op_sel_hi:[0,1]
	v_pk_mul_f32 v[84:85], v[102:103], v[84:85] op_sel_hi:[0,1]
	v_pk_mul_f32 v[86:87], v[102:103], v[86:87] op_sel_hi:[0,1]
	v_pk_mul_f32 v[88:89], v[104:105], v[88:89] op_sel_hi:[0,1]
	v_pk_mul_f32 v[90:91], v[104:105], v[90:91] op_sel_hi:[0,1]
	v_pk_mul_f32 v[92:93], v[106:107], v[92:93] op_sel_hi:[0,1]
	v_pk_mul_f32 v[94:95], v[106:107], v[94:95] op_sel_hi:[0,1]
	v_pk_mul_f32 v[80:81], v[2:3], v[80:81]
	v_pk_mul_f32 v[82:83], v[4:5], v[82:83]
	v_pk_mul_f32 v[84:85], v[6:7], v[84:85]
	v_pk_mul_f32 v[86:87], v[8:9], v[86:87]
	v_pk_mul_f32 v[88:89], v[10:11], v[88:89]
	v_pk_mul_f32 v[90:91], v[12:13], v[90:91]
	v_pk_mul_f32 v[92:93], v[14:15], v[92:93]
	v_pk_mul_f32 v[94:95], v[16:17], v[94:95]
	v_cvt_pk_bf16_f32 v28, v80, v81
	v_cvt_pk_bf16_f32 v29, v82, v83
	v_cvt_pk_bf16_f32 v30, v84, v85
	v_cvt_pk_bf16_f32 v31, v86, v87
	v_cvt_pk_bf16_f32 v32, v88, v89
	v_cvt_pk_bf16_f32 v33, v90, v91
	v_cvt_pk_bf16_f32 v34, v92, v93
	v_cvt_pk_bf16_f32 v35, v94, v95
	global_store_dwordx2 v1, v[28:29], s[10:11] offset:0
	global_store_dwordx2 v1, v[30:31], s[10:11] offset:512
	global_store_dwordx2 v1, v[32:33], s[10:11] offset:1024
	global_store_dwordx2 v1, v[34:35], s[10:11] offset:1536
	s_add_u32 s10, s10, 0x800
	s_addc_u32 s11, s11, 0
	s_waitcnt vmcnt(20)
	v_lshlrev_b32_e32 v80, 16, v38
	v_and_b32_e32 v81, 0xffff0000, v38
	v_lshlrev_b32_e32 v82, 16, v39
	v_and_b32_e32 v83, 0xffff0000, v39
	v_lshlrev_b32_e32 v84, 16, v40
	v_and_b32_e32 v85, 0xffff0000, v40
	v_lshlrev_b32_e32 v86, 16, v41
	v_and_b32_e32 v87, 0xffff0000, v41
	v_lshlrev_b32_e32 v88, 16, v42
	v_and_b32_e32 v89, 0xffff0000, v42
	v_lshlrev_b32_e32 v90, 16, v43
	v_and_b32_e32 v91, 0xffff0000, v43
	v_lshlrev_b32_e32 v92, 16, v44
	v_and_b32_e32 v93, 0xffff0000, v44
	v_lshlrev_b32_e32 v94, 16, v45
	v_and_b32_e32 v95, 0xffff0000, v45
	v_lshlrev_b32_e32 v114, 16, v46
	v_and_b32_e32 v115, 0xffff0000, v46
	v_lshlrev_b32_e32 v116, 16, v47
	v_and_b32_e32 v117, 0xffff0000, v47
	v_mul_f32_e32 v114, 0xbfb8aa3b, v114
	v_mul_f32_e32 v115, 0xbfb8aa3b, v115
	v_mul_f32_e32 v116, 0xbfb8aa3b, v116
	v_mul_f32_e32 v117, 0xbfb8aa3b, v117
	v_exp_f32_e32 v114, v114
	v_exp_f32_e32 v115, v115
	v_exp_f32_e32 v116, v116
	v_exp_f32_e32 v117, v117
	s_nop 0
	v_add_f32_e32 v114, 1.0, v114
	v_add_f32_e32 v115, 1.0, v115
	v_add_f32_e32 v116, 1.0, v116
	v_add_f32_e32 v117, 1.0, v117
	v_div_scale_f32 v108, s[22:23], v114, v114, 1.0
	v_rcp_f32_e32 v109, v108
	s_nop 0
	v_fma_f32 v110, -v108, v109, 1.0
	v_fmac_f32_e32 v109, v110, v109
	v_div_scale_f32 v110, vcc, 1.0, v114, 1.0
	v_mul_f32_e32 v111, v110, v109
	v_fma_f32 v112, -v108, v111, v110
	v_fmac_f32_e32 v111, v112, v109
	v_fma_f32 v108, -v108, v111, v110
	v_div_fmas_f32 v108, v108, v109, v111
	v_div_fixup_f32 v114, v108, v114, 1.0
	v_mul_f32_e32 v92, v114, v92
	v_div_scale_f32 v108, s[22:23], v115, v115, 1.0
	v_rcp_f32_e32 v109, v108
	s_nop 0
	v_fma_f32 v110, -v108, v109, 1.0
	v_fmac_f32_e32 v109, v110, v109
	v_div_scale_f32 v110, vcc, 1.0, v115, 1.0
	v_mul_f32_e32 v111, v110, v109
	v_fma_f32 v112, -v108, v111, v110
	v_fmac_f32_e32 v111, v112, v109
	v_fma_f32 v108, -v108, v111, v110
	v_div_fmas_f32 v108, v108, v109, v111
	v_div_fixup_f32 v115, v108, v115, 1.0
	v_mul_f32_e32 v93, v115, v93
	v_div_scale_f32 v108, s[22:23], v116, v116, 1.0
	v_rcp_f32_e32 v109, v108
	s_nop 0
	v_fma_f32 v110, -v108, v109, 1.0
	v_fmac_f32_e32 v109, v110, v109
	v_div_scale_f32 v110, vcc, 1.0, v116, 1.0
	v_mul_f32_e32 v111, v110, v109
	v_fma_f32 v112, -v108, v111, v110
	v_fmac_f32_e32 v111, v112, v109
	v_fma_f32 v108, -v108, v111, v110
	v_div_fmas_f32 v108, v108, v109, v111
	v_div_fixup_f32 v116, v108, v116, 1.0
	v_mul_f32_e32 v94, v116, v94
	v_div_scale_f32 v108, s[22:23], v117, v117, 1.0
	v_rcp_f32_e32 v109, v108
	s_nop 0
	v_fma_f32 v110, -v108, v109, 1.0
	v_fmac_f32_e32 v109, v110, v109
	v_div_scale_f32 v110, vcc, 1.0, v117, 1.0
	v_mul_f32_e32 v111, v110, v109
	v_fma_f32 v112, -v108, v111, v110
	v_fmac_f32_e32 v111, v112, v109
	v_fma_f32 v108, -v108, v111, v110
	v_div_fmas_f32 v108, v108, v109, v111
	v_div_fixup_f32 v117, v108, v117, 1.0
	v_mul_f32_e32 v95, v117, v95
	v_pk_mul_f32 v[108:109], v[80:81], v[80:81]
	v_pk_fma_f32 v[108:109], v[82:83], v[82:83], v[108:109]
	v_add_f32_e32 v96, v108, v109
	v_pk_mul_f32 v[110:111], v[84:85], v[84:85]
	v_pk_fma_f32 v[110:111], v[86:87], v[86:87], v[110:111]
	v_add_f32_e32 v97, v110, v111
	v_pk_mul_f32 v[108:109], v[88:89], v[88:89]
	v_pk_fma_f32 v[108:109], v[90:91], v[90:91], v[108:109]
	v_add_f32_e32 v98, v108, v109
	v_pk_mul_f32 v[110:111], v[92:93], v[92:93]
	v_pk_fma_f32 v[110:111], v[94:95], v[94:95], v[110:111]
	v_add_f32_e32 v99, v110, v111
	v_add_f32_dpp v96, v96, v96 row_ror:8 row_mask:0xf bank_mask:0xf
	s_nop 0
	v_add_f32_dpp v97, v97, v97 row_ror:8 row_mask:0xf bank_mask:0xf
	s_nop 0
	v_add_f32_dpp v96, v96, v96 row_ror:4 row_mask:0xf bank_mask:0xf
	s_nop 0
	v_add_f32_dpp v97, v97, v97 row_ror:4 row_mask:0xf bank_mask:0xf
	s_nop 0
	v_add_f32_dpp v96, v96, v96 row_ror:2 row_mask:0xf bank_mask:0xf
	s_nop 0
	v_add_f32_dpp v97, v97, v97 row_ror:2 row_mask:0xf bank_mask:0xf
	s_nop 0
	v_add_f32_dpp v96, v96, v96 row_ror:1 row_mask:0xf bank_mask:0xf
	s_nop 0
	v_add_f32_dpp v97, v97, v97 row_ror:1 row_mask:0xf bank_mask:0xf
	s_nop 0
	v_readlane_b32 s0, v96, 0
	v_readlane_b32 s1, v96, 16
	v_readlane_b32 s18, v96, 32
	v_readlane_b32 s19, v96, 48
	v_readlane_b32 s20, v97, 0
	v_readlane_b32 s21, v97, 16
	v_readlane_b32 s22, v97, 32
	v_readlane_b32 s23, v97, 48
	s_nop 1
	v_mov_b32_e32 v100, s0
	v_mov_b32_e32 v102, s20
	v_add_f32_e32 v100, s1, v100
	v_add_f32_e32 v102, s21, v102
	v_add_f32_e32 v100, s18, v100
	v_add_f32_e32 v102, s22, v102
	v_add_f32_e32 v100, s19, v100
	v_add_f32_e32 v102, s23, v102
	v_add_f32_dpp v98, v98, v98 row_ror:8 row_mask:0xf bank_mask:0xf
	s_nop 0
	v_add_f32_dpp v99, v99, v99 row_ror:8 row_mask:0xf bank_mask:0xf
	s_nop 0
	v_add_f32_dpp v98, v98, v98 row_ror:4 row_mask:0xf bank_mask:0xf
	s_nop 0
	v_add_f32_dpp v99, v99, v99 row_ror:4 row_mask:0xf bank_mask:0xf
	s_nop 0
	v_add_f32_dpp v98, v98, v98 row_ror:2 row_mask:0xf bank_mask:0xf
	s_nop 0
	v_add_f32_dpp v99, v99, v99 row_ror:2 row_mask:0xf bank_mask:0xf
	s_nop 0
	v_add_f32_dpp v98, v98, v98 row_ror:1 row_mask:0xf bank_mask:0xf
	s_nop 0
	v_add_f32_dpp v99, v99, v99 row_ror:1 row_mask:0xf bank_mask:0xf
	s_nop 0
	v_readlane_b32 s0, v98, 0
	v_readlane_b32 s1, v98, 16
	v_readlane_b32 s18, v98, 32
	v_readlane_b32 s19, v98, 48
	v_readlane_b32 s20, v99, 0
	v_readlane_b32 s21, v99, 16
	v_readlane_b32 s22, v99, 32
	v_readlane_b32 s23, v99, 48
	s_nop 1
	v_mov_b32_e32 v104, s0
	v_mov_b32_e32 v106, s20
	v_add_f32_e32 v104, s1, v104
	v_add_f32_e32 v106, s21, v106
	v_add_f32_e32 v104, s18, v104
	v_add_f32_e32 v106, s22, v106
	v_add_f32_e32 v104, s19, v104
	v_add_f32_e32 v106, s23, v106
	v_fmamk_f32 v100, v100, 0x3b800000, v197
	v_fmamk_f32 v102, v102, 0x3b800000, v197
	v_fmamk_f32 v104, v104, 0x3b800000, v197
	v_fmamk_f32 v106, v106, 0x3b800000, v197
	v_rsq_f32_e32 v100, v100
	v_rsq_f32_e32 v102, v102
	v_rsq_f32_e32 v104, v104
	v_rsq_f32_e32 v106, v106
	s_nop 0
	v_pk_mul_f32 v[80:81], v[100:101], v[80:81] op_sel_hi:[0,1]
	v_pk_mul_f32 v[82:83], v[100:101], v[82:83] op_sel_hi:[0,1]
	v_pk_mul_f32 v[84:85], v[102:103], v[84:85] op_sel_hi:[0,1]
	v_pk_mul_f32 v[86:87], v[102:103], v[86:87] op_sel_hi:[0,1]
	v_pk_mul_f32 v[88:89], v[104:105], v[88:89] op_sel_hi:[0,1]
	v_pk_mul_f32 v[90:91], v[104:105], v[90:91] op_sel_hi:[0,1]
	v_pk_mul_f32 v[92:93], v[106:107], v[92:93] op_sel_hi:[0,1]
	v_pk_mul_f32 v[94:95], v[106:107], v[94:95] op_sel_hi:[0,1]
	v_pk_mul_f32 v[80:81], v[2:3], v[80:81]
	v_pk_mul_f32 v[82:83], v[4:5], v[82:83]
	v_pk_mul_f32 v[84:85], v[6:7], v[84:85]
	v_pk_mul_f32 v[86:87], v[8:9], v[86:87]
	v_pk_mul_f32 v[88:89], v[10:11], v[88:89]
	v_pk_mul_f32 v[90:91], v[12:13], v[90:91]
	v_pk_mul_f32 v[92:93], v[14:15], v[92:93]
	v_pk_mul_f32 v[94:95], v[16:17], v[94:95]
	v_cvt_pk_bf16_f32 v38, v80, v81
	v_cvt_pk_bf16_f32 v39, v82, v83
	v_cvt_pk_bf16_f32 v40, v84, v85
	v_cvt_pk_bf16_f32 v41, v86, v87
	v_cvt_pk_bf16_f32 v42, v88, v89
	v_cvt_pk_bf16_f32 v43, v90, v91
	v_cvt_pk_bf16_f32 v44, v92, v93
	v_cvt_pk_bf16_f32 v45, v94, v95
	global_store_dwordx2 v1, v[38:39], s[10:11] offset:0
	global_store_dwordx2 v1, v[40:41], s[10:11] offset:512
	global_store_dwordx2 v1, v[42:43], s[10:11] offset:1024
	global_store_dwordx2 v1, v[44:45], s[10:11] offset:1536
	s_branch .Lrn_gn_end
.Lrn_gn_noctx:
	global_load_dwordx2 v[18:19], v1, s[6:7] offset:0
	global_load_dwordx2 v[20:21], v1, s[6:7] offset:512
	global_load_dwordx2 v[22:23], v1, s[6:7] offset:1024
	global_load_dwordx2 v[24:25], v1, s[8:9]
	global_load_dwordx2 v[26:27], v1, s[8:9] offset:512
	s_add_u32 s6, s6, 0x600
	s_addc_u32 s7, s7, 0
	s_add_u32 s8, s8, 0x400
	s_addc_u32 s9, s9, 0
	global_load_dwordx2 v[28:29], v1, s[6:7] offset:0
	global_load_dwordx2 v[30:31], v1, s[6:7] offset:512
	global_load_dwordx2 v[32:33], v1, s[6:7] offset:1024
	global_load_dwordx2 v[34:35], v1, s[8:9]
	global_load_dwordx2 v[36:37], v1, s[8:9] offset:512
	s_add_u32 s6, s6, 0x600
	s_addc_u32 s7, s7, 0
	s_add_u32 s8, s8, 0x400
	s_addc_u32 s9, s9, 0
	global_load_dwordx2 v[38:39], v1, s[6:7] offset:0
	global_load_dwordx2 v[40:41], v1, s[6:7] offset:512
	global_load_dwordx2 v[42:43], v1, s[6:7] offset:1024
	global_load_dwordx2 v[44:45], v1, s[8:9]
	global_load_dwordx2 v[46:47], v1, s[8:9] offset:512
	s_add_u32 s6, s6, 0x600
	s_addc_u32 s7, s7, 0
	s_add_u32 s8, s8, 0x400
	s_addc_u32 s9, s9, 0
	global_load_dwordx2 v[48:49], v1, s[6:7] offset:0
	global_load_dwordx2 v[50:51], v1, s[6:7] offset:512
	global_load_dwordx2 v[52:53], v1, s[6:7] offset:1024
	global_load_dwordx2 v[54:55], v1, s[8:9]
	global_load_dwordx2 v[56:57], v1, s[8:9] offset:512
	s_add_u32 s6, s6, 0x600
	s_addc_u32 s7, s7, 0
	s_add_u32 s8, s8, 0x400
	s_addc_u32 s9, s9, 0
	global_load_dwordx2 v[58:59], v1, s[6:7] offset:0
	global_load_dwordx2 v[60:61], v1, s[6:7] offset:512
	global_load_dwordx2 v[62:63], v1, s[6:7] offset:1024
	global_load_dwordx2 v[64:65], v1, s[8:9]
	global_load_dwordx2 v[66:67], v1, s[8:9] offset:512
	s_add_u32 s6, s6, 0x600
	s_addc_u32 s7, s7, 0
	s_add_u32 s8, s8, 0x400
	s_addc_u32 s9, s9, 0
	global_load_dwordx2 v[68:69], v1, s[6:7] offset:0
	global_load_dwordx2 v[70:71], v1, s[6:7] offset:512
	global_load_dwordx2 v[72:73], v1, s[6:7] offset:1024
	global_load_dwordx2 v[74:75], v1, s[8:9]
	global_load_dwordx2 v[76:77], v1, s[8:9] offset:512
	s_add_u32 s6, s6, 0x600
	s_addc_u32 s7, s7, 0
	s_add_u32 s8, s8, 0x400
	s_addc_u32 s9, s9, 0
	s_waitcnt vmcnt(25)
	v_lshlrev_b32_e32 v80, 16, v18
	v_and_b32_e32 v81, 0xffff0000, v18
	v_lshlrev_b32_e32 v82, 16, v19
	v_and_b32_e32 v83, 0xffff0000, v19
	v_lshlrev_b32_e32 v84, 16, v20
	v_and_b32_e32 v85, 0xffff0000, v20
	v_lshlrev_b32_e32 v86, 16, v21
	v_and_b32_e32 v87, 0xffff0000, v21
	v_lshlrev_b32_e32 v88, 16, v22
	v_and_b32_e32 v89, 0xffff0000, v22
	v_lshlrev_b32_e32 v90, 16, v23
	v_and_b32_e32 v91, 0xffff0000, v23
	v_lshlrev_b32_e32 v92, 16, v24
	v_and_b32_e32 v93, 0xffff0000, v24
	v_lshlrev_b32_e32 v94, 16, v25
	v_and_b32_e32 v95, 0xffff0000, v25
	v_lshlrev_b32_e32 v114, 16, v26
	v_and_b32_e32 v115, 0xffff0000, v26
	v_lshlrev_b32_e32 v116, 16, v27
	v_and_b32_e32 v117, 0xffff0000, v27
	v_mul_f32_e32 v114, 0xbfb8aa3b, v114
	v_mul_f32_e32 v115, 0xbfb8aa3b, v115
	v_mul_f32_e32 v116, 0xbfb8aa3b, v116
	v_mul_f32_e32 v117, 0xbfb8aa3b, v117
	v_exp_f32_e32 v114, v114
	v_exp_f32_e32 v115, v115
	v_exp_f32_e32 v116, v116
	v_exp_f32_e32 v117, v117
	s_nop 0
	v_add_f32_e32 v114, 1.0, v114
	v_add_f32_e32 v115, 1.0, v115
	v_add_f32_e32 v116, 1.0, v116
	v_add_f32_e32 v117, 1.0, v117
	v_div_scale_f32 v108, s[22:23], v114, v114, 1.0
	v_rcp_f32_e32 v109, v108
	s_nop 0
	v_fma_f32 v110, -v108, v109, 1.0
	v_fmac_f32_e32 v109, v110, v109
	v_div_scale_f32 v110, vcc, 1.0, v114, 1.0
	v_mul_f32_e32 v111, v110, v109
	v_fma_f32 v112, -v108, v111, v110
	v_fmac_f32_e32 v111, v112, v109
	v_fma_f32 v108, -v108, v111, v110
	v_div_fmas_f32 v108, v108, v109, v111
	v_div_fixup_f32 v114, v108, v114, 1.0
	v_mul_f32_e32 v92, v114, v92
	v_div_scale_f32 v108, s[22:23], v115, v115, 1.0
	v_rcp_f32_e32 v109, v108
	s_nop 0
	v_fma_f32 v110, -v108, v109, 1.0
	v_fmac_f32_e32 v109, v110, v109
	v_div_scale_f32 v110, vcc, 1.0, v115, 1.0
	v_mul_f32_e32 v111, v110, v109
	v_fma_f32 v112, -v108, v111, v110
	v_fmac_f32_e32 v111, v112, v109
	v_fma_f32 v108, -v108, v111, v110
	v_div_fmas_f32 v108, v108, v109, v111
	v_div_fixup_f32 v115, v108, v115, 1.0
	v_mul_f32_e32 v93, v115, v93
	v_div_scale_f32 v108, s[22:23], v116, v116, 1.0
	v_rcp_f32_e32 v109, v108
	s_nop 0
	v_fma_f32 v110, -v108, v109, 1.0
	v_fmac_f32_e32 v109, v110, v109
	v_div_scale_f32 v110, vcc, 1.0, v116, 1.0
	v_mul_f32_e32 v111, v110, v109
	v_fma_f32 v112, -v108, v111, v110
	v_fmac_f32_e32 v111, v112, v109
	v_fma_f32 v108, -v108, v111, v110
	v_div_fmas_f32 v108, v108, v109, v111
	v_div_fixup_f32 v116, v108, v116, 1.0
	v_mul_f32_e32 v94, v116, v94
	v_div_scale_f32 v108, s[22:23], v117, v117, 1.0
	v_rcp_f32_e32 v109, v108
	s_nop 0
	v_fma_f32 v110, -v108, v109, 1.0
	v_fmac_f32_e32 v109, v110, v109
	v_div_scale_f32 v110, vcc, 1.0, v117, 1.0
	v_mul_f32_e32 v111, v110, v109
	v_fma_f32 v112, -v108, v111, v110
	v_fmac_f32_e32 v111, v112, v109
	v_fma_f32 v108, -v108, v111, v110
	v_div_fmas_f32 v108, v108, v109, v111
	v_div_fixup_f32 v117, v108, v117, 1.0
	v_mul_f32_e32 v95, v117, v95
	v_pk_mul_f32 v[108:109], v[80:81], v[80:81]
	v_pk_fma_f32 v[108:109], v[82:83], v[82:83], v[108:109]
	v_add_f32_e32 v96, v108, v109
	v_pk_mul_f32 v[110:111], v[84:85], v[84:85]
	v_pk_fma_f32 v[110:111], v[86:87], v[86:87], v[110:111]
	v_add_f32_e32 v97, v110, v111
	v_pk_mul_f32 v[108:109], v[88:89], v[88:89]
	v_pk_fma_f32 v[108:109], v[90:91], v[90:91], v[108:109]
	v_add_f32_e32 v98, v108, v109
	v_pk_mul_f32 v[110:111], v[92:93], v[92:93]
	v_pk_fma_f32 v[110:111], v[94:95], v[94:95], v[110:111]
	v_add_f32_e32 v99, v110, v111
	v_add_f32_dpp v96, v96, v96 row_ror:8 row_mask:0xf bank_mask:0xf
	s_nop 0
	v_add_f32_dpp v97, v97, v97 row_ror:8 row_mask:0xf bank_mask:0xf
	s_nop 0
	v_add_f32_dpp v96, v96, v96 row_ror:4 row_mask:0xf bank_mask:0xf
	s_nop 0
	v_add_f32_dpp v97, v97, v97 row_ror:4 row_mask:0xf bank_mask:0xf
	s_nop 0
	v_add_f32_dpp v96, v96, v96 row_ror:2 row_mask:0xf bank_mask:0xf
	s_nop 0
	v_add_f32_dpp v97, v97, v97 row_ror:2 row_mask:0xf bank_mask:0xf
	s_nop 0
	v_add_f32_dpp v96, v96, v96 row_ror:1 row_mask:0xf bank_mask:0xf
	s_nop 0
	v_add_f32_dpp v97, v97, v97 row_ror:1 row_mask:0xf bank_mask:0xf
	s_nop 0
	v_readlane_b32 s0, v96, 0
	v_readlane_b32 s1, v96, 16
	v_readlane_b32 s18, v96, 32
	v_readlane_b32 s19, v96, 48
	v_readlane_b32 s20, v97, 0
	v_readlane_b32 s21, v97, 16
	v_readlane_b32 s22, v97, 32
	v_readlane_b32 s23, v97, 48
	s_nop 1
	v_mov_b32_e32 v100, s0
	v_mov_b32_e32 v102, s20
	v_add_f32_e32 v100, s1, v100
	v_add_f32_e32 v102, s21, v102
	v_add_f32_e32 v100, s18, v100
	v_add_f32_e32 v102, s22, v102
	v_add_f32_e32 v100, s19, v100
	v_add_f32_e32 v102, s23, v102
	v_add_f32_dpp v98, v98, v98 row_ror:8 row_mask:0xf bank_mask:0xf
	s_nop 0
	v_add_f32_dpp v99, v99, v99 row_ror:8 row_mask:0xf bank_mask:0xf
	s_nop 0
	v_add_f32_dpp v98, v98, v98 row_ror:4 row_mask:0xf bank_mask:0xf
	s_nop 0
	v_add_f32_dpp v99, v99, v99 row_ror:4 row_mask:0xf bank_mask:0xf
	s_nop 0
	v_add_f32_dpp v98, v98, v98 row_ror:2 row_mask:0xf bank_mask:0xf
	s_nop 0
	v_add_f32_dpp v99, v99, v99 row_ror:2 row_mask:0xf bank_mask:0xf
	s_nop 0
	v_add_f32_dpp v98, v98, v98 row_ror:1 row_mask:0xf bank_mask:0xf
	s_nop 0
	v_add_f32_dpp v99, v99, v99 row_ror:1 row_mask:0xf bank_mask:0xf
	s_nop 0
	v_readlane_b32 s0, v98, 0
	v_readlane_b32 s1, v98, 16
	v_readlane_b32 s18, v98, 32
	v_readlane_b32 s19, v98, 48
	v_readlane_b32 s20, v99, 0
	v_readlane_b32 s21, v99, 16
	v_readlane_b32 s22, v99, 32
	v_readlane_b32 s23, v99, 48
	s_nop 1
	v_mov_b32_e32 v104, s0
	v_mov_b32_e32 v106, s20
	v_add_f32_e32 v104, s1, v104
	v_add_f32_e32 v106, s21, v106
	v_add_f32_e32 v104, s18, v104
	v_add_f32_e32 v106, s22, v106
	v_add_f32_e32 v104, s19, v104
	v_add_f32_e32 v106, s23, v106
	v_fmamk_f32 v100, v100, 0x3b800000, v197
	v_fmamk_f32 v102, v102, 0x3b800000, v197
	v_fmamk_f32 v104, v104, 0x3b800000, v197
	v_fmamk_f32 v106, v106, 0x3b800000, v197
	v_rsq_f32_e32 v100, v100
	v_rsq_f32_e32 v102, v102
	v_rsq_f32_e32 v104, v104
	v_rsq_f32_e32 v106, v106
	s_nop 0
	v_pk_mul_f32 v[80:81], v[100:101], v[80:81] op_sel_hi:[0,1]
	v_pk_mul_f32 v[82:83], v[100:101], v[82:83] op_sel_hi:[0,1]
	v_pk_mul_f32 v[84:85], v[102:103], v[84:85] op_sel_hi:[0,1]
	v_pk_mul_f32 v[86:87], v[102:103], v[86:87] op_sel_hi:[0,1]
	v_pk_mul_f32 v[88:89], v[104:105], v[88:89] op_sel_hi:[0,1]
	v_pk_mul_f32 v[90:91], v[104:105], v[90:91] op_sel_hi:[0,1]
	v_pk_mul_f32 v[92:93], v[106:107], v[92:93] op_sel_hi:[0,1]
	v_pk_mul_f32 v[94:95], v[106:107], v[94:95] op_sel_hi:[0,1]
	v_pk_mul_f32 v[80:81], v[2:3], v[80:81]
	v_pk_mul_f32 v[82:83], v[4:5], v[82:83]
	v_pk_mul_f32 v[84:85], v[6:7], v[84:85]
	v_pk_mul_f32 v[86:87], v[8:9], v[86:87]
	v_pk_mul_f32 v[88:89], v[10:11], v[88:89]
	v_pk_mul_f32 v[90:91], v[12:13], v[90:91]
	v_pk_mul_f32 v[92:93], v[14:15], v[92:93]
	v_pk_mul_f32 v[94:95], v[16:17], v[94:95]
	v_cvt_pk_bf16_f32 v18, v80, v81
	v_cvt_pk_bf16_f32 v19, v82, v83
	v_cvt_pk_bf16_f32 v20, v84, v85
	v_cvt_pk_bf16_f32 v21, v86, v87
	v_cvt_pk_bf16_f32 v22, v88, v89
	v_cvt_pk_bf16_f32 v23, v90, v91
	v_cvt_pk_bf16_f32 v24, v92, v93
	v_cvt_pk_bf16_f32 v25, v94, v95
	global_store_dwordx2 v1, v[18:19], s[10:11] offset:0
	global_store_dwordx2 v1, v[20:21], s[10:11] offset:512
	global_store_dwordx2 v1, v[22:23], s[10:11] offset:1024
	global_store_dwordx2 v1, v[24:25], s[10:11] offset:1536
	s_add_u32 s10, s10, 0x800
	s_addc_u32 s11, s11, 0
	global_load_dwordx2 v[18:19], v1, s[6:7] offset:0
	global_load_dwordx2 v[20:21], v1, s[6:7] offset:512
	global_load_dwordx2 v[22:23], v1, s[6:7] offset:1024
	global_load_dwordx2 v[24:25], v1, s[8:9]
	global_load_dwordx2 v[26:27], v1, s[8:9] offset:512
	s_add_u32 s6, s6, 0x600
	s_addc_u32 s7, s7, 0
	s_add_u32 s8, s8, 0x400
	s_addc_u32 s9, s9, 0
	s_waitcnt vmcnt(29)
	v_lshlrev_b32_e32 v80, 16, v28
	v_and_b32_e32 v81, 0xffff0000, v28
	v_lshlrev_b32_e32 v82, 16, v29
	v_and_b32_e32 v83, 0xffff0000, v29
	v_lshlrev_b32_e32 v84, 16, v30
	v_and_b32_e32 v85, 0xffff0000, v30
	v_lshlrev_b32_e32 v86, 16, v31
	v_and_b32_e32 v87, 0xffff0000, v31
	v_lshlrev_b32_e32 v88, 16, v32
	v_and_b32_e32 v89, 0xffff0000, v32
	v_lshlrev_b32_e32 v90, 16, v33
	v_and_b32_e32 v91, 0xffff0000, v33
	v_lshlrev_b32_e32 v92, 16, v34
	v_and_b32_e32 v93, 0xffff0000, v34
	v_lshlrev_b32_e32 v94, 16, v35
	v_and_b32_e32 v95, 0xffff0000, v35
	v_lshlrev_b32_e32 v114, 16, v36
	v_and_b32_e32 v115, 0xffff0000, v36
	v_lshlrev_b32_e32 v116, 16, v37
	v_and_b32_e32 v117, 0xffff0000, v37
	v_mul_f32_e32 v114, 0xbfb8aa3b, v114
	v_mul_f32_e32 v115, 0xbfb8aa3b, v115
	v_mul_f32_e32 v116, 0xbfb8aa3b, v116
	v_mul_f32_e32 v117, 0xbfb8aa3b, v117
	v_exp_f32_e32 v114, v114
	v_exp_f32_e32 v115, v115
	v_exp_f32_e32 v116, v116
	v_exp_f32_e32 v117, v117
	s_nop 0
	v_add_f32_e32 v114, 1.0, v114
	v_add_f32_e32 v115, 1.0, v115
	v_add_f32_e32 v116, 1.0, v116
	v_add_f32_e32 v117, 1.0, v117
	v_div_scale_f32 v108, s[22:23], v114, v114, 1.0
	v_rcp_f32_e32 v109, v108
	s_nop 0
	v_fma_f32 v110, -v108, v109, 1.0
	v_fmac_f32_e32 v109, v110, v109
	v_div_scale_f32 v110, vcc, 1.0, v114, 1.0
	v_mul_f32_e32 v111, v110, v109
	v_fma_f32 v112, -v108, v111, v110
	v_fmac_f32_e32 v111, v112, v109
	v_fma_f32 v108, -v108, v111, v110
	v_div_fmas_f32 v108, v108, v109, v111
	v_div_fixup_f32 v114, v108, v114, 1.0
	v_mul_f32_e32 v92, v114, v92
	v_div_scale_f32 v108, s[22:23], v115, v115, 1.0
	v_rcp_f32_e32 v109, v108
	s_nop 0
	v_fma_f32 v110, -v108, v109, 1.0
	v_fmac_f32_e32 v109, v110, v109
	v_div_scale_f32 v110, vcc, 1.0, v115, 1.0
	v_mul_f32_e32 v111, v110, v109
	v_fma_f32 v112, -v108, v111, v110
	v_fmac_f32_e32 v111, v112, v109
	v_fma_f32 v108, -v108, v111, v110
	v_div_fmas_f32 v108, v108, v109, v111
	v_div_fixup_f32 v115, v108, v115, 1.0
	v_mul_f32_e32 v93, v115, v93
	v_div_scale_f32 v108, s[22:23], v116, v116, 1.0
	v_rcp_f32_e32 v109, v108
	s_nop 0
	v_fma_f32 v110, -v108, v109, 1.0
	v_fmac_f32_e32 v109, v110, v109
	v_div_scale_f32 v110, vcc, 1.0, v116, 1.0
	v_mul_f32_e32 v111, v110, v109
	v_fma_f32 v112, -v108, v111, v110
	v_fmac_f32_e32 v111, v112, v109
	v_fma_f32 v108, -v108, v111, v110
	v_div_fmas_f32 v108, v108, v109, v111
	v_div_fixup_f32 v116, v108, v116, 1.0
	v_mul_f32_e32 v94, v116, v94
	v_div_scale_f32 v108, s[22:23], v117, v117, 1.0
	v_rcp_f32_e32 v109, v108
	s_nop 0
	v_fma_f32 v110, -v108, v109, 1.0
	v_fmac_f32_e32 v109, v110, v109
	v_div_scale_f32 v110, vcc, 1.0, v117, 1.0
	v_mul_f32_e32 v111, v110, v109
	v_fma_f32 v112, -v108, v111, v110
	v_fmac_f32_e32 v111, v112, v109
	v_fma_f32 v108, -v108, v111, v110
	v_div_fmas_f32 v108, v108, v109, v111
	v_div_fixup_f32 v117, v108, v117, 1.0
	v_mul_f32_e32 v95, v117, v95
	v_pk_mul_f32 v[108:109], v[80:81], v[80:81]
	v_pk_fma_f32 v[108:109], v[82:83], v[82:83], v[108:109]
	v_add_f32_e32 v96, v108, v109
	v_pk_mul_f32 v[110:111], v[84:85], v[84:85]
	v_pk_fma_f32 v[110:111], v[86:87], v[86:87], v[110:111]
	v_add_f32_e32 v97, v110, v111
	v_pk_mul_f32 v[108:109], v[88:89], v[88:89]
	v_pk_fma_f32 v[108:109], v[90:91], v[90:91], v[108:109]
	v_add_f32_e32 v98, v108, v109
	v_pk_mul_f32 v[110:111], v[92:93], v[92:93]
	v_pk_fma_f32 v[110:111], v[94:95], v[94:95], v[110:111]
	v_add_f32_e32 v99, v110, v111
	v_add_f32_dpp v96, v96, v96 row_ror:8 row_mask:0xf bank_mask:0xf
	s_nop 0
	v_add_f32_dpp v97, v97, v97 row_ror:8 row_mask:0xf bank_mask:0xf
	s_nop 0
	v_add_f32_dpp v96, v96, v96 row_ror:4 row_mask:0xf bank_mask:0xf
	s_nop 0
	v_add_f32_dpp v97, v97, v97 row_ror:4 row_mask:0xf bank_mask:0xf
	s_nop 0
	v_add_f32_dpp v96, v96, v96 row_ror:2 row_mask:0xf bank_mask:0xf
	s_nop 0
	v_add_f32_dpp v97, v97, v97 row_ror:2 row_mask:0xf bank_mask:0xf
	s_nop 0
	v_add_f32_dpp v96, v96, v96 row_ror:1 row_mask:0xf bank_mask:0xf
	s_nop 0
	v_add_f32_dpp v97, v97, v97 row_ror:1 row_mask:0xf bank_mask:0xf
	s_nop 0
	v_readlane_b32 s0, v96, 0
	v_readlane_b32 s1, v96, 16
	v_readlane_b32 s18, v96, 32
	v_readlane_b32 s19, v96, 48
	v_readlane_b32 s20, v97, 0
	v_readlane_b32 s21, v97, 16
	v_readlane_b32 s22, v97, 32
	v_readlane_b32 s23, v97, 48
	s_nop 1
	v_mov_b32_e32 v100, s0
	v_mov_b32_e32 v102, s20
	v_add_f32_e32 v100, s1, v100
	v_add_f32_e32 v102, s21, v102
	v_add_f32_e32 v100, s18, v100
	v_add_f32_e32 v102, s22, v102
	v_add_f32_e32 v100, s19, v100
	v_add_f32_e32 v102, s23, v102
	v_add_f32_dpp v98, v98, v98 row_ror:8 row_mask:0xf bank_mask:0xf
	s_nop 0
	v_add_f32_dpp v99, v99, v99 row_ror:8 row_mask:0xf bank_mask:0xf
	s_nop 0
	v_add_f32_dpp v98, v98, v98 row_ror:4 row_mask:0xf bank_mask:0xf
	s_nop 0
	v_add_f32_dpp v99, v99, v99 row_ror:4 row_mask:0xf bank_mask:0xf
	s_nop 0
	v_add_f32_dpp v98, v98, v98 row_ror:2 row_mask:0xf bank_mask:0xf
	s_nop 0
	v_add_f32_dpp v99, v99, v99 row_ror:2 row_mask:0xf bank_mask:0xf
	s_nop 0
	v_add_f32_dpp v98, v98, v98 row_ror:1 row_mask:0xf bank_mask:0xf
	s_nop 0
	v_add_f32_dpp v99, v99, v99 row_ror:1 row_mask:0xf bank_mask:0xf
	s_nop 0
	v_readlane_b32 s0, v98, 0
	v_readlane_b32 s1, v98, 16
	v_readlane_b32 s18, v98, 32
	v_readlane_b32 s19, v98, 48
	v_readlane_b32 s20, v99, 0
	v_readlane_b32 s21, v99, 16
	v_readlane_b32 s22, v99, 32
	v_readlane_b32 s23, v99, 48
	s_nop 1
	v_mov_b32_e32 v104, s0
	v_mov_b32_e32 v106, s20
	v_add_f32_e32 v104, s1, v104
	v_add_f32_e32 v106, s21, v106
	v_add_f32_e32 v104, s18, v104
	v_add_f32_e32 v106, s22, v106
	v_add_f32_e32 v104, s19, v104
	v_add_f32_e32 v106, s23, v106
	v_fmamk_f32 v100, v100, 0x3b800000, v197
	v_fmamk_f32 v102, v102, 0x3b800000, v197
	v_fmamk_f32 v104, v104, 0x3b800000, v197
	v_fmamk_f32 v106, v106, 0x3b800000, v197
	v_rsq_f32_e32 v100, v100
	v_rsq_f32_e32 v102, v102
	v_rsq_f32_e32 v104, v104
	v_rsq_f32_e32 v106, v106
	s_nop 0
	v_pk_mul_f32 v[80:81], v[100:101], v[80:81] op_sel_hi:[0,1]
	v_pk_mul_f32 v[82:83], v[100:101], v[82:83] op_sel_hi:[0,1]
	v_pk_mul_f32 v[84:85], v[102:103], v[84:85] op_sel_hi:[0,1]
	v_pk_mul_f32 v[86:87], v[102:103], v[86:87] op_sel_hi:[0,1]
	v_pk_mul_f32 v[88:89], v[104:105], v[88:89] op_sel_hi:[0,1]
	v_pk_mul_f32 v[90:91], v[104:105], v[90:91] op_sel_hi:[0,1]
	v_pk_mul_f32 v[92:93], v[106:107], v[92:93] op_sel_hi:[0,1]
	v_pk_mul_f32 v[94:95], v[106:107], v[94:95] op_sel_hi:[0,1]
	v_pk_mul_f32 v[80:81], v[2:3], v[80:81]
	v_pk_mul_f32 v[82:83], v[4:5], v[82:83]
	v_pk_mul_f32 v[84:85], v[6:7], v[84:85]
	v_pk_mul_f32 v[86:87], v[8:9], v[86:87]
	v_pk_mul_f32 v[88:89], v[10:11], v[88:89]
	v_pk_mul_f32 v[90:91], v[12:13], v[90:91]
	v_pk_mul_f32 v[92:93], v[14:15], v[92:93]
	v_pk_mul_f32 v[94:95], v[16:17], v[94:95]
	v_cvt_pk_bf16_f32 v28, v80, v81
	v_cvt_pk_bf16_f32 v29, v82, v83
	v_cvt_pk_bf16_f32 v30, v84, v85
	v_cvt_pk_bf16_f32 v31, v86, v87
	v_cvt_pk_bf16_f32 v32, v88, v89
	v_cvt_pk_bf16_f32 v33, v90, v91
	v_cvt_pk_bf16_f32 v34, v92, v93
	v_cvt_pk_bf16_f32 v35, v94, v95
	global_store_dwordx2 v1, v[28:29], s[10:11] offset:0
	global_store_dwordx2 v1, v[30:31], s[10:11] offset:512
	global_store_dwordx2 v1, v[32:33], s[10:11] offset:1024
	global_store_dwordx2 v1, v[34:35], s[10:11] offset:1536
	s_add_u32 s10, s10, 0x800
	s_addc_u32 s11, s11, 0
	global_load_dwordx2 v[28:29], v1, s[6:7] offset:0
	global_load_dwordx2 v[30:31], v1, s[6:7] offset:512
	global_load_dwordx2 v[32:33], v1, s[6:7] offset:1024
	global_load_dwordx2 v[34:35], v1, s[8:9]
	global_load_dwordx2 v[36:37], v1, s[8:9] offset:512
	s_waitcnt vmcnt(33)
	v_lshlrev_b32_e32 v80, 16, v38
	v_and_b32_e32 v81, 0xffff0000, v38
	v_lshlrev_b32_e32 v82, 16, v39
	v_and_b32_e32 v83, 0xffff0000, v39
	v_lshlrev_b32_e32 v84, 16, v40
	v_and_b32_e32 v85, 0xffff0000, v40
	v_lshlrev_b32_e32 v86, 16, v41
	v_and_b32_e32 v87, 0xffff0000, v41
	v_lshlrev_b32_e32 v88, 16, v42
	v_and_b32_e32 v89, 0xffff0000, v42
	v_lshlrev_b32_e32 v90, 16, v43
	v_and_b32_e32 v91, 0xffff0000, v43
	v_lshlrev_b32_e32 v92, 16, v44
	v_and_b32_e32 v93, 0xffff0000, v44
	v_lshlrev_b32_e32 v94, 16, v45
	v_and_b32_e32 v95, 0xffff0000, v45
	v_lshlrev_b32_e32 v114, 16, v46
	v_and_b32_e32 v115, 0xffff0000, v46
	v_lshlrev_b32_e32 v116, 16, v47
	v_and_b32_e32 v117, 0xffff0000, v47
	v_mul_f32_e32 v114, 0xbfb8aa3b, v114
	v_mul_f32_e32 v115, 0xbfb8aa3b, v115
	v_mul_f32_e32 v116, 0xbfb8aa3b, v116
	v_mul_f32_e32 v117, 0xbfb8aa3b, v117
	v_exp_f32_e32 v114, v114
	v_exp_f32_e32 v115, v115
	v_exp_f32_e32 v116, v116
	v_exp_f32_e32 v117, v117
	s_nop 0
	v_add_f32_e32 v114, 1.0, v114
	v_add_f32_e32 v115, 1.0, v115
	v_add_f32_e32 v116, 1.0, v116
	v_add_f32_e32 v117, 1.0, v117
	v_div_scale_f32 v108, s[22:23], v114, v114, 1.0
	v_rcp_f32_e32 v109, v108
	s_nop 0
	v_fma_f32 v110, -v108, v109, 1.0
	v_fmac_f32_e32 v109, v110, v109
	v_div_scale_f32 v110, vcc, 1.0, v114, 1.0
	v_mul_f32_e32 v111, v110, v109
	v_fma_f32 v112, -v108, v111, v110
	v_fmac_f32_e32 v111, v112, v109
	v_fma_f32 v108, -v108, v111, v110
	v_div_fmas_f32 v108, v108, v109, v111
	v_div_fixup_f32 v114, v108, v114, 1.0
	v_mul_f32_e32 v92, v114, v92
	v_div_scale_f32 v108, s[22:23], v115, v115, 1.0
	v_rcp_f32_e32 v109, v108
	s_nop 0
	v_fma_f32 v110, -v108, v109, 1.0
	v_fmac_f32_e32 v109, v110, v109
	v_div_scale_f32 v110, vcc, 1.0, v115, 1.0
	v_mul_f32_e32 v111, v110, v109
	v_fma_f32 v112, -v108, v111, v110
	v_fmac_f32_e32 v111, v112, v109
	v_fma_f32 v108, -v108, v111, v110
	v_div_fmas_f32 v108, v108, v109, v111
	v_div_fixup_f32 v115, v108, v115, 1.0
	v_mul_f32_e32 v93, v115, v93
	v_div_scale_f32 v108, s[22:23], v116, v116, 1.0
	v_rcp_f32_e32 v109, v108
	s_nop 0
	v_fma_f32 v110, -v108, v109, 1.0
	v_fmac_f32_e32 v109, v110, v109
	v_div_scale_f32 v110, vcc, 1.0, v116, 1.0
	v_mul_f32_e32 v111, v110, v109
	v_fma_f32 v112, -v108, v111, v110
	v_fmac_f32_e32 v111, v112, v109
	v_fma_f32 v108, -v108, v111, v110
	v_div_fmas_f32 v108, v108, v109, v111
	v_div_fixup_f32 v116, v108, v116, 1.0
	v_mul_f32_e32 v94, v116, v94
	v_div_scale_f32 v108, s[22:23], v117, v117, 1.0
	v_rcp_f32_e32 v109, v108
	s_nop 0
	v_fma_f32 v110, -v108, v109, 1.0
	v_fmac_f32_e32 v109, v110, v109
	v_div_scale_f32 v110, vcc, 1.0, v117, 1.0
	v_mul_f32_e32 v111, v110, v109
	v_fma_f32 v112, -v108, v111, v110
	v_fmac_f32_e32 v111, v112, v109
	v_fma_f32 v108, -v108, v111, v110
	v_div_fmas_f32 v108, v108, v109, v111
	v_div_fixup_f32 v117, v108, v117, 1.0
	v_mul_f32_e32 v95, v117, v95
	v_pk_mul_f32 v[108:109], v[80:81], v[80:81]
	v_pk_fma_f32 v[108:109], v[82:83], v[82:83], v[108:109]
	v_add_f32_e32 v96, v108, v109
	v_pk_mul_f32 v[110:111], v[84:85], v[84:85]
	v_pk_fma_f32 v[110:111], v[86:87], v[86:87], v[110:111]
	v_add_f32_e32 v97, v110, v111
	v_pk_mul_f32 v[108:109], v[88:89], v[88:89]
	v_pk_fma_f32 v[108:109], v[90:91], v[90:91], v[108:109]
	v_add_f32_e32 v98, v108, v109
	v_pk_mul_f32 v[110:111], v[92:93], v[92:93]
	v_pk_fma_f32 v[110:111], v[94:95], v[94:95], v[110:111]
	v_add_f32_e32 v99, v110, v111
	v_add_f32_dpp v96, v96, v96 row_ror:8 row_mask:0xf bank_mask:0xf
	s_nop 0
	v_add_f32_dpp v97, v97, v97 row_ror:8 row_mask:0xf bank_mask:0xf
	s_nop 0
	v_add_f32_dpp v96, v96, v96 row_ror:4 row_mask:0xf bank_mask:0xf
	s_nop 0
	v_add_f32_dpp v97, v97, v97 row_ror:4 row_mask:0xf bank_mask:0xf
	s_nop 0
	v_add_f32_dpp v96, v96, v96 row_ror:2 row_mask:0xf bank_mask:0xf
	s_nop 0
	v_add_f32_dpp v97, v97, v97 row_ror:2 row_mask:0xf bank_mask:0xf
	s_nop 0
	v_add_f32_dpp v96, v96, v96 row_ror:1 row_mask:0xf bank_mask:0xf
	s_nop 0
	v_add_f32_dpp v97, v97, v97 row_ror:1 row_mask:0xf bank_mask:0xf
	s_nop 0
	v_readlane_b32 s0, v96, 0
	v_readlane_b32 s1, v96, 16
	v_readlane_b32 s18, v96, 32
	v_readlane_b32 s19, v96, 48
	v_readlane_b32 s20, v97, 0
	v_readlane_b32 s21, v97, 16
	v_readlane_b32 s22, v97, 32
	v_readlane_b32 s23, v97, 48
	s_nop 1
	v_mov_b32_e32 v100, s0
	v_mov_b32_e32 v102, s20
	v_add_f32_e32 v100, s1, v100
	v_add_f32_e32 v102, s21, v102
	v_add_f32_e32 v100, s18, v100
	v_add_f32_e32 v102, s22, v102
	v_add_f32_e32 v100, s19, v100
	v_add_f32_e32 v102, s23, v102
	v_add_f32_dpp v98, v98, v98 row_ror:8 row_mask:0xf bank_mask:0xf
	s_nop 0
	v_add_f32_dpp v99, v99, v99 row_ror:8 row_mask:0xf bank_mask:0xf
	s_nop 0
	v_add_f32_dpp v98, v98, v98 row_ror:4 row_mask:0xf bank_mask:0xf
	s_nop 0
	v_add_f32_dpp v99, v99, v99 row_ror:4 row_mask:0xf bank_mask:0xf
	s_nop 0
	v_add_f32_dpp v98, v98, v98 row_ror:2 row_mask:0xf bank_mask:0xf
	s_nop 0
	v_add_f32_dpp v99, v99, v99 row_ror:2 row_mask:0xf bank_mask:0xf
	s_nop 0
	v_add_f32_dpp v98, v98, v98 row_ror:1 row_mask:0xf bank_mask:0xf
	s_nop 0
	v_add_f32_dpp v99, v99, v99 row_ror:1 row_mask:0xf bank_mask:0xf
	s_nop 0
	v_readlane_b32 s0, v98, 0
	v_readlane_b32 s1, v98, 16
	v_readlane_b32 s18, v98, 32
	v_readlane_b32 s19, v98, 48
	v_readlane_b32 s20, v99, 0
	v_readlane_b32 s21, v99, 16
	v_readlane_b32 s22, v99, 32
	v_readlane_b32 s23, v99, 48
	s_nop 1
	v_mov_b32_e32 v104, s0
	v_mov_b32_e32 v106, s20
	v_add_f32_e32 v104, s1, v104
	v_add_f32_e32 v106, s21, v106
	v_add_f32_e32 v104, s18, v104
	v_add_f32_e32 v106, s22, v106
	v_add_f32_e32 v104, s19, v104
	v_add_f32_e32 v106, s23, v106
	v_fmamk_f32 v100, v100, 0x3b800000, v197
	v_fmamk_f32 v102, v102, 0x3b800000, v197
	v_fmamk_f32 v104, v104, 0x3b800000, v197
	v_fmamk_f32 v106, v106, 0x3b800000, v197
	v_rsq_f32_e32 v100, v100
	v_rsq_f32_e32 v102, v102
	v_rsq_f32_e32 v104, v104
	v_rsq_f32_e32 v106, v106
	s_nop 0
	v_pk_mul_f32 v[80:81], v[100:101], v[80:81] op_sel_hi:[0,1]
	v_pk_mul_f32 v[82:83], v[100:101], v[82:83] op_sel_hi:[0,1]
	v_pk_mul_f32 v[84:85], v[102:103], v[84:85] op_sel_hi:[0,1]
	v_pk_mul_f32 v[86:87], v[102:103], v[86:87] op_sel_hi:[0,1]
	v_pk_mul_f32 v[88:89], v[104:105], v[88:89] op_sel_hi:[0,1]
	v_pk_mul_f32 v[90:91], v[104:105], v[90:91] op_sel_hi:[0,1]
	v_pk_mul_f32 v[92:93], v[106:107], v[92:93] op_sel_hi:[0,1]
	v_pk_mul_f32 v[94:95], v[106:107], v[94:95] op_sel_hi:[0,1]
	v_pk_mul_f32 v[80:81], v[2:3], v[80:81]
	v_pk_mul_f32 v[82:83], v[4:5], v[82:83]
	v_pk_mul_f32 v[84:85], v[6:7], v[84:85]
	v_pk_mul_f32 v[86:87], v[8:9], v[86:87]
	v_pk_mul_f32 v[88:89], v[10:11], v[88:89]
	v_pk_mul_f32 v[90:91], v[12:13], v[90:91]
	v_pk_mul_f32 v[92:93], v[14:15], v[92:93]
	v_pk_mul_f32 v[94:95], v[16:17], v[94:95]
	v_cvt_pk_bf16_f32 v38, v80, v81
	v_cvt_pk_bf16_f32 v39, v82, v83
	v_cvt_pk_bf16_f32 v40, v84, v85
	v_cvt_pk_bf16_f32 v41, v86, v87
	v_cvt_pk_bf16_f32 v42, v88, v89
	v_cvt_pk_bf16_f32 v43, v90, v91
	v_cvt_pk_bf16_f32 v44, v92, v93
	v_cvt_pk_bf16_f32 v45, v94, v95
	global_store_dwordx2 v1, v[38:39], s[10:11] offset:0
	global_store_dwordx2 v1, v[40:41], s[10:11] offset:512
	global_store_dwordx2 v1, v[42:43], s[10:11] offset:1024
	global_store_dwordx2 v1, v[44:45], s[10:11] offset:1536
	s_add_u32 s10, s10, 0x800
	s_addc_u32 s11, s11, 0
	s_waitcnt vmcnt(32)
	v_lshlrev_b32_e32 v80, 16, v48
	v_and_b32_e32 v81, 0xffff0000, v48
	v_lshlrev_b32_e32 v82, 16, v49
	v_and_b32_e32 v83, 0xffff0000, v49
	v_lshlrev_b32_e32 v84, 16, v50
	v_and_b32_e32 v85, 0xffff0000, v50
	v_lshlrev_b32_e32 v86, 16, v51
	v_and_b32_e32 v87, 0xffff0000, v51
	v_lshlrev_b32_e32 v88, 16, v52
	v_and_b32_e32 v89, 0xffff0000, v52
	v_lshlrev_b32_e32 v90, 16, v53
	v_and_b32_e32 v91, 0xffff0000, v53
	v_lshlrev_b32_e32 v92, 16, v54
	v_and_b32_e32 v93, 0xffff0000, v54
	v_lshlrev_b32_e32 v94, 16, v55
	v_and_b32_e32 v95, 0xffff0000, v55
	v_lshlrev_b32_e32 v114, 16, v56
	v_and_b32_e32 v115, 0xffff0000, v56
	v_lshlrev_b32_e32 v116, 16, v57
	v_and_b32_e32 v117, 0xffff0000, v57
	v_mul_f32_e32 v114, 0xbfb8aa3b, v114
	v_mul_f32_e32 v115, 0xbfb8aa3b, v115
	v_mul_f32_e32 v116, 0xbfb8aa3b, v116
	v_mul_f32_e32 v117, 0xbfb8aa3b, v117
	v_exp_f32_e32 v114, v114
	v_exp_f32_e32 v115, v115
	v_exp_f32_e32 v116, v116
	v_exp_f32_e32 v117, v117
	s_nop 0
	v_add_f32_e32 v114, 1.0, v114
	v_add_f32_e32 v115, 1.0, v115
	v_add_f32_e32 v116, 1.0, v116
	v_add_f32_e32 v117, 1.0, v117
	v_div_scale_f32 v108, s[22:23], v114, v114, 1.0
	v_rcp_f32_e32 v109, v108
	s_nop 0
	v_fma_f32 v110, -v108, v109, 1.0
	v_fmac_f32_e32 v109, v110, v109
	v_div_scale_f32 v110, vcc, 1.0, v114, 1.0
	v_mul_f32_e32 v111, v110, v109
	v_fma_f32 v112, -v108, v111, v110
	v_fmac_f32_e32 v111, v112, v109
	v_fma_f32 v108, -v108, v111, v110
	v_div_fmas_f32 v108, v108, v109, v111
	v_div_fixup_f32 v114, v108, v114, 1.0
	v_mul_f32_e32 v92, v114, v92
	v_div_scale_f32 v108, s[22:23], v115, v115, 1.0
	v_rcp_f32_e32 v109, v108
	s_nop 0
	v_fma_f32 v110, -v108, v109, 1.0
	v_fmac_f32_e32 v109, v110, v109
	v_div_scale_f32 v110, vcc, 1.0, v115, 1.0
	v_mul_f32_e32 v111, v110, v109
	v_fma_f32 v112, -v108, v111, v110
	v_fmac_f32_e32 v111, v112, v109
	v_fma_f32 v108, -v108, v111, v110
	v_div_fmas_f32 v108, v108, v109, v111
	v_div_fixup_f32 v115, v108, v115, 1.0
	v_mul_f32_e32 v93, v115, v93
	v_div_scale_f32 v108, s[22:23], v116, v116, 1.0
	v_rcp_f32_e32 v109, v108
	s_nop 0
	v_fma_f32 v110, -v108, v109, 1.0
	v_fmac_f32_e32 v109, v110, v109
	v_div_scale_f32 v110, vcc, 1.0, v116, 1.0
	v_mul_f32_e32 v111, v110, v109
	v_fma_f32 v112, -v108, v111, v110
	v_fmac_f32_e32 v111, v112, v109
	v_fma_f32 v108, -v108, v111, v110
	v_div_fmas_f32 v108, v108, v109, v111
	v_div_fixup_f32 v116, v108, v116, 1.0
	v_mul_f32_e32 v94, v116, v94
	v_div_scale_f32 v108, s[22:23], v117, v117, 1.0
	v_rcp_f32_e32 v109, v108
	s_nop 0
	v_fma_f32 v110, -v108, v109, 1.0
	v_fmac_f32_e32 v109, v110, v109
	v_div_scale_f32 v110, vcc, 1.0, v117, 1.0
	v_mul_f32_e32 v111, v110, v109
	v_fma_f32 v112, -v108, v111, v110
	v_fmac_f32_e32 v111, v112, v109
	v_fma_f32 v108, -v108, v111, v110
	v_div_fmas_f32 v108, v108, v109, v111
	v_div_fixup_f32 v117, v108, v117, 1.0
	v_mul_f32_e32 v95, v117, v95
	v_pk_mul_f32 v[108:109], v[80:81], v[80:81]
	v_pk_fma_f32 v[108:109], v[82:83], v[82:83], v[108:109]
	v_add_f32_e32 v96, v108, v109
	v_pk_mul_f32 v[110:111], v[84:85], v[84:85]
	v_pk_fma_f32 v[110:111], v[86:87], v[86:87], v[110:111]
	v_add_f32_e32 v97, v110, v111
	v_pk_mul_f32 v[108:109], v[88:89], v[88:89]
	v_pk_fma_f32 v[108:109], v[90:91], v[90:91], v[108:109]
	v_add_f32_e32 v98, v108, v109
	v_pk_mul_f32 v[110:111], v[92:93], v[92:93]
	v_pk_fma_f32 v[110:111], v[94:95], v[94:95], v[110:111]
	v_add_f32_e32 v99, v110, v111
	v_add_f32_dpp v96, v96, v96 row_ror:8 row_mask:0xf bank_mask:0xf
	s_nop 0
	v_add_f32_dpp v97, v97, v97 row_ror:8 row_mask:0xf bank_mask:0xf
	s_nop 0
	v_add_f32_dpp v96, v96, v96 row_ror:4 row_mask:0xf bank_mask:0xf
	s_nop 0
	v_add_f32_dpp v97, v97, v97 row_ror:4 row_mask:0xf bank_mask:0xf
	s_nop 0
	v_add_f32_dpp v96, v96, v96 row_ror:2 row_mask:0xf bank_mask:0xf
	s_nop 0
	v_add_f32_dpp v97, v97, v97 row_ror:2 row_mask:0xf bank_mask:0xf
	s_nop 0
	v_add_f32_dpp v96, v96, v96 row_ror:1 row_mask:0xf bank_mask:0xf
	s_nop 0
	v_add_f32_dpp v97, v97, v97 row_ror:1 row_mask:0xf bank_mask:0xf
	s_nop 0
	v_readlane_b32 s0, v96, 0
	v_readlane_b32 s1, v96, 16
	v_readlane_b32 s18, v96, 32
	v_readlane_b32 s19, v96, 48
	v_readlane_b32 s20, v97, 0
	v_readlane_b32 s21, v97, 16
	v_readlane_b32 s22, v97, 32
	v_readlane_b32 s23, v97, 48
	s_nop 1
	v_mov_b32_e32 v100, s0
	v_mov_b32_e32 v102, s20
	v_add_f32_e32 v100, s1, v100
	v_add_f32_e32 v102, s21, v102
	v_add_f32_e32 v100, s18, v100
	v_add_f32_e32 v102, s22, v102
	v_add_f32_e32 v100, s19, v100
	v_add_f32_e32 v102, s23, v102
	v_add_f32_dpp v98, v98, v98 row_ror:8 row_mask:0xf bank_mask:0xf
	s_nop 0
	v_add_f32_dpp v99, v99, v99 row_ror:8 row_mask:0xf bank_mask:0xf
	s_nop 0
	v_add_f32_dpp v98, v98, v98 row_ror:4 row_mask:0xf bank_mask:0xf
	s_nop 0
	v_add_f32_dpp v99, v99, v99 row_ror:4 row_mask:0xf bank_mask:0xf
	s_nop 0
	v_add_f32_dpp v98, v98, v98 row_ror:2 row_mask:0xf bank_mask:0xf
	s_nop 0
	v_add_f32_dpp v99, v99, v99 row_ror:2 row_mask:0xf bank_mask:0xf
	s_nop 0
	v_add_f32_dpp v98, v98, v98 row_ror:1 row_mask:0xf bank_mask:0xf
	s_nop 0
	v_add_f32_dpp v99, v99, v99 row_ror:1 row_mask:0xf bank_mask:0xf
	s_nop 0
	v_readlane_b32 s0, v98, 0
	v_readlane_b32 s1, v98, 16
	v_readlane_b32 s18, v98, 32
	v_readlane_b32 s19, v98, 48
	v_readlane_b32 s20, v99, 0
	v_readlane_b32 s21, v99, 16
	v_readlane_b32 s22, v99, 32
	v_readlane_b32 s23, v99, 48
	s_nop 1
	v_mov_b32_e32 v104, s0
	v_mov_b32_e32 v106, s20
	v_add_f32_e32 v104, s1, v104
	v_add_f32_e32 v106, s21, v106
	v_add_f32_e32 v104, s18, v104
	v_add_f32_e32 v106, s22, v106
	v_add_f32_e32 v104, s19, v104
	v_add_f32_e32 v106, s23, v106
	v_fmamk_f32 v100, v100, 0x3b800000, v197
	v_fmamk_f32 v102, v102, 0x3b800000, v197
	v_fmamk_f32 v104, v104, 0x3b800000, v197
	v_fmamk_f32 v106, v106, 0x3b800000, v197
	v_rsq_f32_e32 v100, v100
	v_rsq_f32_e32 v102, v102
	v_rsq_f32_e32 v104, v104
	v_rsq_f32_e32 v106, v106
	s_nop 0
	v_pk_mul_f32 v[80:81], v[100:101], v[80:81] op_sel_hi:[0,1]
	v_pk_mul_f32 v[82:83], v[100:101], v[82:83] op_sel_hi:[0,1]
	v_pk_mul_f32 v[84:85], v[102:103], v[84:85] op_sel_hi:[0,1]
	v_pk_mul_f32 v[86:87], v[102:103], v[86:87] op_sel_hi:[0,1]
	v_pk_mul_f32 v[88:89], v[104:105], v[88:89] op_sel_hi:[0,1]
	v_pk_mul_f32 v[90:91], v[104:105], v[90:91] op_sel_hi:[0,1]
	v_pk_mul_f32 v[92:93], v[106:107], v[92:93] op_sel_hi:[0,1]
	v_pk_mul_f32 v[94:95], v[106:107], v[94:95] op_sel_hi:[0,1]
	v_pk_mul_f32 v[80:81], v[2:3], v[80:81]
	v_pk_mul_f32 v[82:83], v[4:5], v[82:83]
	v_pk_mul_f32 v[84:85], v[6:7], v[84:85]
	v_pk_mul_f32 v[86:87], v[8:9], v[86:87]
	v_pk_mul_f32 v[88:89], v[10:11], v[88:89]
	v_pk_mul_f32 v[90:91], v[12:13], v[90:91]
	v_pk_mul_f32 v[92:93], v[14:15], v[92:93]
	v_pk_mul_f32 v[94:95], v[16:17], v[94:95]
	v_cvt_pk_bf16_f32 v48, v80, v81
	v_cvt_pk_bf16_f32 v49, v82, v83
	v_cvt_pk_bf16_f32 v50, v84, v85
	v_cvt_pk_bf16_f32 v51, v86, v87
	v_cvt_pk_bf16_f32 v52, v88, v89
	v_cvt_pk_bf16_f32 v53, v90, v91
	v_cvt_pk_bf16_f32 v54, v92, v93
	v_cvt_pk_bf16_f32 v55, v94, v95
	global_store_dwordx2 v1, v[48:49], s[10:11] offset:0
	global_store_dwordx2 v1, v[50:51], s[10:11] offset:512
	global_store_dwordx2 v1, v[52:53], s[10:11] offset:1024
	global_store_dwordx2 v1, v[54:55], s[10:11] offset:1536
	s_add_u32 s10, s10, 0x800
	s_addc_u32 s11, s11, 0
	s_waitcnt vmcnt(31)
	v_lshlrev_b32_e32 v80, 16, v58
	v_and_b32_e32 v81, 0xffff0000, v58
	v_lshlrev_b32_e32 v82, 16, v59
	v_and_b32_e32 v83, 0xffff0000, v59
	v_lshlrev_b32_e32 v84, 16, v60
	v_and_b32_e32 v85, 0xffff0000, v60
	v_lshlrev_b32_e32 v86, 16, v61
	v_and_b32_e32 v87, 0xffff0000, v61
	v_lshlrev_b32_e32 v88, 16, v62
	v_and_b32_e32 v89, 0xffff0000, v62
	v_lshlrev_b32_e32 v90, 16, v63
	v_and_b32_e32 v91, 0xffff0000, v63
	v_lshlrev_b32_e32 v92, 16, v64
	v_and_b32_e32 v93, 0xffff0000, v64
	v_lshlrev_b32_e32 v94, 16, v65
	v_and_b32_e32 v95, 0xffff0000, v65
	v_lshlrev_b32_e32 v114, 16, v66
	v_and_b32_e32 v115, 0xffff0000, v66
	v_lshlrev_b32_e32 v116, 16, v67
	v_and_b32_e32 v117, 0xffff0000, v67
	v_mul_f32_e32 v114, 0xbfb8aa3b, v114
	v_mul_f32_e32 v115, 0xbfb8aa3b, v115
	v_mul_f32_e32 v116, 0xbfb8aa3b, v116
	v_mul_f32_e32 v117, 0xbfb8aa3b, v117
	v_exp_f32_e32 v114, v114
	v_exp_f32_e32 v115, v115
	v_exp_f32_e32 v116, v116
	v_exp_f32_e32 v117, v117
	s_nop 0
	v_add_f32_e32 v114, 1.0, v114
	v_add_f32_e32 v115, 1.0, v115
	v_add_f32_e32 v116, 1.0, v116
	v_add_f32_e32 v117, 1.0, v117
	v_div_scale_f32 v108, s[22:23], v114, v114, 1.0
	v_rcp_f32_e32 v109, v108
	s_nop 0
	v_fma_f32 v110, -v108, v109, 1.0
	v_fmac_f32_e32 v109, v110, v109
	v_div_scale_f32 v110, vcc, 1.0, v114, 1.0
	v_mul_f32_e32 v111, v110, v109
	v_fma_f32 v112, -v108, v111, v110
	v_fmac_f32_e32 v111, v112, v109
	v_fma_f32 v108, -v108, v111, v110
	v_div_fmas_f32 v108, v108, v109, v111
	v_div_fixup_f32 v114, v108, v114, 1.0
	v_mul_f32_e32 v92, v114, v92
	v_div_scale_f32 v108, s[22:23], v115, v115, 1.0
	v_rcp_f32_e32 v109, v108
	s_nop 0
	v_fma_f32 v110, -v108, v109, 1.0
	v_fmac_f32_e32 v109, v110, v109
	v_div_scale_f32 v110, vcc, 1.0, v115, 1.0
	v_mul_f32_e32 v111, v110, v109
	v_fma_f32 v112, -v108, v111, v110
	v_fmac_f32_e32 v111, v112, v109
	v_fma_f32 v108, -v108, v111, v110
	v_div_fmas_f32 v108, v108, v109, v111
	v_div_fixup_f32 v115, v108, v115, 1.0
	v_mul_f32_e32 v93, v115, v93
	v_div_scale_f32 v108, s[22:23], v116, v116, 1.0
	v_rcp_f32_e32 v109, v108
	s_nop 0
	v_fma_f32 v110, -v108, v109, 1.0
	v_fmac_f32_e32 v109, v110, v109
	v_div_scale_f32 v110, vcc, 1.0, v116, 1.0
	v_mul_f32_e32 v111, v110, v109
	v_fma_f32 v112, -v108, v111, v110
	v_fmac_f32_e32 v111, v112, v109
	v_fma_f32 v108, -v108, v111, v110
	v_div_fmas_f32 v108, v108, v109, v111
	v_div_fixup_f32 v116, v108, v116, 1.0
	v_mul_f32_e32 v94, v116, v94
	v_div_scale_f32 v108, s[22:23], v117, v117, 1.0
	v_rcp_f32_e32 v109, v108
	s_nop 0
	v_fma_f32 v110, -v108, v109, 1.0
	v_fmac_f32_e32 v109, v110, v109
	v_div_scale_f32 v110, vcc, 1.0, v117, 1.0
	v_mul_f32_e32 v111, v110, v109
	v_fma_f32 v112, -v108, v111, v110
	v_fmac_f32_e32 v111, v112, v109
	v_fma_f32 v108, -v108, v111, v110
	v_div_fmas_f32 v108, v108, v109, v111
	v_div_fixup_f32 v117, v108, v117, 1.0
	v_mul_f32_e32 v95, v117, v95
	v_pk_mul_f32 v[108:109], v[80:81], v[80:81]
	v_pk_fma_f32 v[108:109], v[82:83], v[82:83], v[108:109]
	v_add_f32_e32 v96, v108, v109
	v_pk_mul_f32 v[110:111], v[84:85], v[84:85]
	v_pk_fma_f32 v[110:111], v[86:87], v[86:87], v[110:111]
	v_add_f32_e32 v97, v110, v111
	v_pk_mul_f32 v[108:109], v[88:89], v[88:89]
	v_pk_fma_f32 v[108:109], v[90:91], v[90:91], v[108:109]
	v_add_f32_e32 v98, v108, v109
	v_pk_mul_f32 v[110:111], v[92:93], v[92:93]
	v_pk_fma_f32 v[110:111], v[94:95], v[94:95], v[110:111]
	v_add_f32_e32 v99, v110, v111
	v_add_f32_dpp v96, v96, v96 row_ror:8 row_mask:0xf bank_mask:0xf
	s_nop 0
	v_add_f32_dpp v97, v97, v97 row_ror:8 row_mask:0xf bank_mask:0xf
	s_nop 0
	v_add_f32_dpp v96, v96, v96 row_ror:4 row_mask:0xf bank_mask:0xf
	s_nop 0
	v_add_f32_dpp v97, v97, v97 row_ror:4 row_mask:0xf bank_mask:0xf
	s_nop 0
	v_add_f32_dpp v96, v96, v96 row_ror:2 row_mask:0xf bank_mask:0xf
	s_nop 0
	v_add_f32_dpp v97, v97, v97 row_ror:2 row_mask:0xf bank_mask:0xf
	s_nop 0
	v_add_f32_dpp v96, v96, v96 row_ror:1 row_mask:0xf bank_mask:0xf
	s_nop 0
	v_add_f32_dpp v97, v97, v97 row_ror:1 row_mask:0xf bank_mask:0xf
	s_nop 0
	v_readlane_b32 s0, v96, 0
	v_readlane_b32 s1, v96, 16
	v_readlane_b32 s18, v96, 32
	v_readlane_b32 s19, v96, 48
	v_readlane_b32 s20, v97, 0
	v_readlane_b32 s21, v97, 16
	v_readlane_b32 s22, v97, 32
	v_readlane_b32 s23, v97, 48
	s_nop 1
	v_mov_b32_e32 v100, s0
	v_mov_b32_e32 v102, s20
	v_add_f32_e32 v100, s1, v100
	v_add_f32_e32 v102, s21, v102
	v_add_f32_e32 v100, s18, v100
	v_add_f32_e32 v102, s22, v102
	v_add_f32_e32 v100, s19, v100
	v_add_f32_e32 v102, s23, v102
	v_add_f32_dpp v98, v98, v98 row_ror:8 row_mask:0xf bank_mask:0xf
	s_nop 0
	v_add_f32_dpp v99, v99, v99 row_ror:8 row_mask:0xf bank_mask:0xf
	s_nop 0
	v_add_f32_dpp v98, v98, v98 row_ror:4 row_mask:0xf bank_mask:0xf
	s_nop 0
	v_add_f32_dpp v99, v99, v99 row_ror:4 row_mask:0xf bank_mask:0xf
	s_nop 0
	v_add_f32_dpp v98, v98, v98 row_ror:2 row_mask:0xf bank_mask:0xf
	s_nop 0
	v_add_f32_dpp v99, v99, v99 row_ror:2 row_mask:0xf bank_mask:0xf
	s_nop 0
	v_add_f32_dpp v98, v98, v98 row_ror:1 row_mask:0xf bank_mask:0xf
	s_nop 0
	v_add_f32_dpp v99, v99, v99 row_ror:1 row_mask:0xf bank_mask:0xf
	s_nop 0
	v_readlane_b32 s0, v98, 0
	v_readlane_b32 s1, v98, 16
	v_readlane_b32 s18, v98, 32
	v_readlane_b32 s19, v98, 48
	v_readlane_b32 s20, v99, 0
	v_readlane_b32 s21, v99, 16
	v_readlane_b32 s22, v99, 32
	v_readlane_b32 s23, v99, 48
	s_nop 1
	v_mov_b32_e32 v104, s0
	v_mov_b32_e32 v106, s20
	v_add_f32_e32 v104, s1, v104
	v_add_f32_e32 v106, s21, v106
	v_add_f32_e32 v104, s18, v104
	v_add_f32_e32 v106, s22, v106
	v_add_f32_e32 v104, s19, v104
	v_add_f32_e32 v106, s23, v106
	v_fmamk_f32 v100, v100, 0x3b800000, v197
	v_fmamk_f32 v102, v102, 0x3b800000, v197
	v_fmamk_f32 v104, v104, 0x3b800000, v197
	v_fmamk_f32 v106, v106, 0x3b800000, v197
	v_rsq_f32_e32 v100, v100
	v_rsq_f32_e32 v102, v102
	v_rsq_f32_e32 v104, v104
	v_rsq_f32_e32 v106, v106
	s_nop 0
	v_pk_mul_f32 v[80:81], v[100:101], v[80:81] op_sel_hi:[0,1]
	v_pk_mul_f32 v[82:83], v[100:101], v[82:83] op_sel_hi:[0,1]
	v_pk_mul_f32 v[84:85], v[102:103], v[84:85] op_sel_hi:[0,1]
	v_pk_mul_f32 v[86:87], v[102:103], v[86:87] op_sel_hi:[0,1]
	v_pk_mul_f32 v[88:89], v[104:105], v[88:89] op_sel_hi:[0,1]
	v_pk_mul_f32 v[90:91], v[104:105], v[90:91] op_sel_hi:[0,1]
	v_pk_mul_f32 v[92:93], v[106:107], v[92:93] op_sel_hi:[0,1]
	v_pk_mul_f32 v[94:95], v[106:107], v[94:95] op_sel_hi:[0,1]
	v_pk_mul_f32 v[80:81], v[2:3], v[80:81]
	v_pk_mul_f32 v[82:83], v[4:5], v[82:83]
	v_pk_mul_f32 v[84:85], v[6:7], v[84:85]
	v_pk_mul_f32 v[86:87], v[8:9], v[86:87]
	v_pk_mul_f32 v[88:89], v[10:11], v[88:89]
	v_pk_mul_f32 v[90:91], v[12:13], v[90:91]
	v_pk_mul_f32 v[92:93], v[14:15], v[92:93]
	v_pk_mul_f32 v[94:95], v[16:17], v[94:95]
	v_cvt_pk_bf16_f32 v58, v80, v81
	v_cvt_pk_bf16_f32 v59, v82, v83
	v_cvt_pk_bf16_f32 v60, v84, v85
	v_cvt_pk_bf16_f32 v61, v86, v87
	v_cvt_pk_bf16_f32 v62, v88, v89
	v_cvt_pk_bf16_f32 v63, v90, v91
	v_cvt_pk_bf16_f32 v64, v92, v93
	v_cvt_pk_bf16_f32 v65, v94, v95
	global_store_dwordx2 v1, v[58:59], s[10:11] offset:0
	global_store_dwordx2 v1, v[60:61], s[10:11] offset:512
	global_store_dwordx2 v1, v[62:63], s[10:11] offset:1024
	global_store_dwordx2 v1, v[64:65], s[10:11] offset:1536
	s_add_u32 s10, s10, 0x800
	s_addc_u32 s11, s11, 0
	s_waitcnt vmcnt(30)
	v_lshlrev_b32_e32 v80, 16, v68
	v_and_b32_e32 v81, 0xffff0000, v68
	v_lshlrev_b32_e32 v82, 16, v69
	v_and_b32_e32 v83, 0xffff0000, v69
	v_lshlrev_b32_e32 v84, 16, v70
	v_and_b32_e32 v85, 0xffff0000, v70
	v_lshlrev_b32_e32 v86, 16, v71
	v_and_b32_e32 v87, 0xffff0000, v71
	v_lshlrev_b32_e32 v88, 16, v72
	v_and_b32_e32 v89, 0xffff0000, v72
	v_lshlrev_b32_e32 v90, 16, v73
	v_and_b32_e32 v91, 0xffff0000, v73
	v_lshlrev_b32_e32 v92, 16, v74
	v_and_b32_e32 v93, 0xffff0000, v74
	v_lshlrev_b32_e32 v94, 16, v75
	v_and_b32_e32 v95, 0xffff0000, v75
	v_lshlrev_b32_e32 v114, 16, v76
	v_and_b32_e32 v115, 0xffff0000, v76
	v_lshlrev_b32_e32 v116, 16, v77
	v_and_b32_e32 v117, 0xffff0000, v77
	v_mul_f32_e32 v114, 0xbfb8aa3b, v114
	v_mul_f32_e32 v115, 0xbfb8aa3b, v115
	v_mul_f32_e32 v116, 0xbfb8aa3b, v116
	v_mul_f32_e32 v117, 0xbfb8aa3b, v117
	v_exp_f32_e32 v114, v114
	v_exp_f32_e32 v115, v115
	v_exp_f32_e32 v116, v116
	v_exp_f32_e32 v117, v117
	s_nop 0
	v_add_f32_e32 v114, 1.0, v114
	v_add_f32_e32 v115, 1.0, v115
	v_add_f32_e32 v116, 1.0, v116
	v_add_f32_e32 v117, 1.0, v117
	v_div_scale_f32 v108, s[22:23], v114, v114, 1.0
	v_rcp_f32_e32 v109, v108
	s_nop 0
	v_fma_f32 v110, -v108, v109, 1.0
	v_fmac_f32_e32 v109, v110, v109
	v_div_scale_f32 v110, vcc, 1.0, v114, 1.0
	v_mul_f32_e32 v111, v110, v109
	v_fma_f32 v112, -v108, v111, v110
	v_fmac_f32_e32 v111, v112, v109
	v_fma_f32 v108, -v108, v111, v110
	v_div_fmas_f32 v108, v108, v109, v111
	v_div_fixup_f32 v114, v108, v114, 1.0
	v_mul_f32_e32 v92, v114, v92
	v_div_scale_f32 v108, s[22:23], v115, v115, 1.0
	v_rcp_f32_e32 v109, v108
	s_nop 0
	v_fma_f32 v110, -v108, v109, 1.0
	v_fmac_f32_e32 v109, v110, v109
	v_div_scale_f32 v110, vcc, 1.0, v115, 1.0
	v_mul_f32_e32 v111, v110, v109
	v_fma_f32 v112, -v108, v111, v110
	v_fmac_f32_e32 v111, v112, v109
	v_fma_f32 v108, -v108, v111, v110
	v_div_fmas_f32 v108, v108, v109, v111
	v_div_fixup_f32 v115, v108, v115, 1.0
	v_mul_f32_e32 v93, v115, v93
	v_div_scale_f32 v108, s[22:23], v116, v116, 1.0
	v_rcp_f32_e32 v109, v108
	s_nop 0
	v_fma_f32 v110, -v108, v109, 1.0
	v_fmac_f32_e32 v109, v110, v109
	v_div_scale_f32 v110, vcc, 1.0, v116, 1.0
	v_mul_f32_e32 v111, v110, v109
	v_fma_f32 v112, -v108, v111, v110
	v_fmac_f32_e32 v111, v112, v109
	v_fma_f32 v108, -v108, v111, v110
	v_div_fmas_f32 v108, v108, v109, v111
	v_div_fixup_f32 v116, v108, v116, 1.0
	v_mul_f32_e32 v94, v116, v94
	v_div_scale_f32 v108, s[22:23], v117, v117, 1.0
	v_rcp_f32_e32 v109, v108
	s_nop 0
	v_fma_f32 v110, -v108, v109, 1.0
	v_fmac_f32_e32 v109, v110, v109
	v_div_scale_f32 v110, vcc, 1.0, v117, 1.0
	v_mul_f32_e32 v111, v110, v109
	v_fma_f32 v112, -v108, v111, v110
	v_fmac_f32_e32 v111, v112, v109
	v_fma_f32 v108, -v108, v111, v110
	v_div_fmas_f32 v108, v108, v109, v111
	v_div_fixup_f32 v117, v108, v117, 1.0
	v_mul_f32_e32 v95, v117, v95
	v_pk_mul_f32 v[108:109], v[80:81], v[80:81]
	v_pk_fma_f32 v[108:109], v[82:83], v[82:83], v[108:109]
	v_add_f32_e32 v96, v108, v109
	v_pk_mul_f32 v[110:111], v[84:85], v[84:85]
	v_pk_fma_f32 v[110:111], v[86:87], v[86:87], v[110:111]
	v_add_f32_e32 v97, v110, v111
	v_pk_mul_f32 v[108:109], v[88:89], v[88:89]
	v_pk_fma_f32 v[108:109], v[90:91], v[90:91], v[108:109]
	v_add_f32_e32 v98, v108, v109
	v_pk_mul_f32 v[110:111], v[92:93], v[92:93]
	v_pk_fma_f32 v[110:111], v[94:95], v[94:95], v[110:111]
	v_add_f32_e32 v99, v110, v111
	v_add_f32_dpp v96, v96, v96 row_ror:8 row_mask:0xf bank_mask:0xf
	s_nop 0
	v_add_f32_dpp v97, v97, v97 row_ror:8 row_mask:0xf bank_mask:0xf
	s_nop 0
	v_add_f32_dpp v96, v96, v96 row_ror:4 row_mask:0xf bank_mask:0xf
	s_nop 0
	v_add_f32_dpp v97, v97, v97 row_ror:4 row_mask:0xf bank_mask:0xf
	s_nop 0
	v_add_f32_dpp v96, v96, v96 row_ror:2 row_mask:0xf bank_mask:0xf
	s_nop 0
	v_add_f32_dpp v97, v97, v97 row_ror:2 row_mask:0xf bank_mask:0xf
	s_nop 0
	v_add_f32_dpp v96, v96, v96 row_ror:1 row_mask:0xf bank_mask:0xf
	s_nop 0
	v_add_f32_dpp v97, v97, v97 row_ror:1 row_mask:0xf bank_mask:0xf
	s_nop 0
	v_readlane_b32 s0, v96, 0
	v_readlane_b32 s1, v96, 16
	v_readlane_b32 s18, v96, 32
	v_readlane_b32 s19, v96, 48
	v_readlane_b32 s20, v97, 0
	v_readlane_b32 s21, v97, 16
	v_readlane_b32 s22, v97, 32
	v_readlane_b32 s23, v97, 48
	s_nop 1
	v_mov_b32_e32 v100, s0
	v_mov_b32_e32 v102, s20
	v_add_f32_e32 v100, s1, v100
	v_add_f32_e32 v102, s21, v102
	v_add_f32_e32 v100, s18, v100
	v_add_f32_e32 v102, s22, v102
	v_add_f32_e32 v100, s19, v100
	v_add_f32_e32 v102, s23, v102
	v_add_f32_dpp v98, v98, v98 row_ror:8 row_mask:0xf bank_mask:0xf
	s_nop 0
	v_add_f32_dpp v99, v99, v99 row_ror:8 row_mask:0xf bank_mask:0xf
	s_nop 0
	v_add_f32_dpp v98, v98, v98 row_ror:4 row_mask:0xf bank_mask:0xf
	s_nop 0
	v_add_f32_dpp v99, v99, v99 row_ror:4 row_mask:0xf bank_mask:0xf
	s_nop 0
	v_add_f32_dpp v98, v98, v98 row_ror:2 row_mask:0xf bank_mask:0xf
	s_nop 0
	v_add_f32_dpp v99, v99, v99 row_ror:2 row_mask:0xf bank_mask:0xf
	s_nop 0
	v_add_f32_dpp v98, v98, v98 row_ror:1 row_mask:0xf bank_mask:0xf
	s_nop 0
	v_add_f32_dpp v99, v99, v99 row_ror:1 row_mask:0xf bank_mask:0xf
	s_nop 0
	v_readlane_b32 s0, v98, 0
	v_readlane_b32 s1, v98, 16
	v_readlane_b32 s18, v98, 32
	v_readlane_b32 s19, v98, 48
	v_readlane_b32 s20, v99, 0
	v_readlane_b32 s21, v99, 16
	v_readlane_b32 s22, v99, 32
	v_readlane_b32 s23, v99, 48
	s_nop 1
	v_mov_b32_e32 v104, s0
	v_mov_b32_e32 v106, s20
	v_add_f32_e32 v104, s1, v104
	v_add_f32_e32 v106, s21, v106
	v_add_f32_e32 v104, s18, v104
	v_add_f32_e32 v106, s22, v106
	v_add_f32_e32 v104, s19, v104
	v_add_f32_e32 v106, s23, v106
	v_fmamk_f32 v100, v100, 0x3b800000, v197
	v_fmamk_f32 v102, v102, 0x3b800000, v197
	v_fmamk_f32 v104, v104, 0x3b800000, v197
	v_fmamk_f32 v106, v106, 0x3b800000, v197
	v_rsq_f32_e32 v100, v100
	v_rsq_f32_e32 v102, v102
	v_rsq_f32_e32 v104, v104
	v_rsq_f32_e32 v106, v106
	s_nop 0
	v_pk_mul_f32 v[80:81], v[100:101], v[80:81] op_sel_hi:[0,1]
	v_pk_mul_f32 v[82:83], v[100:101], v[82:83] op_sel_hi:[0,1]
	v_pk_mul_f32 v[84:85], v[102:103], v[84:85] op_sel_hi:[0,1]
	v_pk_mul_f32 v[86:87], v[102:103], v[86:87] op_sel_hi:[0,1]
	v_pk_mul_f32 v[88:89], v[104:105], v[88:89] op_sel_hi:[0,1]
	v_pk_mul_f32 v[90:91], v[104:105], v[90:91] op_sel_hi:[0,1]
	v_pk_mul_f32 v[92:93], v[106:107], v[92:93] op_sel_hi:[0,1]
	v_pk_mul_f32 v[94:95], v[106:107], v[94:95] op_sel_hi:[0,1]
	v_pk_mul_f32 v[80:81], v[2:3], v[80:81]
	v_pk_mul_f32 v[82:83], v[4:5], v[82:83]
	v_pk_mul_f32 v[84:85], v[6:7], v[84:85]
	v_pk_mul_f32 v[86:87], v[8:9], v[86:87]
	v_pk_mul_f32 v[88:89], v[10:11], v[88:89]
	v_pk_mul_f32 v[90:91], v[12:13], v[90:91]
	v_pk_mul_f32 v[92:93], v[14:15], v[92:93]
	v_pk_mul_f32 v[94:95], v[16:17], v[94:95]
	v_cvt_pk_bf16_f32 v68, v80, v81
	v_cvt_pk_bf16_f32 v69, v82, v83
	v_cvt_pk_bf16_f32 v70, v84, v85
	v_cvt_pk_bf16_f32 v71, v86, v87
	v_cvt_pk_bf16_f32 v72, v88, v89
	v_cvt_pk_bf16_f32 v73, v90, v91
	v_cvt_pk_bf16_f32 v74, v92, v93
	v_cvt_pk_bf16_f32 v75, v94, v95
	global_store_dwordx2 v1, v[68:69], s[10:11] offset:0
	global_store_dwordx2 v1, v[70:71], s[10:11] offset:512
	global_store_dwordx2 v1, v[72:73], s[10:11] offset:1024
	global_store_dwordx2 v1, v[74:75], s[10:11] offset:1536
	s_add_u32 s10, s10, 0x800
	s_addc_u32 s11, s11, 0
	s_waitcnt vmcnt(25)
	v_lshlrev_b32_e32 v80, 16, v18
	v_and_b32_e32 v81, 0xffff0000, v18
	v_lshlrev_b32_e32 v82, 16, v19
	v_and_b32_e32 v83, 0xffff0000, v19
	v_lshlrev_b32_e32 v84, 16, v20
	v_and_b32_e32 v85, 0xffff0000, v20
	v_lshlrev_b32_e32 v86, 16, v21
	v_and_b32_e32 v87, 0xffff0000, v21
	v_lshlrev_b32_e32 v88, 16, v22
	v_and_b32_e32 v89, 0xffff0000, v22
	v_lshlrev_b32_e32 v90, 16, v23
	v_and_b32_e32 v91, 0xffff0000, v23
	v_lshlrev_b32_e32 v92, 16, v24
	v_and_b32_e32 v93, 0xffff0000, v24
	v_lshlrev_b32_e32 v94, 16, v25
	v_and_b32_e32 v95, 0xffff0000, v25
	v_lshlrev_b32_e32 v114, 16, v26
	v_and_b32_e32 v115, 0xffff0000, v26
	v_lshlrev_b32_e32 v116, 16, v27
	v_and_b32_e32 v117, 0xffff0000, v27
	v_mul_f32_e32 v114, 0xbfb8aa3b, v114
	v_mul_f32_e32 v115, 0xbfb8aa3b, v115
	v_mul_f32_e32 v116, 0xbfb8aa3b, v116
	v_mul_f32_e32 v117, 0xbfb8aa3b, v117
	v_exp_f32_e32 v114, v114
	v_exp_f32_e32 v115, v115
	v_exp_f32_e32 v116, v116
	v_exp_f32_e32 v117, v117
	s_nop 0
	v_add_f32_e32 v114, 1.0, v114
	v_add_f32_e32 v115, 1.0, v115
	v_add_f32_e32 v116, 1.0, v116
	v_add_f32_e32 v117, 1.0, v117
	v_div_scale_f32 v108, s[22:23], v114, v114, 1.0
	v_rcp_f32_e32 v109, v108
	s_nop 0
	v_fma_f32 v110, -v108, v109, 1.0
	v_fmac_f32_e32 v109, v110, v109
	v_div_scale_f32 v110, vcc, 1.0, v114, 1.0
	v_mul_f32_e32 v111, v110, v109
	v_fma_f32 v112, -v108, v111, v110
	v_fmac_f32_e32 v111, v112, v109
	v_fma_f32 v108, -v108, v111, v110
	v_div_fmas_f32 v108, v108, v109, v111
	v_div_fixup_f32 v114, v108, v114, 1.0
	v_mul_f32_e32 v92, v114, v92
	v_div_scale_f32 v108, s[22:23], v115, v115, 1.0
	v_rcp_f32_e32 v109, v108
	s_nop 0
	v_fma_f32 v110, -v108, v109, 1.0
	v_fmac_f32_e32 v109, v110, v109
	v_div_scale_f32 v110, vcc, 1.0, v115, 1.0
	v_mul_f32_e32 v111, v110, v109
	v_fma_f32 v112, -v108, v111, v110
	v_fmac_f32_e32 v111, v112, v109
	v_fma_f32 v108, -v108, v111, v110
	v_div_fmas_f32 v108, v108, v109, v111
	v_div_fixup_f32 v115, v108, v115, 1.0
	v_mul_f32_e32 v93, v115, v93
	v_div_scale_f32 v108, s[22:23], v116, v116, 1.0
	v_rcp_f32_e32 v109, v108
	s_nop 0
	v_fma_f32 v110, -v108, v109, 1.0
	v_fmac_f32_e32 v109, v110, v109
	v_div_scale_f32 v110, vcc, 1.0, v116, 1.0
	v_mul_f32_e32 v111, v110, v109
	v_fma_f32 v112, -v108, v111, v110
	v_fmac_f32_e32 v111, v112, v109
	v_fma_f32 v108, -v108, v111, v110
	v_div_fmas_f32 v108, v108, v109, v111
	v_div_fixup_f32 v116, v108, v116, 1.0
	v_mul_f32_e32 v94, v116, v94
	v_div_scale_f32 v108, s[22:23], v117, v117, 1.0
	v_rcp_f32_e32 v109, v108
	s_nop 0
	v_fma_f32 v110, -v108, v109, 1.0
	v_fmac_f32_e32 v109, v110, v109
	v_div_scale_f32 v110, vcc, 1.0, v117, 1.0
	v_mul_f32_e32 v111, v110, v109
	v_fma_f32 v112, -v108, v111, v110
	v_fmac_f32_e32 v111, v112, v109
	v_fma_f32 v108, -v108, v111, v110
	v_div_fmas_f32 v108, v108, v109, v111
	v_div_fixup_f32 v117, v108, v117, 1.0
	v_mul_f32_e32 v95, v117, v95
	v_pk_mul_f32 v[108:109], v[80:81], v[80:81]
	v_pk_fma_f32 v[108:109], v[82:83], v[82:83], v[108:109]
	v_add_f32_e32 v96, v108, v109
	v_pk_mul_f32 v[110:111], v[84:85], v[84:85]
	v_pk_fma_f32 v[110:111], v[86:87], v[86:87], v[110:111]
	v_add_f32_e32 v97, v110, v111
	v_pk_mul_f32 v[108:109], v[88:89], v[88:89]
	v_pk_fma_f32 v[108:109], v[90:91], v[90:91], v[108:109]
	v_add_f32_e32 v98, v108, v109
	v_pk_mul_f32 v[110:111], v[92:93], v[92:93]
	v_pk_fma_f32 v[110:111], v[94:95], v[94:95], v[110:111]
	v_add_f32_e32 v99, v110, v111
	v_add_f32_dpp v96, v96, v96 row_ror:8 row_mask:0xf bank_mask:0xf
	s_nop 0
	v_add_f32_dpp v97, v97, v97 row_ror:8 row_mask:0xf bank_mask:0xf
	s_nop 0
	v_add_f32_dpp v96, v96, v96 row_ror:4 row_mask:0xf bank_mask:0xf
	s_nop 0
	v_add_f32_dpp v97, v97, v97 row_ror:4 row_mask:0xf bank_mask:0xf
	s_nop 0
	v_add_f32_dpp v96, v96, v96 row_ror:2 row_mask:0xf bank_mask:0xf
	s_nop 0
	v_add_f32_dpp v97, v97, v97 row_ror:2 row_mask:0xf bank_mask:0xf
	s_nop 0
	v_add_f32_dpp v96, v96, v96 row_ror:1 row_mask:0xf bank_mask:0xf
	s_nop 0
	v_add_f32_dpp v97, v97, v97 row_ror:1 row_mask:0xf bank_mask:0xf
	s_nop 0
	v_readlane_b32 s0, v96, 0
	v_readlane_b32 s1, v96, 16
	v_readlane_b32 s18, v96, 32
	v_readlane_b32 s19, v96, 48
	v_readlane_b32 s20, v97, 0
	v_readlane_b32 s21, v97, 16
	v_readlane_b32 s22, v97, 32
	v_readlane_b32 s23, v97, 48
	s_nop 1
	v_mov_b32_e32 v100, s0
	v_mov_b32_e32 v102, s20
	v_add_f32_e32 v100, s1, v100
	v_add_f32_e32 v102, s21, v102
	v_add_f32_e32 v100, s18, v100
	v_add_f32_e32 v102, s22, v102
	v_add_f32_e32 v100, s19, v100
	v_add_f32_e32 v102, s23, v102
	v_add_f32_dpp v98, v98, v98 row_ror:8 row_mask:0xf bank_mask:0xf
	s_nop 0
	v_add_f32_dpp v99, v99, v99 row_ror:8 row_mask:0xf bank_mask:0xf
	s_nop 0
	v_add_f32_dpp v98, v98, v98 row_ror:4 row_mask:0xf bank_mask:0xf
	s_nop 0
	v_add_f32_dpp v99, v99, v99 row_ror:4 row_mask:0xf bank_mask:0xf
	s_nop 0
	v_add_f32_dpp v98, v98, v98 row_ror:2 row_mask:0xf bank_mask:0xf
	s_nop 0
	v_add_f32_dpp v99, v99, v99 row_ror:2 row_mask:0xf bank_mask:0xf
	s_nop 0
	v_add_f32_dpp v98, v98, v98 row_ror:1 row_mask:0xf bank_mask:0xf
	s_nop 0
	v_add_f32_dpp v99, v99, v99 row_ror:1 row_mask:0xf bank_mask:0xf
	s_nop 0
	v_readlane_b32 s0, v98, 0
	v_readlane_b32 s1, v98, 16
	v_readlane_b32 s18, v98, 32
	v_readlane_b32 s19, v98, 48
	v_readlane_b32 s20, v99, 0
	v_readlane_b32 s21, v99, 16
	v_readlane_b32 s22, v99, 32
	v_readlane_b32 s23, v99, 48
	s_nop 1
	v_mov_b32_e32 v104, s0
	v_mov_b32_e32 v106, s20
	v_add_f32_e32 v104, s1, v104
	v_add_f32_e32 v106, s21, v106
	v_add_f32_e32 v104, s18, v104
	v_add_f32_e32 v106, s22, v106
	v_add_f32_e32 v104, s19, v104
	v_add_f32_e32 v106, s23, v106
	v_fmamk_f32 v100, v100, 0x3b800000, v197
	v_fmamk_f32 v102, v102, 0x3b800000, v197
	v_fmamk_f32 v104, v104, 0x3b800000, v197
	v_fmamk_f32 v106, v106, 0x3b800000, v197
	v_rsq_f32_e32 v100, v100
	v_rsq_f32_e32 v102, v102
	v_rsq_f32_e32 v104, v104
	v_rsq_f32_e32 v106, v106
	s_nop 0
	v_pk_mul_f32 v[80:81], v[100:101], v[80:81] op_sel_hi:[0,1]
	v_pk_mul_f32 v[82:83], v[100:101], v[82:83] op_sel_hi:[0,1]
	v_pk_mul_f32 v[84:85], v[102:103], v[84:85] op_sel_hi:[0,1]
	v_pk_mul_f32 v[86:87], v[102:103], v[86:87] op_sel_hi:[0,1]
	v_pk_mul_f32 v[88:89], v[104:105], v[88:89] op_sel_hi:[0,1]
	v_pk_mul_f32 v[90:91], v[104:105], v[90:91] op_sel_hi:[0,1]
	v_pk_mul_f32 v[92:93], v[106:107], v[92:93] op_sel_hi:[0,1]
	v_pk_mul_f32 v[94:95], v[106:107], v[94:95] op_sel_hi:[0,1]
	v_pk_mul_f32 v[80:81], v[2:3], v[80:81]
	v_pk_mul_f32 v[82:83], v[4:5], v[82:83]
	v_pk_mul_f32 v[84:85], v[6:7], v[84:85]
	v_pk_mul_f32 v[86:87], v[8:9], v[86:87]
	v_pk_mul_f32 v[88:89], v[10:11], v[88:89]
	v_pk_mul_f32 v[90:91], v[12:13], v[90:91]
	v_pk_mul_f32 v[92:93], v[14:15], v[92:93]
	v_pk_mul_f32 v[94:95], v[16:17], v[94:95]
	v_cvt_pk_bf16_f32 v18, v80, v81
	v_cvt_pk_bf16_f32 v19, v82, v83
	v_cvt_pk_bf16_f32 v20, v84, v85
	v_cvt_pk_bf16_f32 v21, v86, v87
	v_cvt_pk_bf16_f32 v22, v88, v89
	v_cvt_pk_bf16_f32 v23, v90, v91
	v_cvt_pk_bf16_f32 v24, v92, v93
	v_cvt_pk_bf16_f32 v25, v94, v95
	global_store_dwordx2 v1, v[18:19], s[10:11] offset:0
	global_store_dwordx2 v1, v[20:21], s[10:11] offset:512
	global_store_dwordx2 v1, v[22:23], s[10:11] offset:1024
	global_store_dwordx2 v1, v[24:25], s[10:11] offset:1536
	s_add_u32 s10, s10, 0x800
	s_addc_u32 s11, s11, 0
	s_waitcnt vmcnt(20)
	v_lshlrev_b32_e32 v80, 16, v28
	v_and_b32_e32 v81, 0xffff0000, v28
	v_lshlrev_b32_e32 v82, 16, v29
	v_and_b32_e32 v83, 0xffff0000, v29
	v_lshlrev_b32_e32 v84, 16, v30
	v_and_b32_e32 v85, 0xffff0000, v30
	v_lshlrev_b32_e32 v86, 16, v31
	v_and_b32_e32 v87, 0xffff0000, v31
	v_lshlrev_b32_e32 v88, 16, v32
	v_and_b32_e32 v89, 0xffff0000, v32
	v_lshlrev_b32_e32 v90, 16, v33
	v_and_b32_e32 v91, 0xffff0000, v33
	v_lshlrev_b32_e32 v92, 16, v34
	v_and_b32_e32 v93, 0xffff0000, v34
	v_lshlrev_b32_e32 v94, 16, v35
	v_and_b32_e32 v95, 0xffff0000, v35
	v_lshlrev_b32_e32 v114, 16, v36
	v_and_b32_e32 v115, 0xffff0000, v36
	v_lshlrev_b32_e32 v116, 16, v37
	v_and_b32_e32 v117, 0xffff0000, v37
	v_mul_f32_e32 v114, 0xbfb8aa3b, v114
	v_mul_f32_e32 v115, 0xbfb8aa3b, v115
	v_mul_f32_e32 v116, 0xbfb8aa3b, v116
	v_mul_f32_e32 v117, 0xbfb8aa3b, v117
	v_exp_f32_e32 v114, v114
	v_exp_f32_e32 v115, v115
	v_exp_f32_e32 v116, v116
	v_exp_f32_e32 v117, v117
	s_nop 0
	v_add_f32_e32 v114, 1.0, v114
	v_add_f32_e32 v115, 1.0, v115
	v_add_f32_e32 v116, 1.0, v116
	v_add_f32_e32 v117, 1.0, v117
	v_div_scale_f32 v108, s[22:23], v114, v114, 1.0
	v_rcp_f32_e32 v109, v108
	s_nop 0
	v_fma_f32 v110, -v108, v109, 1.0
	v_fmac_f32_e32 v109, v110, v109
	v_div_scale_f32 v110, vcc, 1.0, v114, 1.0
	v_mul_f32_e32 v111, v110, v109
	v_fma_f32 v112, -v108, v111, v110
	v_fmac_f32_e32 v111, v112, v109
	v_fma_f32 v108, -v108, v111, v110
	v_div_fmas_f32 v108, v108, v109, v111
	v_div_fixup_f32 v114, v108, v114, 1.0
	v_mul_f32_e32 v92, v114, v92
	v_div_scale_f32 v108, s[22:23], v115, v115, 1.0
	v_rcp_f32_e32 v109, v108
	s_nop 0
	v_fma_f32 v110, -v108, v109, 1.0
	v_fmac_f32_e32 v109, v110, v109
	v_div_scale_f32 v110, vcc, 1.0, v115, 1.0
	v_mul_f32_e32 v111, v110, v109
	v_fma_f32 v112, -v108, v111, v110
	v_fmac_f32_e32 v111, v112, v109
	v_fma_f32 v108, -v108, v111, v110
	v_div_fmas_f32 v108, v108, v109, v111
	v_div_fixup_f32 v115, v108, v115, 1.0
	v_mul_f32_e32 v93, v115, v93
	v_div_scale_f32 v108, s[22:23], v116, v116, 1.0
	v_rcp_f32_e32 v109, v108
	s_nop 0
	v_fma_f32 v110, -v108, v109, 1.0
	v_fmac_f32_e32 v109, v110, v109
	v_div_scale_f32 v110, vcc, 1.0, v116, 1.0
	v_mul_f32_e32 v111, v110, v109
	v_fma_f32 v112, -v108, v111, v110
	v_fmac_f32_e32 v111, v112, v109
	v_fma_f32 v108, -v108, v111, v110
	v_div_fmas_f32 v108, v108, v109, v111
	v_div_fixup_f32 v116, v108, v116, 1.0
	v_mul_f32_e32 v94, v116, v94
	v_div_scale_f32 v108, s[22:23], v117, v117, 1.0
	v_rcp_f32_e32 v109, v108
	s_nop 0
	v_fma_f32 v110, -v108, v109, 1.0
	v_fmac_f32_e32 v109, v110, v109
	v_div_scale_f32 v110, vcc, 1.0, v117, 1.0
	v_mul_f32_e32 v111, v110, v109
	v_fma_f32 v112, -v108, v111, v110
	v_fmac_f32_e32 v111, v112, v109
	v_fma_f32 v108, -v108, v111, v110
	v_div_fmas_f32 v108, v108, v109, v111
	v_div_fixup_f32 v117, v108, v117, 1.0
	v_mul_f32_e32 v95, v117, v95
	v_pk_mul_f32 v[108:109], v[80:81], v[80:81]
	v_pk_fma_f32 v[108:109], v[82:83], v[82:83], v[108:109]
	v_add_f32_e32 v96, v108, v109
	v_pk_mul_f32 v[110:111], v[84:85], v[84:85]
	v_pk_fma_f32 v[110:111], v[86:87], v[86:87], v[110:111]
	v_add_f32_e32 v97, v110, v111
	v_pk_mul_f32 v[108:109], v[88:89], v[88:89]
	v_pk_fma_f32 v[108:109], v[90:91], v[90:91], v[108:109]
	v_add_f32_e32 v98, v108, v109
	v_pk_mul_f32 v[110:111], v[92:93], v[92:93]
	v_pk_fma_f32 v[110:111], v[94:95], v[94:95], v[110:111]
	v_add_f32_e32 v99, v110, v111
	v_add_f32_dpp v96, v96, v96 row_ror:8 row_mask:0xf bank_mask:0xf
	s_nop 0
	v_add_f32_dpp v97, v97, v97 row_ror:8 row_mask:0xf bank_mask:0xf
	s_nop 0
	v_add_f32_dpp v96, v96, v96 row_ror:4 row_mask:0xf bank_mask:0xf
	s_nop 0
	v_add_f32_dpp v97, v97, v97 row_ror:4 row_mask:0xf bank_mask:0xf
	s_nop 0
	v_add_f32_dpp v96, v96, v96 row_ror:2 row_mask:0xf bank_mask:0xf
	s_nop 0
	v_add_f32_dpp v97, v97, v97 row_ror:2 row_mask:0xf bank_mask:0xf
	s_nop 0
	v_add_f32_dpp v96, v96, v96 row_ror:1 row_mask:0xf bank_mask:0xf
	s_nop 0
	v_add_f32_dpp v97, v97, v97 row_ror:1 row_mask:0xf bank_mask:0xf
	s_nop 0
	v_readlane_b32 s0, v96, 0
	v_readlane_b32 s1, v96, 16
	v_readlane_b32 s18, v96, 32
	v_readlane_b32 s19, v96, 48
	v_readlane_b32 s20, v97, 0
	v_readlane_b32 s21, v97, 16
	v_readlane_b32 s22, v97, 32
	v_readlane_b32 s23, v97, 48
	s_nop 1
	v_mov_b32_e32 v100, s0
	v_mov_b32_e32 v102, s20
	v_add_f32_e32 v100, s1, v100
	v_add_f32_e32 v102, s21, v102
	v_add_f32_e32 v100, s18, v100
	v_add_f32_e32 v102, s22, v102
	v_add_f32_e32 v100, s19, v100
	v_add_f32_e32 v102, s23, v102
	v_add_f32_dpp v98, v98, v98 row_ror:8 row_mask:0xf bank_mask:0xf
	s_nop 0
	v_add_f32_dpp v99, v99, v99 row_ror:8 row_mask:0xf bank_mask:0xf
	s_nop 0
	v_add_f32_dpp v98, v98, v98 row_ror:4 row_mask:0xf bank_mask:0xf
	s_nop 0
	v_add_f32_dpp v99, v99, v99 row_ror:4 row_mask:0xf bank_mask:0xf
	s_nop 0
	v_add_f32_dpp v98, v98, v98 row_ror:2 row_mask:0xf bank_mask:0xf
	s_nop 0
	v_add_f32_dpp v99, v99, v99 row_ror:2 row_mask:0xf bank_mask:0xf
	s_nop 0
	v_add_f32_dpp v98, v98, v98 row_ror:1 row_mask:0xf bank_mask:0xf
	s_nop 0
	v_add_f32_dpp v99, v99, v99 row_ror:1 row_mask:0xf bank_mask:0xf
	s_nop 0
	v_readlane_b32 s0, v98, 0
	v_readlane_b32 s1, v98, 16
	v_readlane_b32 s18, v98, 32
	v_readlane_b32 s19, v98, 48
	v_readlane_b32 s20, v99, 0
	v_readlane_b32 s21, v99, 16
	v_readlane_b32 s22, v99, 32
	v_readlane_b32 s23, v99, 48
	s_nop 1
	v_mov_b32_e32 v104, s0
	v_mov_b32_e32 v106, s20
	v_add_f32_e32 v104, s1, v104
	v_add_f32_e32 v106, s21, v106
	v_add_f32_e32 v104, s18, v104
	v_add_f32_e32 v106, s22, v106
	v_add_f32_e32 v104, s19, v104
	v_add_f32_e32 v106, s23, v106
	v_fmamk_f32 v100, v100, 0x3b800000, v197
	v_fmamk_f32 v102, v102, 0x3b800000, v197
	v_fmamk_f32 v104, v104, 0x3b800000, v197
	v_fmamk_f32 v106, v106, 0x3b800000, v197
	v_rsq_f32_e32 v100, v100
	v_rsq_f32_e32 v102, v102
	v_rsq_f32_e32 v104, v104
	v_rsq_f32_e32 v106, v106
	s_nop 0
	v_pk_mul_f32 v[80:81], v[100:101], v[80:81] op_sel_hi:[0,1]
	v_pk_mul_f32 v[82:83], v[100:101], v[82:83] op_sel_hi:[0,1]
	v_pk_mul_f32 v[84:85], v[102:103], v[84:85] op_sel_hi:[0,1]
	v_pk_mul_f32 v[86:87], v[102:103], v[86:87] op_sel_hi:[0,1]
	v_pk_mul_f32 v[88:89], v[104:105], v[88:89] op_sel_hi:[0,1]
	v_pk_mul_f32 v[90:91], v[104:105], v[90:91] op_sel_hi:[0,1]
	v_pk_mul_f32 v[92:93], v[106:107], v[92:93] op_sel_hi:[0,1]
	v_pk_mul_f32 v[94:95], v[106:107], v[94:95] op_sel_hi:[0,1]
	v_pk_mul_f32 v[80:81], v[2:3], v[80:81]
	v_pk_mul_f32 v[82:83], v[4:5], v[82:83]
	v_pk_mul_f32 v[84:85], v[6:7], v[84:85]
	v_pk_mul_f32 v[86:87], v[8:9], v[86:87]
	v_pk_mul_f32 v[88:89], v[10:11], v[88:89]
	v_pk_mul_f32 v[90:91], v[12:13], v[90:91]
	v_pk_mul_f32 v[92:93], v[14:15], v[92:93]
	v_pk_mul_f32 v[94:95], v[16:17], v[94:95]
	v_cvt_pk_bf16_f32 v28, v80, v81
	v_cvt_pk_bf16_f32 v29, v82, v83
	v_cvt_pk_bf16_f32 v30, v84, v85
	v_cvt_pk_bf16_f32 v31, v86, v87
	v_cvt_pk_bf16_f32 v32, v88, v89
	v_cvt_pk_bf16_f32 v33, v90, v91
	v_cvt_pk_bf16_f32 v34, v92, v93
	v_cvt_pk_bf16_f32 v35, v94, v95
	global_store_dwordx2 v1, v[28:29], s[10:11] offset:0
	global_store_dwordx2 v1, v[30:31], s[10:11] offset:512
	global_store_dwordx2 v1, v[32:33], s[10:11] offset:1024
	global_store_dwordx2 v1, v[34:35], s[10:11] offset:1536
.Lrn_gn_end:
.LBB0_624:
	s_bitcmp0_b32 s94, 16
	s_cbranch_scc1 .LBB0_632
	v_lshlrev_b32_e32 v0, 4, v205
	v_lshlrev_b32_e32 v1, 3, v205
	v_readlane_b32 s0, v245, 21
	v_readlane_b32 s6, v247, 29
	v_readlane_b32 s7, v247, 30
	s_add_u32 s8, s4, 0x3800000
	s_addc_u32 s9, s5, 0
	s_lshl_b32 s1, s0, 15
	s_add_u32 s6, s6, s1
	s_addc_u32 s7, s7, 0
	s_lshl_b32 s1, s0, 12
	s_add_u32 s8, s8, s1
	s_addc_u32 s9, s9, 0
	s_lshl_b32 s1, s0, 14
	s_add_u32 s1, s1, 0x3e00000
	s_add_u32 s10, s4, s1
	s_addc_u32 s11, s5, 0
	s_lshl_b32 s1, s0, 11
	s_add_u32 s1, s1, 0x3c00000
	s_add_u32 s12, s4, s1
	s_addc_u32 s13, s5, 0
	s_lshl_b32 s1, s24, 12
	s_add_u32 s1, s1, 0x225320
	s_add_u32 s14, s4, s1
	s_addc_u32 s15, s5, 0
	s_mul_i32 s1, s24, 0x1e000
	s_add_u32 s16, s4, s1
	s_addc_u32 s17, s5, 0
	s_lshr_b32 s1, s0, 9
	s_mul_i32 s1, s1, 0x6000
	s_add_u32 s1, s1, 0x3000
	s_add_u32 s18, s16, s1
	s_addc_u32 s19, s17, 0
	s_add_u32 s16, s16, 0x1b000
	s_addc_u32 s17, s17, 0
	s_cmp_lt_u32 s0, 0x400
	s_cselect_b32 s1, 1, 0
	s_cmp_eq_u32 s27, 0
	s_cselect_b32 s1, s1, 0
	s_cmp_eq_u32 s1, 1
	s_cbranch_scc0 .Lrn_p3_noctx
	global_load_dwordx4 v[2:5], v0, s[14:15] offset:0
	global_load_dwordx4 v[6:9], v0, s[14:15] offset:1024
	global_load_dwordx4 v[10:13], v0, s[14:15] offset:2048
	global_load_dwordx4 v[14:17], v0, s[14:15] offset:3072
	s_add_u32 s20, s16, 0x1000
	s_addc_u32 s21, s17, 0
	global_load_dwordx4 v[18:21], v0, s[20:21] offset:0
	global_load_dwordx4 v[22:25], v0, s[20:21] offset:1024
	global_load_dwordx4 v[26:29], v0, s[20:21] offset:2048
	global_load_dwordx4 v[30:33], v0, s[20:21] offset:3072
	global_load_dwordx4 v[34:37], v0, s[16:17] offset:0
	global_load_dwordx4 v[38:41], v0, s[16:17] offset:1024
	global_load_dwordx4 v[42:45], v0, s[16:17] offset:2048
	global_load_dwordx4 v[46:49], v0, s[16:17] offset:3072
	global_load_dwordx4 v[82:85], v0, s[8:9] offset:0
	global_load_dwordx4 v[86:89], v0, s[8:9] offset:1024
	global_load_dwordx4 v[90:93], v0, s[8:9] offset:2048
	global_load_dwordx4 v[94:97], v0, s[8:9] offset:3072
	s_add_u32 s20, s18, 0x1000
	s_addc_u32 s21, s19, 0
	global_load_dwordx4 v[50:53], v0, s[20:21] offset:0
	global_load_dwordx4 v[54:57], v0, s[20:21] offset:1024
	global_load_dwordx4 v[58:61], v0, s[20:21] offset:2048
	global_load_dwordx4 v[62:65], v0, s[20:21] offset:3072
	global_load_dwordx4 v[66:69], v0, s[18:19] offset:0
	global_load_dwordx4 v[70:73], v0, s[18:19] offset:1024
	global_load_dwordx4 v[74:77], v0, s[18:19] offset:2048
	global_load_dwordx4 v[78:81], v0, s[18:19] offset:3072
	global_load_dwordx4 v[98:101], v0, s[6:7] offset:0
	global_load_dwordx4 v[102:105], v0, s[6:7] offset:1024
	global_load_dwordx4 v[106:109], v0, s[6:7] offset:2048
	global_load_dwordx4 v[110:113], v0, s[6:7] offset:3072
	s_add_u32 s6, s6, 0x1000
	s_addc_u32 s7, s7, 0
	global_load_dwordx4 v[114:117], v0, s[6:7] offset:0
	global_load_dwordx4 v[118:121], v0, s[6:7] offset:1024
	global_load_dwordx4 v[122:125], v0, s[6:7] offset:2048
	global_load_dwordx4 v[126:129], v0, s[6:7] offset:3072
	s_add_u32 s6, s6, 0x1000
	s_addc_u32 s7, s7, 0
	global_load_dwordx4 v[138:141], v0, s[6:7] offset:0
	global_load_dwordx4 v[142:145], v0, s[6:7] offset:1024
	global_load_dwordx4 v[146:149], v0, s[6:7] offset:2048
	global_load_dwordx4 v[150:153], v0, s[6:7] offset:3072
	s_add_u32 s6, s6, 0x1000
	s_addc_u32 s7, s7, 0
	global_load_dwordx4 v[154:157], v0, s[6:7] offset:0
	global_load_dwordx4 v[158:161], v0, s[6:7] offset:1024
	global_load_dwordx4 v[162:165], v0, s[6:7] offset:2048
	global_load_dwordx4 v[166:169], v0, s[6:7] offset:3072
	s_add_u32 s6, s6, 0x1000
	s_addc_u32 s7, s7, 0
	global_load_dwordx4 v[170:173], v0, s[6:7] offset:0
	global_load_dwordx4 v[174:177], v0, s[6:7] offset:1024
	global_load_dwordx4 v[178:181], v0, s[6:7] offset:2048
	global_load_dwordx4 v[182:185], v0, s[6:7] offset:3072
	s_add_u32 s6, s6, 0x1000
	s_addc_u32 s7, s7, 0
	s_waitcnt vmcnt(28)
	v_pk_mul_f32 v[130:131], v[82:83], v[82:83]
	v_pk_fma_f32 v[130:131], v[84:85], v[84:85], v[130:131]
	v_pk_fma_f32 v[130:131], v[86:87], v[86:87], v[130:131]
	v_pk_fma_f32 v[130:131], v[88:89], v[88:89], v[130:131]
	v_pk_fma_f32 v[130:131], v[90:91], v[90:91], v[130:131]
	v_pk_fma_f32 v[130:131], v[92:93], v[92:93], v[130:131]
	v_pk_fma_f32 v[130:131], v[94:95], v[94:95], v[130:131]
	v_pk_fma_f32 v[130:131], v[96:97], v[96:97], v[130:131]
	v_add_f32_e32 v130, v130, v131
	s_nop 1
	v_add_f32_dpp v130, v130, v130 row_ror:8 row_mask:0xf bank_mask:0xf
	s_nop 1
	v_add_f32_dpp v130, v130, v130 row_ror:4 row_mask:0xf bank_mask:0xf
	s_nop 1
	v_add_f32_dpp v130, v130, v130 row_ror:2 row_mask:0xf bank_mask:0xf
	s_nop 1
	v_add_f32_dpp v130, v130, v130 row_ror:1 row_mask:0xf bank_mask:0xf
	s_nop 1
	s_nop 0
	v_readlane_b32 s0, v130, 0
	v_readlane_b32 s1, v130, 16
	v_readlane_b32 s22, v130, 32
	v_readlane_b32 s23, v130, 48
	s_nop 1
	v_mov_b32_e32 v132, s0
	v_add_f32_e32 v132, s1, v132
	v_add_f32_e32 v132, s22, v132
	v_add_f32_e32 v132, s23, v132
	v_fmamk_f32 v132, v132, 0x3a800000, v197
	v_rsq_f32_e32 v132, v132
	s_nop 0
	v_pk_add_f32 v[18:19], v[18:19], 1.0 op_sel_hi:[1,0]
	v_pk_add_f32 v[20:21], v[20:21], 1.0 op_sel_hi:[1,0]
	v_pk_add_f32 v[22:23], v[22:23], 1.0 op_sel_hi:[1,0]
	v_pk_add_f32 v[24:25], v[24:25], 1.0 op_sel_hi:[1,0]
	v_pk_add_f32 v[26:27], v[26:27], 1.0 op_sel_hi:[1,0]
	v_pk_add_f32 v[28:29], v[28:29], 1.0 op_sel_hi:[1,0]
	v_pk_add_f32 v[30:31], v[30:31], 1.0 op_sel_hi:[1,0]
	v_pk_add_f32 v[32:33], v[32:33], 1.0 op_sel_hi:[1,0]
	v_pk_mul_f32 v[82:83], v[82:83], v[132:133] op_sel_hi:[1,0]
	v_pk_mul_f32 v[84:85], v[84:85], v[132:133] op_sel_hi:[1,0]
	v_pk_mul_f32 v[86:87], v[86:87], v[132:133] op_sel_hi:[1,0]
	v_pk_mul_f32 v[88:89], v[88:89], v[132:133] op_sel_hi:[1,0]
	v_pk_mul_f32 v[90:91], v[90:91], v[132:133] op_sel_hi:[1,0]
	v_pk_mul_f32 v[92:93], v[92:93], v[132:133] op_sel_hi:[1,0]
	v_pk_mul_f32 v[94:95], v[94:95], v[132:133] op_sel_hi:[1,0]
	v_pk_mul_f32 v[96:97], v[96:97], v[132:133] op_sel_hi:[1,0]
	v_pk_mul_f32 v[82:83], v[2:3], v[82:83]
	v_pk_mul_f32 v[84:85], v[4:5], v[84:85]
	v_pk_mul_f32 v[86:87], v[6:7], v[86:87]
	v_pk_mul_f32 v[88:89], v[8:9], v[88:89]
	v_pk_mul_f32 v[90:91], v[10:11], v[90:91]
	v_pk_mul_f32 v[92:93], v[12:13], v[92:93]
	v_pk_mul_f32 v[94:95], v[14:15], v[94:95]
	v_pk_mul_f32 v[96:97], v[16:17], v[96:97]
	v_pk_fma_f32 v[82:83], v[18:19], v[82:83], v[34:35]
	v_pk_fma_f32 v[84:85], v[20:21], v[84:85], v[36:37]
	v_pk_fma_f32 v[86:87], v[22:23], v[86:87], v[38:39]
	v_pk_fma_f32 v[88:89], v[24:25], v[88:89], v[40:41]
	v_pk_fma_f32 v[90:91], v[26:27], v[90:91], v[42:43]
	v_pk_fma_f32 v[92:93], v[28:29], v[92:93], v[44:45]
	v_pk_fma_f32 v[94:95], v[30:31], v[94:95], v[46:47]
	v_pk_fma_f32 v[96:97], v[32:33], v[96:97], v[48:49]
	v_cvt_pk_bf16_f32 v82, v82, v83
	v_cvt_pk_bf16_f32 v83, v84, v85
	v_cvt_pk_bf16_f32 v84, v86, v87
	v_cvt_pk_bf16_f32 v85, v88, v89
	v_cvt_pk_bf16_f32 v86, v90, v91
	v_cvt_pk_bf16_f32 v87, v92, v93
	v_cvt_pk_bf16_f32 v88, v94, v95
	v_cvt_pk_bf16_f32 v89, v96, v97
	global_store_dwordx2 v1, v[82:83], s[12:13] offset:0
	global_store_dwordx2 v1, v[84:85], s[12:13] offset:512
	global_store_dwordx2 v1, v[86:87], s[12:13] offset:1024
	global_store_dwordx2 v1, v[88:89], s[12:13] offset:1536
	global_load_dwordx4 v[82:85], v0, s[6:7] offset:0
	global_load_dwordx4 v[86:89], v0, s[6:7] offset:1024
	global_load_dwordx4 v[90:93], v0, s[6:7] offset:2048
	global_load_dwordx4 v[94:97], v0, s[6:7] offset:3072
	s_add_u32 s6, s6, 0x1000
	s_addc_u32 s7, s7, 0
	s_waitcnt vmcnt(24)
	v_pk_mul_f32 v[130:131], v[98:99], v[98:99]
	v_pk_fma_f32 v[130:131], v[100:101], v[100:101], v[130:131]
	v_pk_fma_f32 v[130:131], v[102:103], v[102:103], v[130:131]
	v_pk_fma_f32 v[130:131], v[104:105], v[104:105], v[130:131]
	v_pk_fma_f32 v[130:131], v[106:107], v[106:107], v[130:131]
	v_pk_fma_f32 v[130:131], v[108:109], v[108:109], v[130:131]
	v_pk_fma_f32 v[130:131], v[110:111], v[110:111], v[130:131]
	v_pk_fma_f32 v[130:131], v[112:113], v[112:113], v[130:131]
	v_add_f32_e32 v130, v130, v131
	s_nop 1
	v_add_f32_dpp v130, v130, v130 row_ror:8 row_mask:0xf bank_mask:0xf
	s_nop 1
	v_add_f32_dpp v130, v130, v130 row_ror:4 row_mask:0xf bank_mask:0xf
	s_nop 1
	v_add_f32_dpp v130, v130, v130 row_ror:2 row_mask:0xf bank_mask:0xf
	s_nop 1
	v_add_f32_dpp v130, v130, v130 row_ror:1 row_mask:0xf bank_mask:0xf
	s_nop 1
	s_nop 0
	v_readlane_b32 s0, v130, 0
	v_readlane_b32 s1, v130, 16
	v_readlane_b32 s22, v130, 32
	v_readlane_b32 s23, v130, 48
	s_nop 1
	v_mov_b32_e32 v132, s0
	v_add_f32_e32 v132, s1, v132
	v_add_f32_e32 v132, s22, v132
	v_add_f32_e32 v132, s23, v132
	v_fmamk_f32 v132, v132, 0x3a800000, v197
	v_rsq_f32_e32 v132, v132
	s_nop 0
	v_pk_add_f32 v[50:51], v[50:51], 1.0 op_sel_hi:[1,0]
	v_pk_add_f32 v[52:53], v[52:53], 1.0 op_sel_hi:[1,0]
	v_pk_add_f32 v[54:55], v[54:55], 1.0 op_sel_hi:[1,0]
	v_pk_add_f32 v[56:57], v[56:57], 1.0 op_sel_hi:[1,0]
	v_pk_add_f32 v[58:59], v[58:59], 1.0 op_sel_hi:[1,0]
	v_pk_add_f32 v[60:61], v[60:61], 1.0 op_sel_hi:[1,0]
	v_pk_add_f32 v[62:63], v[62:63], 1.0 op_sel_hi:[1,0]
	v_pk_add_f32 v[64:65], v[64:65], 1.0 op_sel_hi:[1,0]
	v_pk_mul_f32 v[98:99], v[98:99], v[132:133] op_sel_hi:[1,0]
	v_pk_mul_f32 v[100:101], v[100:101], v[132:133] op_sel_hi:[1,0]
	v_pk_mul_f32 v[102:103], v[102:103], v[132:133] op_sel_hi:[1,0]
	v_pk_mul_f32 v[104:105], v[104:105], v[132:133] op_sel_hi:[1,0]
	v_pk_mul_f32 v[106:107], v[106:107], v[132:133] op_sel_hi:[1,0]
	v_pk_mul_f32 v[108:109], v[108:109], v[132:133] op_sel_hi:[1,0]
	v_pk_mul_f32 v[110:111], v[110:111], v[132:133] op_sel_hi:[1,0]
	v_pk_mul_f32 v[112:113], v[112:113], v[132:133] op_sel_hi:[1,0]
	v_pk_mul_f32 v[98:99], v[2:3], v[98:99]
	v_pk_mul_f32 v[100:101], v[4:5], v[100:101]
	v_pk_mul_f32 v[102:103], v[6:7], v[102:103]
	v_pk_mul_f32 v[104:105], v[8:9], v[104:105]
	v_pk_mul_f32 v[106:107], v[10:11], v[106:107]
	v_pk_mul_f32 v[108:109], v[12:13], v[108:109]
	v_pk_mul_f32 v[110:111], v[14:15], v[110:111]
	v_pk_mul_f32 v[112:113], v[16:17], v[112:113]
	v_pk_fma_f32 v[98:99], v[50:51], v[98:99], v[66:67]
	v_pk_fma_f32 v[100:101], v[52:53], v[100:101], v[68:69]
	v_pk_fma_f32 v[102:103], v[54:55], v[102:103], v[70:71]
	v_pk_fma_f32 v[104:105], v[56:57], v[104:105], v[72:73]
	v_pk_fma_f32 v[106:107], v[58:59], v[106:107], v[74:75]
	v_pk_fma_f32 v[108:109], v[60:61], v[108:109], v[76:77]
	v_pk_fma_f32 v[110:111], v[62:63], v[110:111], v[78:79]
	v_pk_fma_f32 v[112:113], v[64:65], v[112:113], v[80:81]
	v_cvt_pk_bf16_f32 v98, v98, v99
	v_cvt_pk_bf16_f32 v99, v100, v101
	v_cvt_pk_bf16_f32 v100, v102, v103
	v_cvt_pk_bf16_f32 v101, v104, v105
	v_cvt_pk_bf16_f32 v102, v106, v107
	v_cvt_pk_bf16_f32 v103, v108, v109
	v_cvt_pk_bf16_f32 v104, v110, v111
	v_cvt_pk_bf16_f32 v105, v112, v113
	global_store_dwordx2 v1, v[98:99], s[10:11] offset:0
	global_store_dwordx2 v1, v[100:101], s[10:11] offset:512
	global_store_dwordx2 v1, v[102:103], s[10:11] offset:1024
	global_store_dwordx2 v1, v[104:105], s[10:11] offset:1536
	s_add_u32 s10, s10, 0x800
	s_addc_u32 s11, s11, 0
	global_load_dwordx4 v[98:101], v0, s[6:7] offset:0
	global_load_dwordx4 v[102:105], v0, s[6:7] offset:1024
	global_load_dwordx4 v[106:109], v0, s[6:7] offset:2048
	global_load_dwordx4 v[110:113], v0, s[6:7] offset:3072
	s_add_u32 s6, s6, 0x1000
	s_addc_u32 s7, s7, 0
	s_waitcnt vmcnt(28)
	v_pk_mul_f32 v[130:131], v[114:115], v[114:115]
	v_pk_fma_f32 v[130:131], v[116:117], v[116:117], v[130:131]
	v_pk_fma_f32 v[130:131], v[118:119], v[118:119], v[130:131]
	v_pk_fma_f32 v[130:131], v[120:121], v[120:121], v[130:131]
	v_pk_fma_f32 v[130:131], v[122:123], v[122:123], v[130:131]
	v_pk_fma_f32 v[130:131], v[124:125], v[124:125], v[130:131]
	v_pk_fma_f32 v[130:131], v[126:127], v[126:127], v[130:131]
	v_pk_fma_f32 v[130:131], v[128:129], v[128:129], v[130:131]
	v_add_f32_e32 v130, v130, v131
	s_nop 1
	v_add_f32_dpp v130, v130, v130 row_ror:8 row_mask:0xf bank_mask:0xf
	s_nop 1
	v_add_f32_dpp v130, v130, v130 row_ror:4 row_mask:0xf bank_mask:0xf
	s_nop 1
	v_add_f32_dpp v130, v130, v130 row_ror:2 row_mask:0xf bank_mask:0xf
	s_nop 1
	v_add_f32_dpp v130, v130, v130 row_ror:1 row_mask:0xf bank_mask:0xf
	s_nop 1
	s_nop 0
	v_readlane_b32 s0, v130, 0
	v_readlane_b32 s1, v130, 16
	v_readlane_b32 s22, v130, 32
	v_readlane_b32 s23, v130, 48
	s_nop 1
	v_mov_b32_e32 v132, s0
	v_add_f32_e32 v132, s1, v132
	v_add_f32_e32 v132, s22, v132
	v_add_f32_e32 v132, s23, v132
	v_fmamk_f32 v132, v132, 0x3a800000, v197
	v_rsq_f32_e32 v132, v132
	s_nop 0
	v_pk_mul_f32 v[114:115], v[114:115], v[132:133] op_sel_hi:[1,0]
	v_pk_mul_f32 v[116:117], v[116:117], v[132:133] op_sel_hi:[1,0]
	v_pk_mul_f32 v[118:119], v[118:119], v[132:133] op_sel_hi:[1,0]
	v_pk_mul_f32 v[120:121], v[120:121], v[132:133] op_sel_hi:[1,0]
	v_pk_mul_f32 v[122:123], v[122:123], v[132:133] op_sel_hi:[1,0]
	v_pk_mul_f32 v[124:125], v[124:125], v[132:133] op_sel_hi:[1,0]
	v_pk_mul_f32 v[126:127], v[126:127], v[132:133] op_sel_hi:[1,0]
	v_pk_mul_f32 v[128:129], v[128:129], v[132:133] op_sel_hi:[1,0]
	v_pk_mul_f32 v[114:115], v[2:3], v[114:115]
	v_pk_mul_f32 v[116:117], v[4:5], v[116:117]
	v_pk_mul_f32 v[118:119], v[6:7], v[118:119]
	v_pk_mul_f32 v[120:121], v[8:9], v[120:121]
	v_pk_mul_f32 v[122:123], v[10:11], v[122:123]
	v_pk_mul_f32 v[124:125], v[12:13], v[124:125]
	v_pk_mul_f32 v[126:127], v[14:15], v[126:127]
	v_pk_mul_f32 v[128:129], v[16:17], v[128:129]
	v_pk_fma_f32 v[114:115], v[50:51], v[114:115], v[66:67]
	v_pk_fma_f32 v[116:117], v[52:53], v[116:117], v[68:69]
	v_pk_fma_f32 v[118:119], v[54:55], v[118:119], v[70:71]
	v_pk_fma_f32 v[120:121], v[56:57], v[120:121], v[72:73]
	v_pk_fma_f32 v[122:123], v[58:59], v[122:123], v[74:75]
	v_pk_fma_f32 v[124:125], v[60:61], v[124:125], v[76:77]
	v_pk_fma_f32 v[126:127], v[62:63], v[126:127], v[78:79]
	v_pk_fma_f32 v[128:129], v[64:65], v[128:129], v[80:81]
	v_cvt_pk_bf16_f32 v114, v114, v115
	v_cvt_pk_bf16_f32 v115, v116, v117
	v_cvt_pk_bf16_f32 v116, v118, v119
	v_cvt_pk_bf16_f32 v117, v120, v121
	v_cvt_pk_bf16_f32 v118, v122, v123
	v_cvt_pk_bf16_f32 v119, v124, v125
	v_cvt_pk_bf16_f32 v120, v126, v127
	v_cvt_pk_bf16_f32 v121, v128, v129
	global_store_dwordx2 v1, v[114:115], s[10:11] offset:0
	global_store_dwordx2 v1, v[116:117], s[10:11] offset:512
	global_store_dwordx2 v1, v[118:119], s[10:11] offset:1024
	global_store_dwordx2 v1, v[120:121], s[10:11] offset:1536
	s_add_u32 s10, s10, 0x800
	s_addc_u32 s11, s11, 0
	global_load_dwordx4 v[114:117], v0, s[6:7] offset:0
	global_load_dwordx4 v[118:121], v0, s[6:7] offset:1024
	global_load_dwordx4 v[122:125], v0, s[6:7] offset:2048
	global_load_dwordx4 v[126:129], v0, s[6:7] offset:3072
	s_waitcnt vmcnt(32)
	v_pk_mul_f32 v[130:131], v[138:139], v[138:139]
	v_pk_fma_f32 v[130:131], v[140:141], v[140:141], v[130:131]
	v_pk_fma_f32 v[130:131], v[142:143], v[142:143], v[130:131]
	v_pk_fma_f32 v[130:131], v[144:145], v[144:145], v[130:131]
	v_pk_fma_f32 v[130:131], v[146:147], v[146:147], v[130:131]
	v_pk_fma_f32 v[130:131], v[148:149], v[148:149], v[130:131]
	v_pk_fma_f32 v[130:131], v[150:151], v[150:151], v[130:131]
	v_pk_fma_f32 v[130:131], v[152:153], v[152:153], v[130:131]
	v_add_f32_e32 v130, v130, v131
	s_nop 1
	v_add_f32_dpp v130, v130, v130 row_ror:8 row_mask:0xf bank_mask:0xf
	s_nop 1
	v_add_f32_dpp v130, v130, v130 row_ror:4 row_mask:0xf bank_mask:0xf
	s_nop 1
	v_add_f32_dpp v130, v130, v130 row_ror:2 row_mask:0xf bank_mask:0xf
	s_nop 1
	v_add_f32_dpp v130, v130, v130 row_ror:1 row_mask:0xf bank_mask:0xf
	s_nop 1
	s_nop 0
	v_readlane_b32 s0, v130, 0
	v_readlane_b32 s1, v130, 16
	v_readlane_b32 s22, v130, 32
	v_readlane_b32 s23, v130, 48
	s_nop 1
	v_mov_b32_e32 v132, s0
	v_add_f32_e32 v132, s1, v132
	v_add_f32_e32 v132, s22, v132
	v_add_f32_e32 v132, s23, v132
	v_fmamk_f32 v132, v132, 0x3a800000, v197
	v_rsq_f32_e32 v132, v132
	s_nop 0
	v_pk_mul_f32 v[138:139], v[138:139], v[132:133] op_sel_hi:[1,0]
	v_pk_mul_f32 v[140:141], v[140:141], v[132:133] op_sel_hi:[1,0]
	v_pk_mul_f32 v[142:143], v[142:143], v[132:133] op_sel_hi:[1,0]
	v_pk_mul_f32 v[144:145], v[144:145], v[132:133] op_sel_hi:[1,0]
	v_pk_mul_f32 v[146:147], v[146:147], v[132:133] op_sel_hi:[1,0]
	v_pk_mul_f32 v[148:149], v[148:149], v[132:133] op_sel_hi:[1,0]
	v_pk_mul_f32 v[150:151], v[150:151], v[132:133] op_sel_hi:[1,0]
	v_pk_mul_f32 v[152:153], v[152:153], v[132:133] op_sel_hi:[1,0]
	v_pk_mul_f32 v[138:139], v[2:3], v[138:139]
	v_pk_mul_f32 v[140:141], v[4:5], v[140:141]
	v_pk_mul_f32 v[142:143], v[6:7], v[142:143]
	v_pk_mul_f32 v[144:145], v[8:9], v[144:145]
	v_pk_mul_f32 v[146:147], v[10:11], v[146:147]
	v_pk_mul_f32 v[148:149], v[12:13], v[148:149]
	v_pk_mul_f32 v[150:151], v[14:15], v[150:151]
	v_pk_mul_f32 v[152:153], v[16:17], v[152:153]
	v_pk_fma_f32 v[138:139], v[50:51], v[138:139], v[66:67]
	v_pk_fma_f32 v[140:141], v[52:53], v[140:141], v[68:69]
	v_pk_fma_f32 v[142:143], v[54:55], v[142:143], v[70:71]
	v_pk_fma_f32 v[144:145], v[56:57], v[144:145], v[72:73]
	v_pk_fma_f32 v[146:147], v[58:59], v[146:147], v[74:75]
	v_pk_fma_f32 v[148:149], v[60:61], v[148:149], v[76:77]
	v_pk_fma_f32 v[150:151], v[62:63], v[150:151], v[78:79]
	v_pk_fma_f32 v[152:153], v[64:65], v[152:153], v[80:81]
	v_cvt_pk_bf16_f32 v138, v138, v139
	v_cvt_pk_bf16_f32 v139, v140, v141
	v_cvt_pk_bf16_f32 v140, v142, v143
	v_cvt_pk_bf16_f32 v141, v144, v145
	v_cvt_pk_bf16_f32 v142, v146, v147
	v_cvt_pk_bf16_f32 v143, v148, v149
	v_cvt_pk_bf16_f32 v144, v150, v151
	v_cvt_pk_bf16_f32 v145, v152, v153
	global_store_dwordx2 v1, v[138:139], s[10:11] offset:0
	global_store_dwordx2 v1, v[140:141], s[10:11] offset:512
	global_store_dwordx2 v1, v[142:143], s[10:11] offset:1024
	global_store_dwordx2 v1, v[144:145], s[10:11] offset:1536
	s_add_u32 s10, s10, 0x800
	s_addc_u32 s11, s11, 0
	s_waitcnt vmcnt(32)
	v_pk_mul_f32 v[130:131], v[154:155], v[154:155]
	v_pk_fma_f32 v[130:131], v[156:157], v[156:157], v[130:131]
	v_pk_fma_f32 v[130:131], v[158:159], v[158:159], v[130:131]
	v_pk_fma_f32 v[130:131], v[160:161], v[160:161], v[130:131]
	v_pk_fma_f32 v[130:131], v[162:163], v[162:163], v[130:131]
	v_pk_fma_f32 v[130:131], v[164:165], v[164:165], v[130:131]
	v_pk_fma_f32 v[130:131], v[166:167], v[166:167], v[130:131]
	v_pk_fma_f32 v[130:131], v[168:169], v[168:169], v[130:131]
	v_add_f32_e32 v130, v130, v131
	s_nop 1
	v_add_f32_dpp v130, v130, v130 row_ror:8 row_mask:0xf bank_mask:0xf
	s_nop 1
	v_add_f32_dpp v130, v130, v130 row_ror:4 row_mask:0xf bank_mask:0xf
	s_nop 1
	v_add_f32_dpp v130, v130, v130 row_ror:2 row_mask:0xf bank_mask:0xf
	s_nop 1
	v_add_f32_dpp v130, v130, v130 row_ror:1 row_mask:0xf bank_mask:0xf
	s_nop 1
	s_nop 0
	v_readlane_b32 s0, v130, 0
	v_readlane_b32 s1, v130, 16
	v_readlane_b32 s22, v130, 32
	v_readlane_b32 s23, v130, 48
	s_nop 1
	v_mov_b32_e32 v132, s0
	v_add_f32_e32 v132, s1, v132
	v_add_f32_e32 v132, s22, v132
	v_add_f32_e32 v132, s23, v132
	v_fmamk_f32 v132, v132, 0x3a800000, v197
	v_rsq_f32_e32 v132, v132
	s_nop 0
	v_pk_mul_f32 v[154:155], v[154:155], v[132:133] op_sel_hi:[1,0]
	v_pk_mul_f32 v[156:157], v[156:157], v[132:133] op_sel_hi:[1,0]
	v_pk_mul_f32 v[158:159], v[158:159], v[132:133] op_sel_hi:[1,0]
	v_pk_mul_f32 v[160:161], v[160:161], v[132:133] op_sel_hi:[1,0]
	v_pk_mul_f32 v[162:163], v[162:163], v[132:133] op_sel_hi:[1,0]
	v_pk_mul_f32 v[164:165], v[164:165], v[132:133] op_sel_hi:[1,0]
	v_pk_mul_f32 v[166:167], v[166:167], v[132:133] op_sel_hi:[1,0]
	v_pk_mul_f32 v[168:169], v[168:169], v[132:133] op_sel_hi:[1,0]
	v_pk_mul_f32 v[154:155], v[2:3], v[154:155]
	v_pk_mul_f32 v[156:157], v[4:5], v[156:157]
	v_pk_mul_f32 v[158:159], v[6:7], v[158:159]
	v_pk_mul_f32 v[160:161], v[8:9], v[160:161]
	v_pk_mul_f32 v[162:163], v[10:11], v[162:163]
	v_pk_mul_f32 v[164:165], v[12:13], v[164:165]
	v_pk_mul_f32 v[166:167], v[14:15], v[166:167]
	v_pk_mul_f32 v[168:169], v[16:17], v[168:169]
	v_pk_fma_f32 v[154:155], v[50:51], v[154:155], v[66:67]
	v_pk_fma_f32 v[156:157], v[52:53], v[156:157], v[68:69]
	v_pk_fma_f32 v[158:159], v[54:55], v[158:159], v[70:71]
	v_pk_fma_f32 v[160:161], v[56:57], v[160:161], v[72:73]
	v_pk_fma_f32 v[162:163], v[58:59], v[162:163], v[74:75]
	v_pk_fma_f32 v[164:165], v[60:61], v[164:165], v[76:77]
	v_pk_fma_f32 v[166:167], v[62:63], v[166:167], v[78:79]
	v_pk_fma_f32 v[168:169], v[64:65], v[168:169], v[80:81]
	v_cvt_pk_bf16_f32 v154, v154, v155
	v_cvt_pk_bf16_f32 v155, v156, v157
	v_cvt_pk_bf16_f32 v156, v158, v159
	v_cvt_pk_bf16_f32 v157, v160, v161
	v_cvt_pk_bf16_f32 v158, v162, v163
	v_cvt_pk_bf16_f32 v159, v164, v165
	v_cvt_pk_bf16_f32 v160, v166, v167
	v_cvt_pk_bf16_f32 v161, v168, v169
	global_store_dwordx2 v1, v[154:155], s[10:11] offset:0
	global_store_dwordx2 v1, v[156:157], s[10:11] offset:512
	global_store_dwordx2 v1, v[158:159], s[10:11] offset:1024
	global_store_dwordx2 v1, v[160:161], s[10:11] offset:1536
	s_add_u32 s10, s10, 0x800
	s_addc_u32 s11, s11, 0
	s_waitcnt vmcnt(32)
	v_pk_mul_f32 v[130:131], v[170:171], v[170:171]
	v_pk_fma_f32 v[130:131], v[172:173], v[172:173], v[130:131]
	v_pk_fma_f32 v[130:131], v[174:175], v[174:175], v[130:131]
	v_pk_fma_f32 v[130:131], v[176:177], v[176:177], v[130:131]
	v_pk_fma_f32 v[130:131], v[178:179], v[178:179], v[130:131]
	v_pk_fma_f32 v[130:131], v[180:181], v[180:181], v[130:131]
	v_pk_fma_f32 v[130:131], v[182:183], v[182:183], v[130:131]
	v_pk_fma_f32 v[130:131], v[184:185], v[184:185], v[130:131]
	v_add_f32_e32 v130, v130, v131
	s_nop 1
	v_add_f32_dpp v130, v130, v130 row_ror:8 row_mask:0xf bank_mask:0xf
	s_nop 1
	v_add_f32_dpp v130, v130, v130 row_ror:4 row_mask:0xf bank_mask:0xf
	s_nop 1
	v_add_f32_dpp v130, v130, v130 row_ror:2 row_mask:0xf bank_mask:0xf
	s_nop 1
	v_add_f32_dpp v130, v130, v130 row_ror:1 row_mask:0xf bank_mask:0xf
	s_nop 1
	s_nop 0
	v_readlane_b32 s0, v130, 0
	v_readlane_b32 s1, v130, 16
	v_readlane_b32 s22, v130, 32
	v_readlane_b32 s23, v130, 48
	s_nop 1
	v_mov_b32_e32 v132, s0
	v_add_f32_e32 v132, s1, v132
	v_add_f32_e32 v132, s22, v132
	v_add_f32_e32 v132, s23, v132
	v_fmamk_f32 v132, v132, 0x3a800000, v197
	v_rsq_f32_e32 v132, v132
	s_nop 0
	v_pk_mul_f32 v[170:171], v[170:171], v[132:133] op_sel_hi:[1,0]
	v_pk_mul_f32 v[172:173], v[172:173], v[132:133] op_sel_hi:[1,0]
	v_pk_mul_f32 v[174:175], v[174:175], v[132:133] op_sel_hi:[1,0]
	v_pk_mul_f32 v[176:177], v[176:177], v[132:133] op_sel_hi:[1,0]
	v_pk_mul_f32 v[178:179], v[178:179], v[132:133] op_sel_hi:[1,0]
	v_pk_mul_f32 v[180:181], v[180:181], v[132:133] op_sel_hi:[1,0]
	v_pk_mul_f32 v[182:183], v[182:183], v[132:133] op_sel_hi:[1,0]
	v_pk_mul_f32 v[184:185], v[184:185], v[132:133] op_sel_hi:[1,0]
	v_pk_mul_f32 v[170:171], v[2:3], v[170:171]
	v_pk_mul_f32 v[172:173], v[4:5], v[172:173]
	v_pk_mul_f32 v[174:175], v[6:7], v[174:175]
	v_pk_mul_f32 v[176:177], v[8:9], v[176:177]
	v_pk_mul_f32 v[178:179], v[10:11], v[178:179]
	v_pk_mul_f32 v[180:181], v[12:13], v[180:181]
	v_pk_mul_f32 v[182:183], v[14:15], v[182:183]
	v_pk_mul_f32 v[184:185], v[16:17], v[184:185]
	v_pk_fma_f32 v[170:171], v[50:51], v[170:171], v[66:67]
	v_pk_fma_f32 v[172:173], v[52:53], v[172:173], v[68:69]
	v_pk_fma_f32 v[174:175], v[54:55], v[174:175], v[70:71]
	v_pk_fma_f32 v[176:177], v[56:57], v[176:177], v[72:73]
	v_pk_fma_f32 v[178:179], v[58:59], v[178:179], v[74:75]
	v_pk_fma_f32 v[180:181], v[60:61], v[180:181], v[76:77]
	v_pk_fma_f32 v[182:183], v[62:63], v[182:183], v[78:79]
	v_pk_fma_f32 v[184:185], v[64:65], v[184:185], v[80:81]
	v_cvt_pk_bf16_f32 v170, v170, v171
	v_cvt_pk_bf16_f32 v171, v172, v173
	v_cvt_pk_bf16_f32 v172, v174, v175
	v_cvt_pk_bf16_f32 v173, v176, v177
	v_cvt_pk_bf16_f32 v174, v178, v179
	v_cvt_pk_bf16_f32 v175, v180, v181
	v_cvt_pk_bf16_f32 v176, v182, v183
	v_cvt_pk_bf16_f32 v177, v184, v185
	global_store_dwordx2 v1, v[170:171], s[10:11] offset:0
	global_store_dwordx2 v1, v[172:173], s[10:11] offset:512
	global_store_dwordx2 v1, v[174:175], s[10:11] offset:1024
	global_store_dwordx2 v1, v[176:177], s[10:11] offset:1536
	s_add_u32 s10, s10, 0x800
	s_addc_u32 s11, s11, 0
	s_waitcnt vmcnt(28)
	v_pk_mul_f32 v[130:131], v[82:83], v[82:83]
	v_pk_fma_f32 v[130:131], v[84:85], v[84:85], v[130:131]
	v_pk_fma_f32 v[130:131], v[86:87], v[86:87], v[130:131]
	v_pk_fma_f32 v[130:131], v[88:89], v[88:89], v[130:131]
	v_pk_fma_f32 v[130:131], v[90:91], v[90:91], v[130:131]
	v_pk_fma_f32 v[130:131], v[92:93], v[92:93], v[130:131]
	v_pk_fma_f32 v[130:131], v[94:95], v[94:95], v[130:131]
	v_pk_fma_f32 v[130:131], v[96:97], v[96:97], v[130:131]
	v_add_f32_e32 v130, v130, v131
	s_nop 1
	v_add_f32_dpp v130, v130, v130 row_ror:8 row_mask:0xf bank_mask:0xf
	s_nop 1
	v_add_f32_dpp v130, v130, v130 row_ror:4 row_mask:0xf bank_mask:0xf
	s_nop 1
	v_add_f32_dpp v130, v130, v130 row_ror:2 row_mask:0xf bank_mask:0xf
	s_nop 1
	v_add_f32_dpp v130, v130, v130 row_ror:1 row_mask:0xf bank_mask:0xf
	s_nop 1
	s_nop 0
	v_readlane_b32 s0, v130, 0
	v_readlane_b32 s1, v130, 16
	v_readlane_b32 s22, v130, 32
	v_readlane_b32 s23, v130, 48
	s_nop 1
	v_mov_b32_e32 v132, s0
	v_add_f32_e32 v132, s1, v132
	v_add_f32_e32 v132, s22, v132
	v_add_f32_e32 v132, s23, v132
	v_fmamk_f32 v132, v132, 0x3a800000, v197
	v_rsq_f32_e32 v132, v132
	s_nop 0
	v_pk_mul_f32 v[82:83], v[82:83], v[132:133] op_sel_hi:[1,0]
	v_pk_mul_f32 v[84:85], v[84:85], v[132:133] op_sel_hi:[1,0]
	v_pk_mul_f32 v[86:87], v[86:87], v[132:133] op_sel_hi:[1,0]
	v_pk_mul_f32 v[88:89], v[88:89], v[132:133] op_sel_hi:[1,0]
	v_pk_mul_f32 v[90:91], v[90:91], v[132:133] op_sel_hi:[1,0]
	v_pk_mul_f32 v[92:93], v[92:93], v[132:133] op_sel_hi:[1,0]
	v_pk_mul_f32 v[94:95], v[94:95], v[132:133] op_sel_hi:[1,0]
	v_pk_mul_f32 v[96:97], v[96:97], v[132:133] op_sel_hi:[1,0]
	v_pk_mul_f32 v[82:83], v[2:3], v[82:83]
	v_pk_mul_f32 v[84:85], v[4:5], v[84:85]
	v_pk_mul_f32 v[86:87], v[6:7], v[86:87]
	v_pk_mul_f32 v[88:89], v[8:9], v[88:89]
	v_pk_mul_f32 v[90:91], v[10:11], v[90:91]
	v_pk_mul_f32 v[92:93], v[12:13], v[92:93]
	v_pk_mul_f32 v[94:95], v[14:15], v[94:95]
	v_pk_mul_f32 v[96:97], v[16:17], v[96:97]
	v_pk_fma_f32 v[82:83], v[50:51], v[82:83], v[66:67]
	v_pk_fma_f32 v[84:85], v[52:53], v[84:85], v[68:69]
	v_pk_fma_f32 v[86:87], v[54:55], v[86:87], v[70:71]
	v_pk_fma_f32 v[88:89], v[56:57], v[88:89], v[72:73]
	v_pk_fma_f32 v[90:91], v[58:59], v[90:91], v[74:75]
	v_pk_fma_f32 v[92:93], v[60:61], v[92:93], v[76:77]
	v_pk_fma_f32 v[94:95], v[62:63], v[94:95], v[78:79]
	v_pk_fma_f32 v[96:97], v[64:65], v[96:97], v[80:81]
	v_cvt_pk_bf16_f32 v82, v82, v83
	v_cvt_pk_bf16_f32 v83, v84, v85
	v_cvt_pk_bf16_f32 v84, v86, v87
	v_cvt_pk_bf16_f32 v85, v88, v89
	v_cvt_pk_bf16_f32 v86, v90, v91
	v_cvt_pk_bf16_f32 v87, v92, v93
	v_cvt_pk_bf16_f32 v88, v94, v95
	v_cvt_pk_bf16_f32 v89, v96, v97
	global_store_dwordx2 v1, v[82:83], s[10:11] offset:0
	global_store_dwordx2 v1, v[84:85], s[10:11] offset:512
	global_store_dwordx2 v1, v[86:87], s[10:11] offset:1024
	global_store_dwordx2 v1, v[88:89], s[10:11] offset:1536
	s_add_u32 s10, s10, 0x800
	s_addc_u32 s11, s11, 0
	s_waitcnt vmcnt(24)
	v_pk_mul_f32 v[130:131], v[98:99], v[98:99]
	v_pk_fma_f32 v[130:131], v[100:101], v[100:101], v[130:131]
	v_pk_fma_f32 v[130:131], v[102:103], v[102:103], v[130:131]
	v_pk_fma_f32 v[130:131], v[104:105], v[104:105], v[130:131]
	v_pk_fma_f32 v[130:131], v[106:107], v[106:107], v[130:131]
	v_pk_fma_f32 v[130:131], v[108:109], v[108:109], v[130:131]
	v_pk_fma_f32 v[130:131], v[110:111], v[110:111], v[130:131]
	v_pk_fma_f32 v[130:131], v[112:113], v[112:113], v[130:131]
	v_add_f32_e32 v130, v130, v131
	s_nop 1
	v_add_f32_dpp v130, v130, v130 row_ror:8 row_mask:0xf bank_mask:0xf
	s_nop 1
	v_add_f32_dpp v130, v130, v130 row_ror:4 row_mask:0xf bank_mask:0xf
	s_nop 1
	v_add_f32_dpp v130, v130, v130 row_ror:2 row_mask:0xf bank_mask:0xf
	s_nop 1
	v_add_f32_dpp v130, v130, v130 row_ror:1 row_mask:0xf bank_mask:0xf
	s_nop 1
	s_nop 0
	v_readlane_b32 s0, v130, 0
	v_readlane_b32 s1, v130, 16
	v_readlane_b32 s22, v130, 32
	v_readlane_b32 s23, v130, 48
	s_nop 1
	v_mov_b32_e32 v132, s0
	v_add_f32_e32 v132, s1, v132
	v_add_f32_e32 v132, s22, v132
	v_add_f32_e32 v132, s23, v132
	v_fmamk_f32 v132, v132, 0x3a800000, v197
	v_rsq_f32_e32 v132, v132
	s_nop 0
	v_pk_mul_f32 v[98:99], v[98:99], v[132:133] op_sel_hi:[1,0]
	v_pk_mul_f32 v[100:101], v[100:101], v[132:133] op_sel_hi:[1,0]
	v_pk_mul_f32 v[102:103], v[102:103], v[132:133] op_sel_hi:[1,0]
	v_pk_mul_f32 v[104:105], v[104:105], v[132:133] op_sel_hi:[1,0]
	v_pk_mul_f32 v[106:107], v[106:107], v[132:133] op_sel_hi:[1,0]
	v_pk_mul_f32 v[108:109], v[108:109], v[132:133] op_sel_hi:[1,0]
	v_pk_mul_f32 v[110:111], v[110:111], v[132:133] op_sel_hi:[1,0]
	v_pk_mul_f32 v[112:113], v[112:113], v[132:133] op_sel_hi:[1,0]
	v_pk_mul_f32 v[98:99], v[2:3], v[98:99]
	v_pk_mul_f32 v[100:101], v[4:5], v[100:101]
	v_pk_mul_f32 v[102:103], v[6:7], v[102:103]
	v_pk_mul_f32 v[104:105], v[8:9], v[104:105]
	v_pk_mul_f32 v[106:107], v[10:11], v[106:107]
	v_pk_mul_f32 v[108:109], v[12:13], v[108:109]
	v_pk_mul_f32 v[110:111], v[14:15], v[110:111]
	v_pk_mul_f32 v[112:113], v[16:17], v[112:113]
	v_pk_fma_f32 v[98:99], v[50:51], v[98:99], v[66:67]
	v_pk_fma_f32 v[100:101], v[52:53], v[100:101], v[68:69]
	v_pk_fma_f32 v[102:103], v[54:55], v[102:103], v[70:71]
	v_pk_fma_f32 v[104:105], v[56:57], v[104:105], v[72:73]
	v_pk_fma_f32 v[106:107], v[58:59], v[106:107], v[74:75]
	v_pk_fma_f32 v[108:109], v[60:61], v[108:109], v[76:77]
	v_pk_fma_f32 v[110:111], v[62:63], v[110:111], v[78:79]
	v_pk_fma_f32 v[112:113], v[64:65], v[112:113], v[80:81]
	v_cvt_pk_bf16_f32 v98, v98, v99
	v_cvt_pk_bf16_f32 v99, v100, v101
	v_cvt_pk_bf16_f32 v100, v102, v103
	v_cvt_pk_bf16_f32 v101, v104, v105
	v_cvt_pk_bf16_f32 v102, v106, v107
	v_cvt_pk_bf16_f32 v103, v108, v109
	v_cvt_pk_bf16_f32 v104, v110, v111
	v_cvt_pk_bf16_f32 v105, v112, v113
	global_store_dwordx2 v1, v[98:99], s[10:11] offset:0
	global_store_dwordx2 v1, v[100:101], s[10:11] offset:512
	global_store_dwordx2 v1, v[102:103], s[10:11] offset:1024
	global_store_dwordx2 v1, v[104:105], s[10:11] offset:1536
	s_add_u32 s10, s10, 0x800
	s_addc_u32 s11, s11, 0
	s_waitcnt vmcnt(20)
	v_pk_mul_f32 v[130:131], v[114:115], v[114:115]
	v_pk_fma_f32 v[130:131], v[116:117], v[116:117], v[130:131]
	v_pk_fma_f32 v[130:131], v[118:119], v[118:119], v[130:131]
	v_pk_fma_f32 v[130:131], v[120:121], v[120:121], v[130:131]
	v_pk_fma_f32 v[130:131], v[122:123], v[122:123], v[130:131]
	v_pk_fma_f32 v[130:131], v[124:125], v[124:125], v[130:131]
	v_pk_fma_f32 v[130:131], v[126:127], v[126:127], v[130:131]
	v_pk_fma_f32 v[130:131], v[128:129], v[128:129], v[130:131]
	v_add_f32_e32 v130, v130, v131
	s_nop 1
	v_add_f32_dpp v130, v130, v130 row_ror:8 row_mask:0xf bank_mask:0xf
	s_nop 1
	v_add_f32_dpp v130, v130, v130 row_ror:4 row_mask:0xf bank_mask:0xf
	s_nop 1
	v_add_f32_dpp v130, v130, v130 row_ror:2 row_mask:0xf bank_mask:0xf
	s_nop 1
	v_add_f32_dpp v130, v130, v130 row_ror:1 row_mask:0xf bank_mask:0xf
	s_nop 1
	s_nop 0
	v_readlane_b32 s0, v130, 0
	v_readlane_b32 s1, v130, 16
	v_readlane_b32 s22, v130, 32
	v_readlane_b32 s23, v130, 48
	s_nop 1
	v_mov_b32_e32 v132, s0
	v_add_f32_e32 v132, s1, v132
	v_add_f32_e32 v132, s22, v132
	v_add_f32_e32 v132, s23, v132
	v_fmamk_f32 v132, v132, 0x3a800000, v197
	v_rsq_f32_e32 v132, v132
	s_nop 0
	v_pk_mul_f32 v[114:115], v[114:115], v[132:133] op_sel_hi:[1,0]
	v_pk_mul_f32 v[116:117], v[116:117], v[132:133] op_sel_hi:[1,0]
	v_pk_mul_f32 v[118:119], v[118:119], v[132:133] op_sel_hi:[1,0]
	v_pk_mul_f32 v[120:121], v[120:121], v[132:133] op_sel_hi:[1,0]
	v_pk_mul_f32 v[122:123], v[122:123], v[132:133] op_sel_hi:[1,0]
	v_pk_mul_f32 v[124:125], v[124:125], v[132:133] op_sel_hi:[1,0]
	v_pk_mul_f32 v[126:127], v[126:127], v[132:133] op_sel_hi:[1,0]
	v_pk_mul_f32 v[128:129], v[128:129], v[132:133] op_sel_hi:[1,0]
	v_pk_mul_f32 v[114:115], v[2:3], v[114:115]
	v_pk_mul_f32 v[116:117], v[4:5], v[116:117]
	v_pk_mul_f32 v[118:119], v[6:7], v[118:119]
	v_pk_mul_f32 v[120:121], v[8:9], v[120:121]
	v_pk_mul_f32 v[122:123], v[10:11], v[122:123]
	v_pk_mul_f32 v[124:125], v[12:13], v[124:125]
	v_pk_mul_f32 v[126:127], v[14:15], v[126:127]
	v_pk_mul_f32 v[128:129], v[16:17], v[128:129]
	v_pk_fma_f32 v[114:115], v[50:51], v[114:115], v[66:67]
	v_pk_fma_f32 v[116:117], v[52:53], v[116:117], v[68:69]
	v_pk_fma_f32 v[118:119], v[54:55], v[118:119], v[70:71]
	v_pk_fma_f32 v[120:121], v[56:57], v[120:121], v[72:73]
	v_pk_fma_f32 v[122:123], v[58:59], v[122:123], v[74:75]
	v_pk_fma_f32 v[124:125], v[60:61], v[124:125], v[76:77]
	v_pk_fma_f32 v[126:127], v[62:63], v[126:127], v[78:79]
	v_pk_fma_f32 v[128:129], v[64:65], v[128:129], v[80:81]
	v_cvt_pk_bf16_f32 v114, v114, v115
	v_cvt_pk_bf16_f32 v115, v116, v117
	v_cvt_pk_bf16_f32 v116, v118, v119
	v_cvt_pk_bf16_f32 v117, v120, v121
	v_cvt_pk_bf16_f32 v118, v122, v123
	v_cvt_pk_bf16_f32 v119, v124, v125
	v_cvt_pk_bf16_f32 v120, v126, v127
	v_cvt_pk_bf16_f32 v121, v128, v129
	global_store_dwordx2 v1, v[114:115], s[10:11] offset:0
	global_store_dwordx2 v1, v[116:117], s[10:11] offset:512
	global_store_dwordx2 v1, v[118:119], s[10:11] offset:1024
	global_store_dwordx2 v1, v[120:121], s[10:11] offset:1536
	s_branch .Lrn_p3_end

.Lrn_p3_end:
.LBB0_632:
	s_add_i32 s0, s28, 1
	s_cmp_ge_i32 s0, s79
	s_cbranch_scc1 .LBB0_686
	s_waitcnt vmcnt(0)
	s_waitcnt vmcnt(0) lgkmcnt(0)
	s_barrier
	s_mov_b64 s[0:1], exec
	v_readlane_b32 s6, v247, 4
	v_readlane_b32 s7, v247, 5
	s_and_b64 s[6:7], s[0:1], s[6:7]
	s_mov_b64 exec, s[6:7]
	s_cbranch_execz .LBB0_685
	v_readlane_b32 s6, v245, 27
	s_waitcnt vmcnt(0) expcnt(0) lgkmcnt(0)
	s_nop 0
	v_mov_b32_e32 v0, s6
	ds_read_b32 v2, v0
	v_readlane_b32 s6, v245, 28
	s_waitcnt lgkmcnt(0)
	v_cmp_ne_u32_e32 vcc, 0, v2
	v_mov_b32_e32 v0, s6
	ds_read_b32 v0, v0
	s_cbranch_vccnz .LBB0_649
	s_mov_b32 s12, 1
	s_branch .LBB0_637

.LBB0_689:
	v_lshlrev_b32_e32 v0, 4, v205
	v_readlane_b32 s0, v245, 21
	v_readlane_b32 s6, v247, 29
	v_readlane_b32 s7, v247, 30
	s_add_u32 s14, s4, 0x231320
	s_addc_u32 s15, s5, 0
	global_load_dwordx4 v[2:5], v0, s[14:15] offset:0
	global_load_dwordx4 v[6:9], v0, s[14:15] offset:1024
	global_load_dwordx4 v[10:13], v0, s[14:15] offset:2048
	global_load_dwordx4 v[14:17], v0, s[14:15] offset:3072
	s_lshl_b32 s1, s0, 15
	s_add_u32 s6, s6, s1
	s_addc_u32 s7, s7, 0
	s_mov_b32 s10, s6
	s_mov_b32 s11, s7
	global_load_dwordx4 v[18:21], v0, s[6:7] offset:0
	global_load_dwordx4 v[22:25], v0, s[6:7] offset:1024
	global_load_dwordx4 v[26:29], v0, s[6:7] offset:2048
	global_load_dwordx4 v[30:33], v0, s[6:7] offset:3072
	s_add_u32 s6, s6, 0x1000
	s_addc_u32 s7, s7, 0
	global_load_dwordx4 v[34:37], v0, s[6:7] offset:0
	global_load_dwordx4 v[38:41], v0, s[6:7] offset:1024
	global_load_dwordx4 v[42:45], v0, s[6:7] offset:2048
	global_load_dwordx4 v[46:49], v0, s[6:7] offset:3072
	s_add_u32 s6, s6, 0x1000
	s_addc_u32 s7, s7, 0
	global_load_dwordx4 v[50:53], v0, s[6:7] offset:0
	global_load_dwordx4 v[54:57], v0, s[6:7] offset:1024
	global_load_dwordx4 v[58:61], v0, s[6:7] offset:2048
	global_load_dwordx4 v[62:65], v0, s[6:7] offset:3072
	s_add_u32 s6, s6, 0x1000
	s_addc_u32 s7, s7, 0
	global_load_dwordx4 v[66:69], v0, s[6:7] offset:0
	global_load_dwordx4 v[70:73], v0, s[6:7] offset:1024
	global_load_dwordx4 v[74:77], v0, s[6:7] offset:2048
	global_load_dwordx4 v[78:81], v0, s[6:7] offset:3072
	s_add_u32 s6, s6, 0x1000
	s_addc_u32 s7, s7, 0
	global_load_dwordx4 v[82:85], v0, s[6:7] offset:0
	global_load_dwordx4 v[86:89], v0, s[6:7] offset:1024
	global_load_dwordx4 v[90:93], v0, s[6:7] offset:2048
	global_load_dwordx4 v[94:97], v0, s[6:7] offset:3072
	s_add_u32 s6, s6, 0x1000
	s_addc_u32 s7, s7, 0
	global_load_dwordx4 v[98:101], v0, s[6:7] offset:0
	global_load_dwordx4 v[102:105], v0, s[6:7] offset:1024
	global_load_dwordx4 v[106:109], v0, s[6:7] offset:2048
	global_load_dwordx4 v[110:113], v0, s[6:7] offset:3072
	s_add_u32 s6, s6, 0x1000
	s_addc_u32 s7, s7, 0
	s_waitcnt vmcnt(20)
	v_pk_mul_f32 v[114:115], v[18:19], v[18:19]
	v_pk_fma_f32 v[114:115], v[20:21], v[20:21], v[114:115]
	v_pk_fma_f32 v[114:115], v[22:23], v[22:23], v[114:115]
	v_pk_fma_f32 v[114:115], v[24:25], v[24:25], v[114:115]
	v_pk_fma_f32 v[114:115], v[26:27], v[26:27], v[114:115]
	v_pk_fma_f32 v[114:115], v[28:29], v[28:29], v[114:115]
	v_pk_fma_f32 v[114:115], v[30:31], v[30:31], v[114:115]
	v_pk_fma_f32 v[114:115], v[32:33], v[32:33], v[114:115]
	v_add_f32_e32 v114, v114, v115
	s_nop 1
	v_add_f32_dpp v114, v114, v114 row_ror:8 row_mask:0xf bank_mask:0xf
	s_nop 1
	v_add_f32_dpp v114, v114, v114 row_ror:4 row_mask:0xf bank_mask:0xf
	s_nop 1
	v_add_f32_dpp v114, v114, v114 row_ror:2 row_mask:0xf bank_mask:0xf
	s_nop 1
	v_add_f32_dpp v114, v114, v114 row_ror:1 row_mask:0xf bank_mask:0xf
	s_nop 1
	s_nop 0
	v_readlane_b32 s0, v114, 0
	v_readlane_b32 s1, v114, 16
	v_readlane_b32 s22, v114, 32
	v_readlane_b32 s23, v114, 48
	s_nop 1
	v_mov_b32_e32 v116, s0
	v_add_f32_e32 v116, s1, v116
	v_add_f32_e32 v116, s22, v116
	v_add_f32_e32 v116, s23, v116
	v_fmamk_f32 v116, v116, 0x3a800000, v197
	v_rsq_f32_e32 v116, v116
	s_nop 0
	v_pk_mul_f32 v[18:19], v[18:19], v[116:117] op_sel_hi:[1,0]
	v_pk_mul_f32 v[20:21], v[20:21], v[116:117] op_sel_hi:[1,0]
	v_pk_mul_f32 v[22:23], v[22:23], v[116:117] op_sel_hi:[1,0]
	v_pk_mul_f32 v[24:25], v[24:25], v[116:117] op_sel_hi:[1,0]
	v_pk_mul_f32 v[26:27], v[26:27], v[116:117] op_sel_hi:[1,0]
	v_pk_mul_f32 v[28:29], v[28:29], v[116:117] op_sel_hi:[1,0]
	v_pk_mul_f32 v[30:31], v[30:31], v[116:117] op_sel_hi:[1,0]
	v_pk_mul_f32 v[32:33], v[32:33], v[116:117] op_sel_hi:[1,0]
	v_pk_mul_f32 v[18:19], v[2:3], v[18:19]
	v_pk_mul_f32 v[20:21], v[4:5], v[20:21]
	v_pk_mul_f32 v[22:23], v[6:7], v[22:23]
	v_pk_mul_f32 v[24:25], v[8:9], v[24:25]
	v_pk_mul_f32 v[26:27], v[10:11], v[26:27]
	v_pk_mul_f32 v[28:29], v[12:13], v[28:29]
	v_pk_mul_f32 v[30:31], v[14:15], v[30:31]
	v_pk_mul_f32 v[32:33], v[16:17], v[32:33]
	global_store_dwordx4 v0, v[18:21], s[10:11] offset:0
	global_store_dwordx4 v0, v[22:25], s[10:11] offset:1024
	global_store_dwordx4 v0, v[26:29], s[10:11] offset:2048
	global_store_dwordx4 v0, v[30:33], s[10:11] offset:3072
	s_add_u32 s10, s10, 0x1000
	s_addc_u32 s11, s11, 0
	global_load_dwordx4 v[18:21], v0, s[6:7] offset:0
	global_load_dwordx4 v[22:25], v0, s[6:7] offset:1024
	global_load_dwordx4 v[26:29], v0, s[6:7] offset:2048
	global_load_dwordx4 v[30:33], v0, s[6:7] offset:3072
	s_add_u32 s6, s6, 0x1000
	s_addc_u32 s7, s7, 0
	s_waitcnt vmcnt(24)
	v_pk_mul_f32 v[114:115], v[34:35], v[34:35]
	v_pk_fma_f32 v[114:115], v[36:37], v[36:37], v[114:115]
	v_pk_fma_f32 v[114:115], v[38:39], v[38:39], v[114:115]
	v_pk_fma_f32 v[114:115], v[40:41], v[40:41], v[114:115]
	v_pk_fma_f32 v[114:115], v[42:43], v[42:43], v[114:115]
	v_pk_fma_f32 v[114:115], v[44:45], v[44:45], v[114:115]
	v_pk_fma_f32 v[114:115], v[46:47], v[46:47], v[114:115]
	v_pk_fma_f32 v[114:115], v[48:49], v[48:49], v[114:115]
	v_add_f32_e32 v114, v114, v115
	s_nop 1
	v_add_f32_dpp v114, v114, v114 row_ror:8 row_mask:0xf bank_mask:0xf
	s_nop 1
	v_add_f32_dpp v114, v114, v114 row_ror:4 row_mask:0xf bank_mask:0xf
	s_nop 1
	v_add_f32_dpp v114, v114, v114 row_ror:2 row_mask:0xf bank_mask:0xf
	s_nop 1
	v_add_f32_dpp v114, v114, v114 row_ror:1 row_mask:0xf bank_mask:0xf
	s_nop 1
	s_nop 0
	v_readlane_b32 s0, v114, 0
	v_readlane_b32 s1, v114, 16
	v_readlane_b32 s22, v114, 32
	v_readlane_b32 s23, v114, 48
	s_nop 1
	v_mov_b32_e32 v116, s0
	v_add_f32_e32 v116, s1, v116
	v_add_f32_e32 v116, s22, v116
	v_add_f32_e32 v116, s23, v116
	v_fmamk_f32 v116, v116, 0x3a800000, v197
	v_rsq_f32_e32 v116, v116
	s_nop 0
	v_pk_mul_f32 v[34:35], v[34:35], v[116:117] op_sel_hi:[1,0]
	v_pk_mul_f32 v[36:37], v[36:37], v[116:117] op_sel_hi:[1,0]
	v_pk_mul_f32 v[38:39], v[38:39], v[116:117] op_sel_hi:[1,0]
	v_pk_mul_f32 v[40:41], v[40:41], v[116:117] op_sel_hi:[1,0]
	v_pk_mul_f32 v[42:43], v[42:43], v[116:117] op_sel_hi:[1,0]
	v_pk_mul_f32 v[44:45], v[44:45], v[116:117] op_sel_hi:[1,0]
	v_pk_mul_f32 v[46:47], v[46:47], v[116:117] op_sel_hi:[1,0]
	v_pk_mul_f32 v[48:49], v[48:49], v[116:117] op_sel_hi:[1,0]
	v_pk_mul_f32 v[34:35], v[2:3], v[34:35]
	v_pk_mul_f32 v[36:37], v[4:5], v[36:37]
	v_pk_mul_f32 v[38:39], v[6:7], v[38:39]
	v_pk_mul_f32 v[40:41], v[8:9], v[40:41]
	v_pk_mul_f32 v[42:43], v[10:11], v[42:43]
	v_pk_mul_f32 v[44:45], v[12:13], v[44:45]
	v_pk_mul_f32 v[46:47], v[14:15], v[46:47]
	v_pk_mul_f32 v[48:49], v[16:17], v[48:49]
	global_store_dwordx4 v0, v[34:37], s[10:11] offset:0
	global_store_dwordx4 v0, v[38:41], s[10:11] offset:1024
	global_store_dwordx4 v0, v[42:45], s[10:11] offset:2048
	global_store_dwordx4 v0, v[46:49], s[10:11] offset:3072
	s_add_u32 s10, s10, 0x1000
	s_addc_u32 s11, s11, 0
	global_load_dwordx4 v[34:37], v0, s[6:7] offset:0
	global_load_dwordx4 v[38:41], v0, s[6:7] offset:1024
	global_load_dwordx4 v[42:45], v0, s[6:7] offset:2048
	global_load_dwordx4 v[46:49], v0, s[6:7] offset:3072
	s_waitcnt vmcnt(28)
	v_pk_mul_f32 v[114:115], v[50:51], v[50:51]
	v_pk_fma_f32 v[114:115], v[52:53], v[52:53], v[114:115]
	v_pk_fma_f32 v[114:115], v[54:55], v[54:55], v[114:115]
	v_pk_fma_f32 v[114:115], v[56:57], v[56:57], v[114:115]
	v_pk_fma_f32 v[114:115], v[58:59], v[58:59], v[114:115]
	v_pk_fma_f32 v[114:115], v[60:61], v[60:61], v[114:115]
	v_pk_fma_f32 v[114:115], v[62:63], v[62:63], v[114:115]
	v_pk_fma_f32 v[114:115], v[64:65], v[64:65], v[114:115]
	v_add_f32_e32 v114, v114, v115
	s_nop 1
	v_add_f32_dpp v114, v114, v114 row_ror:8 row_mask:0xf bank_mask:0xf
	s_nop 1
	v_add_f32_dpp v114, v114, v114 row_ror:4 row_mask:0xf bank_mask:0xf
	s_nop 1
	v_add_f32_dpp v114, v114, v114 row_ror:2 row_mask:0xf bank_mask:0xf
	s_nop 1
	v_add_f32_dpp v114, v114, v114 row_ror:1 row_mask:0xf bank_mask:0xf
	s_nop 1
	s_nop 0
	v_readlane_b32 s0, v114, 0
	v_readlane_b32 s1, v114, 16
	v_readlane_b32 s22, v114, 32
	v_readlane_b32 s23, v114, 48
	s_nop 1
	v_mov_b32_e32 v116, s0
	v_add_f32_e32 v116, s1, v116
	v_add_f32_e32 v116, s22, v116
	v_add_f32_e32 v116, s23, v116
	v_fmamk_f32 v116, v116, 0x3a800000, v197
	v_rsq_f32_e32 v116, v116
	s_nop 0
	v_pk_mul_f32 v[50:51], v[50:51], v[116:117] op_sel_hi:[1,0]
	v_pk_mul_f32 v[52:53], v[52:53], v[116:117] op_sel_hi:[1,0]
	v_pk_mul_f32 v[54:55], v[54:55], v[116:117] op_sel_hi:[1,0]
	v_pk_mul_f32 v[56:57], v[56:57], v[116:117] op_sel_hi:[1,0]
	v_pk_mul_f32 v[58:59], v[58:59], v[116:117] op_sel_hi:[1,0]
	v_pk_mul_f32 v[60:61], v[60:61], v[116:117] op_sel_hi:[1,0]
	v_pk_mul_f32 v[62:63], v[62:63], v[116:117] op_sel_hi:[1,0]
	v_pk_mul_f32 v[64:65], v[64:65], v[116:117] op_sel_hi:[1,0]
	v_pk_mul_f32 v[50:51], v[2:3], v[50:51]
	v_pk_mul_f32 v[52:53], v[4:5], v[52:53]
	v_pk_mul_f32 v[54:55], v[6:7], v[54:55]
	v_pk_mul_f32 v[56:57], v[8:9], v[56:57]
	v_pk_mul_f32 v[58:59], v[10:11], v[58:59]
	v_pk_mul_f32 v[60:61], v[12:13], v[60:61]
	v_pk_mul_f32 v[62:63], v[14:15], v[62:63]
	v_pk_mul_f32 v[64:65], v[16:17], v[64:65]
	global_store_dwordx4 v0, v[50:53], s[10:11] offset:0
	global_store_dwordx4 v0, v[54:57], s[10:11] offset:1024
	global_store_dwordx4 v0, v[58:61], s[10:11] offset:2048
	global_store_dwordx4 v0, v[62:65], s[10:11] offset:3072
	s_add_u32 s10, s10, 0x1000
	s_addc_u32 s11, s11, 0
	s_waitcnt vmcnt(28)
	v_pk_mul_f32 v[114:115], v[66:67], v[66:67]
	v_pk_fma_f32 v[114:115], v[68:69], v[68:69], v[114:115]
	v_pk_fma_f32 v[114:115], v[70:71], v[70:71], v[114:115]
	v_pk_fma_f32 v[114:115], v[72:73], v[72:73], v[114:115]
	v_pk_fma_f32 v[114:115], v[74:75], v[74:75], v[114:115]
	v_pk_fma_f32 v[114:115], v[76:77], v[76:77], v[114:115]
	v_pk_fma_f32 v[114:115], v[78:79], v[78:79], v[114:115]
	v_pk_fma_f32 v[114:115], v[80:81], v[80:81], v[114:115]
	v_add_f32_e32 v114, v114, v115
	s_nop 1
	v_add_f32_dpp v114, v114, v114 row_ror:8 row_mask:0xf bank_mask:0xf
	s_nop 1
	v_add_f32_dpp v114, v114, v114 row_ror:4 row_mask:0xf bank_mask:0xf
	s_nop 1
	v_add_f32_dpp v114, v114, v114 row_ror:2 row_mask:0xf bank_mask:0xf
	s_nop 1
	v_add_f32_dpp v114, v114, v114 row_ror:1 row_mask:0xf bank_mask:0xf
	s_nop 1
	s_nop 0
	v_readlane_b32 s0, v114, 0
	v_readlane_b32 s1, v114, 16
	v_readlane_b32 s22, v114, 32
	v_readlane_b32 s23, v114, 48
	s_nop 1
	v_mov_b32_e32 v116, s0
	v_add_f32_e32 v116, s1, v116
	v_add_f32_e32 v116, s22, v116
	v_add_f32_e32 v116, s23, v116
	v_fmamk_f32 v116, v116, 0x3a800000, v197
	v_rsq_f32_e32 v116, v116
	s_nop 0
	v_pk_mul_f32 v[66:67], v[66:67], v[116:117] op_sel_hi:[1,0]
	v_pk_mul_f32 v[68:69], v[68:69], v[116:117] op_sel_hi:[1,0]
	v_pk_mul_f32 v[70:71], v[70:71], v[116:117] op_sel_hi:[1,0]
	v_pk_mul_f32 v[72:73], v[72:73], v[116:117] op_sel_hi:[1,0]
	v_pk_mul_f32 v[74:75], v[74:75], v[116:117] op_sel_hi:[1,0]
	v_pk_mul_f32 v[76:77], v[76:77], v[116:117] op_sel_hi:[1,0]
	v_pk_mul_f32 v[78:79], v[78:79], v[116:117] op_sel_hi:[1,0]
	v_pk_mul_f32 v[80:81], v[80:81], v[116:117] op_sel_hi:[1,0]
	v_pk_mul_f32 v[66:67], v[2:3], v[66:67]
	v_pk_mul_f32 v[68:69], v[4:5], v[68:69]
	v_pk_mul_f32 v[70:71], v[6:7], v[70:71]
	v_pk_mul_f32 v[72:73], v[8:9], v[72:73]
	v_pk_mul_f32 v[74:75], v[10:11], v[74:75]
	v_pk_mul_f32 v[76:77], v[12:13], v[76:77]
	v_pk_mul_f32 v[78:79], v[14:15], v[78:79]
	v_pk_mul_f32 v[80:81], v[16:17], v[80:81]
	global_store_dwordx4 v0, v[66:69], s[10:11] offset:0
	global_store_dwordx4 v0, v[70:73], s[10:11] offset:1024
	global_store_dwordx4 v0, v[74:77], s[10:11] offset:2048
	global_store_dwordx4 v0, v[78:81], s[10:11] offset:3072
	s_add_u32 s10, s10, 0x1000
	s_addc_u32 s11, s11, 0
	s_waitcnt vmcnt(28)
	v_pk_mul_f32 v[114:115], v[82:83], v[82:83]
	v_pk_fma_f32 v[114:115], v[84:85], v[84:85], v[114:115]
	v_pk_fma_f32 v[114:115], v[86:87], v[86:87], v[114:115]
	v_pk_fma_f32 v[114:115], v[88:89], v[88:89], v[114:115]
	v_pk_fma_f32 v[114:115], v[90:91], v[90:91], v[114:115]
	v_pk_fma_f32 v[114:115], v[92:93], v[92:93], v[114:115]
	v_pk_fma_f32 v[114:115], v[94:95], v[94:95], v[114:115]
	v_pk_fma_f32 v[114:115], v[96:97], v[96:97], v[114:115]
	v_add_f32_e32 v114, v114, v115
	s_nop 1
	v_add_f32_dpp v114, v114, v114 row_ror:8 row_mask:0xf bank_mask:0xf
	s_nop 1
	v_add_f32_dpp v114, v114, v114 row_ror:4 row_mask:0xf bank_mask:0xf
	s_nop 1
	v_add_f32_dpp v114, v114, v114 row_ror:2 row_mask:0xf bank_mask:0xf
	s_nop 1
	v_add_f32_dpp v114, v114, v114 row_ror:1 row_mask:0xf bank_mask:0xf
	s_nop 1
	s_nop 0
	v_readlane_b32 s0, v114, 0
	v_readlane_b32 s1, v114, 16
	v_readlane_b32 s22, v114, 32
	v_readlane_b32 s23, v114, 48
	s_nop 1
	v_mov_b32_e32 v116, s0
	v_add_f32_e32 v116, s1, v116
	v_add_f32_e32 v116, s22, v116
	v_add_f32_e32 v116, s23, v116
	v_fmamk_f32 v116, v116, 0x3a800000, v197
	v_rsq_f32_e32 v116, v116
	s_nop 0
	v_pk_mul_f32 v[82:83], v[82:83], v[116:117] op_sel_hi:[1,0]
	v_pk_mul_f32 v[84:85], v[84:85], v[116:117] op_sel_hi:[1,0]
	v_pk_mul_f32 v[86:87], v[86:87], v[116:117] op_sel_hi:[1,0]
	v_pk_mul_f32 v[88:89], v[88:89], v[116:117] op_sel_hi:[1,0]
	v_pk_mul_f32 v[90:91], v[90:91], v[116:117] op_sel_hi:[1,0]
	v_pk_mul_f32 v[92:93], v[92:93], v[116:117] op_sel_hi:[1,0]
	v_pk_mul_f32 v[94:95], v[94:95], v[116:117] op_sel_hi:[1,0]
	v_pk_mul_f32 v[96:97], v[96:97], v[116:117] op_sel_hi:[1,0]
	v_pk_mul_f32 v[82:83], v[2:3], v[82:83]
	v_pk_mul_f32 v[84:85], v[4:5], v[84:85]
	v_pk_mul_f32 v[86:87], v[6:7], v[86:87]
	v_pk_mul_f32 v[88:89], v[8:9], v[88:89]
	v_pk_mul_f32 v[90:91], v[10:11], v[90:91]
	v_pk_mul_f32 v[92:93], v[12:13], v[92:93]
	v_pk_mul_f32 v[94:95], v[14:15], v[94:95]
	v_pk_mul_f32 v[96:97], v[16:17], v[96:97]
	global_store_dwordx4 v0, v[82:85], s[10:11] offset:0
	global_store_dwordx4 v0, v[86:89], s[10:11] offset:1024
	global_store_dwordx4 v0, v[90:93], s[10:11] offset:2048
	global_store_dwordx4 v0, v[94:97], s[10:11] offset:3072
	s_add_u32 s10, s10, 0x1000
	s_addc_u32 s11, s11, 0
	s_waitcnt vmcnt(28)
	v_pk_mul_f32 v[114:115], v[98:99], v[98:99]
	v_pk_fma_f32 v[114:115], v[100:101], v[100:101], v[114:115]
	v_pk_fma_f32 v[114:115], v[102:103], v[102:103], v[114:115]
	v_pk_fma_f32 v[114:115], v[104:105], v[104:105], v[114:115]
	v_pk_fma_f32 v[114:115], v[106:107], v[106:107], v[114:115]
	v_pk_fma_f32 v[114:115], v[108:109], v[108:109], v[114:115]
	v_pk_fma_f32 v[114:115], v[110:111], v[110:111], v[114:115]
	v_pk_fma_f32 v[114:115], v[112:113], v[112:113], v[114:115]
	v_add_f32_e32 v114, v114, v115
	s_nop 1
	v_add_f32_dpp v114, v114, v114 row_ror:8 row_mask:0xf bank_mask:0xf
	s_nop 1
	v_add_f32_dpp v114, v114, v114 row_ror:4 row_mask:0xf bank_mask:0xf
	s_nop 1
	v_add_f32_dpp v114, v114, v114 row_ror:2 row_mask:0xf bank_mask:0xf
	s_nop 1
	v_add_f32_dpp v114, v114, v114 row_ror:1 row_mask:0xf bank_mask:0xf
	s_nop 1
	s_nop 0
	v_readlane_b32 s0, v114, 0
	v_readlane_b32 s1, v114, 16
	v_readlane_b32 s22, v114, 32
	v_readlane_b32 s23, v114, 48
	s_nop 1
	v_mov_b32_e32 v116, s0
	v_add_f32_e32 v116, s1, v116
	v_add_f32_e32 v116, s22, v116
	v_add_f32_e32 v116, s23, v116
	v_fmamk_f32 v116, v116, 0x3a800000, v197
	v_rsq_f32_e32 v116, v116
	s_nop 0
	v_pk_mul_f32 v[98:99], v[98:99], v[116:117] op_sel_hi:[1,0]
	v_pk_mul_f32 v[100:101], v[100:101], v[116:117] op_sel_hi:[1,0]
	v_pk_mul_f32 v[102:103], v[102:103], v[116:117] op_sel_hi:[1,0]
	v_pk_mul_f32 v[104:105], v[104:105], v[116:117] op_sel_hi:[1,0]
	v_pk_mul_f32 v[106:107], v[106:107], v[116:117] op_sel_hi:[1,0]
	v_pk_mul_f32 v[108:109], v[108:109], v[116:117] op_sel_hi:[1,0]
	v_pk_mul_f32 v[110:111], v[110:111], v[116:117] op_sel_hi:[1,0]
	v_pk_mul_f32 v[112:113], v[112:113], v[116:117] op_sel_hi:[1,0]
	v_pk_mul_f32 v[98:99], v[2:3], v[98:99]
	v_pk_mul_f32 v[100:101], v[4:5], v[100:101]
	v_pk_mul_f32 v[102:103], v[6:7], v[102:103]
	v_pk_mul_f32 v[104:105], v[8:9], v[104:105]
	v_pk_mul_f32 v[106:107], v[10:11], v[106:107]
	v_pk_mul_f32 v[108:109], v[12:13], v[108:109]
	v_pk_mul_f32 v[110:111], v[14:15], v[110:111]
	v_pk_mul_f32 v[112:113], v[16:17], v[112:113]
	global_store_dwordx4 v0, v[98:101], s[10:11] offset:0
	global_store_dwordx4 v0, v[102:105], s[10:11] offset:1024
	global_store_dwordx4 v0, v[106:109], s[10:11] offset:2048
	global_store_dwordx4 v0, v[110:113], s[10:11] offset:3072
	s_add_u32 s10, s10, 0x1000
	s_addc_u32 s11, s11, 0
	s_waitcnt vmcnt(24)
	v_pk_mul_f32 v[114:115], v[18:19], v[18:19]
	v_pk_fma_f32 v[114:115], v[20:21], v[20:21], v[114:115]
	v_pk_fma_f32 v[114:115], v[22:23], v[22:23], v[114:115]
	v_pk_fma_f32 v[114:115], v[24:25], v[24:25], v[114:115]
	v_pk_fma_f32 v[114:115], v[26:27], v[26:27], v[114:115]
	v_pk_fma_f32 v[114:115], v[28:29], v[28:29], v[114:115]
	v_pk_fma_f32 v[114:115], v[30:31], v[30:31], v[114:115]
	v_pk_fma_f32 v[114:115], v[32:33], v[32:33], v[114:115]
	v_add_f32_e32 v114, v114, v115
	s_nop 1
	v_add_f32_dpp v114, v114, v114 row_ror:8 row_mask:0xf bank_mask:0xf
	s_nop 1
	v_add_f32_dpp v114, v114, v114 row_ror:4 row_mask:0xf bank_mask:0xf
	s_nop 1
	v_add_f32_dpp v114, v114, v114 row_ror:2 row_mask:0xf bank_mask:0xf
	s_nop 1
	v_add_f32_dpp v114, v114, v114 row_ror:1 row_mask:0xf bank_mask:0xf
	s_nop 1
	s_nop 0
	v_readlane_b32 s0, v114, 0
	v_readlane_b32 s1, v114, 16
	v_readlane_b32 s22, v114, 32
	v_readlane_b32 s23, v114, 48
	s_nop 1
	v_mov_b32_e32 v116, s0
	v_add_f32_e32 v116, s1, v116
	v_add_f32_e32 v116, s22, v116
	v_add_f32_e32 v116, s23, v116
	v_fmamk_f32 v116, v116, 0x3a800000, v197
	v_rsq_f32_e32 v116, v116
	s_nop 0
	v_pk_mul_f32 v[18:19], v[18:19], v[116:117] op_sel_hi:[1,0]
	v_pk_mul_f32 v[20:21], v[20:21], v[116:117] op_sel_hi:[1,0]
	v_pk_mul_f32 v[22:23], v[22:23], v[116:117] op_sel_hi:[1,0]
	v_pk_mul_f32 v[24:25], v[24:25], v[116:117] op_sel_hi:[1,0]
	v_pk_mul_f32 v[26:27], v[26:27], v[116:117] op_sel_hi:[1,0]
	v_pk_mul_f32 v[28:29], v[28:29], v[116:117] op_sel_hi:[1,0]
	v_pk_mul_f32 v[30:31], v[30:31], v[116:117] op_sel_hi:[1,0]
	v_pk_mul_f32 v[32:33], v[32:33], v[116:117] op_sel_hi:[1,0]
	v_pk_mul_f32 v[18:19], v[2:3], v[18:19]
	v_pk_mul_f32 v[20:21], v[4:5], v[20:21]
	v_pk_mul_f32 v[22:23], v[6:7], v[22:23]
	v_pk_mul_f32 v[24:25], v[8:9], v[24:25]
	v_pk_mul_f32 v[26:27], v[10:11], v[26:27]
	v_pk_mul_f32 v[28:29], v[12:13], v[28:29]
	v_pk_mul_f32 v[30:31], v[14:15], v[30:31]
	v_pk_mul_f32 v[32:33], v[16:17], v[32:33]
	global_store_dwordx4 v0, v[18:21], s[10:11] offset:0
	global_store_dwordx4 v0, v[22:25], s[10:11] offset:1024
	global_store_dwordx4 v0, v[26:29], s[10:11] offset:2048
	global_store_dwordx4 v0, v[30:33], s[10:11] offset:3072
	s_add_u32 s10, s10, 0x1000
	s_addc_u32 s11, s11, 0
	s_waitcnt vmcnt(20)
	v_pk_mul_f32 v[114:115], v[34:35], v[34:35]
	v_pk_fma_f32 v[114:115], v[36:37], v[36:37], v[114:115]
	v_pk_fma_f32 v[114:115], v[38:39], v[38:39], v[114:115]
	v_pk_fma_f32 v[114:115], v[40:41], v[40:41], v[114:115]
	v_pk_fma_f32 v[114:115], v[42:43], v[42:43], v[114:115]
	v_pk_fma_f32 v[114:115], v[44:45], v[44:45], v[114:115]
	v_pk_fma_f32 v[114:115], v[46:47], v[46:47], v[114:115]
	v_pk_fma_f32 v[114:115], v[48:49], v[48:49], v[114:115]
	v_add_f32_e32 v114, v114, v115
	s_nop 1
	v_add_f32_dpp v114, v114, v114 row_ror:8 row_mask:0xf bank_mask:0xf
	s_nop 1
	v_add_f32_dpp v114, v114, v114 row_ror:4 row_mask:0xf bank_mask:0xf
	s_nop 1
	v_add_f32_dpp v114, v114, v114 row_ror:2 row_mask:0xf bank_mask:0xf
	s_nop 1
	v_add_f32_dpp v114, v114, v114 row_ror:1 row_mask:0xf bank_mask:0xf
	s_nop 1
	s_nop 0
	v_readlane_b32 s0, v114, 0
	v_readlane_b32 s1, v114, 16
	v_readlane_b32 s22, v114, 32
	v_readlane_b32 s23, v114, 48
	s_nop 1
	v_mov_b32_e32 v116, s0
	v_add_f32_e32 v116, s1, v116
	v_add_f32_e32 v116, s22, v116
	v_add_f32_e32 v116, s23, v116
	v_fmamk_f32 v116, v116, 0x3a800000, v197
	v_rsq_f32_e32 v116, v116
	s_nop 0
	v_pk_mul_f32 v[34:35], v[34:35], v[116:117] op_sel_hi:[1,0]
	v_pk_mul_f32 v[36:37], v[36:37], v[116:117] op_sel_hi:[1,0]
	v_pk_mul_f32 v[38:39], v[38:39], v[116:117] op_sel_hi:[1,0]
	v_pk_mul_f32 v[40:41], v[40:41], v[116:117] op_sel_hi:[1,0]
	v_pk_mul_f32 v[42:43], v[42:43], v[116:117] op_sel_hi:[1,0]
	v_pk_mul_f32 v[44:45], v[44:45], v[116:117] op_sel_hi:[1,0]
	v_pk_mul_f32 v[46:47], v[46:47], v[116:117] op_sel_hi:[1,0]
	v_pk_mul_f32 v[48:49], v[48:49], v[116:117] op_sel_hi:[1,0]
	v_pk_mul_f32 v[34:35], v[2:3], v[34:35]
	v_pk_mul_f32 v[36:37], v[4:5], v[36:37]
	v_pk_mul_f32 v[38:39], v[6:7], v[38:39]
	v_pk_mul_f32 v[40:41], v[8:9], v[40:41]
	v_pk_mul_f32 v[42:43], v[10:11], v[42:43]
	v_pk_mul_f32 v[44:45], v[12:13], v[44:45]
	v_pk_mul_f32 v[46:47], v[14:15], v[46:47]
	v_pk_mul_f32 v[48:49], v[16:17], v[48:49]
	global_store_dwordx4 v0, v[34:37], s[10:11] offset:0
	global_store_dwordx4 v0, v[38:41], s[10:11] offset:1024
	global_store_dwordx4 v0, v[42:45], s[10:11] offset:2048
	global_store_dwordx4 v0, v[46:49], s[10:11] offset:3072
	s_getpc_b64 s[98:99]
